# exact vmcnt waits in all 9 gemm128 k-loops (restores 2-k-tile prefetch depth), copy-scheme v9/v10 save moved to loop exit
# speedup vs baseline: 1.0387x; 1.0387x over previous
.LBB0_67:
	s_waitcnt vmcnt(15)
	v_lshl_add_u64 v[60:61], v[130:131], 1, s[88:89]
	global_load_dwordx4 v[60:63], v[60:61], off
	ds_read_b128 v[170:173], v132 offset:40960
	ds_read_b128 v[174:177], v132 offset:43520
	ds_read_b128 v[178:181], v133 offset:61440
	ds_read_b128 v[182:185], v133 offset:64000
	ds_read_b128 v[186:189], v132 offset:46080
	ds_read_b128 v[190:193], v132 offset:48640
	ds_read_b128 v[194:197], v150 offset:5120
	ds_read_b128 v[198:201], v150 offset:7680
	s_setprio 1
	s_waitcnt lgkmcnt(5)
	v_mfma_f32_16x16x32_bf16 v[64:67], v[178:181], v[170:173], v[64:67]
	v_mfma_f32_16x16x32_bf16 v[68:71], v[178:181], v[174:177], v[68:71]
	s_waitcnt lgkmcnt(3)
	v_mfma_f32_16x16x32_bf16 v[72:75], v[178:181], v[186:189], v[72:75]
	s_waitcnt lgkmcnt(2)
	v_mfma_f32_16x16x32_bf16 v[76:79], v[178:181], v[190:193], v[76:79]
	v_mfma_f32_16x16x32_bf16 v[80:83], v[182:185], v[170:173], v[80:83]
	v_mfma_f32_16x16x32_bf16 v[84:87], v[182:185], v[174:177], v[84:87]
	v_mfma_f32_16x16x32_bf16 v[88:91], v[182:185], v[186:189], v[88:91]
	v_mfma_f32_16x16x32_bf16 v[92:95], v[182:185], v[190:193], v[92:95]
	s_waitcnt lgkmcnt(1)
	v_mfma_f32_16x16x32_bf16 v[178:181], v[194:197], v[170:173], v[96:99]
	v_mfma_f32_16x16x32_bf16 v[182:185], v[194:197], v[174:177], v[100:103]
	v_mfma_f32_16x16x32_bf16 v[202:205], v[194:197], v[186:189], v[104:107]
	v_mfma_f32_16x16x32_bf16 v[194:197], v[194:197], v[190:193], v[108:111]
	s_waitcnt lgkmcnt(0)
	v_mfma_f32_16x16x32_bf16 v[170:173], v[198:201], v[170:173], v[112:115]
	v_mfma_f32_16x16x32_bf16 v[174:177], v[198:201], v[174:177], v[116:119]
	v_mfma_f32_16x16x32_bf16 v[186:189], v[198:201], v[186:189], v[120:123]
	v_mfma_f32_16x16x32_bf16 v[190:193], v[198:201], v[190:193], v[124:127]
	s_setprio 0
	ds_read_b128 v[198:201], v132 offset:41024
	ds_read_b128 v[206:209], v132 offset:43584
	ds_read_b128 v[96:99], v133 offset:61504
	ds_read_b128 v[210:213], v133 offset:64064
	ds_read_b128 v[214:217], v132 offset:46144
	ds_read_b128 v[218:221], v132 offset:48704
	ds_read_b128 v[222:225], v151 offset:5120
	ds_read_b128 v[226:229], v151 offset:7680
	s_setprio 1
	s_waitcnt lgkmcnt(5)
	v_mfma_f32_16x16x32_bf16 v[124:127], v[96:99], v[198:201], v[64:67]
	v_mfma_f32_16x16x32_bf16 v[120:123], v[96:99], v[206:209], v[68:71]
	s_waitcnt lgkmcnt(3)
	v_mfma_f32_16x16x32_bf16 v[116:119], v[96:99], v[214:217], v[72:75]
	s_waitcnt lgkmcnt(2)
	v_mfma_f32_16x16x32_bf16 v[112:115], v[96:99], v[218:221], v[76:79]
	v_mfma_f32_16x16x32_bf16 v[108:111], v[210:213], v[198:201], v[80:83]
	v_mfma_f32_16x16x32_bf16 v[104:107], v[210:213], v[206:209], v[84:87]
	v_mfma_f32_16x16x32_bf16 v[100:103], v[210:213], v[214:217], v[88:91]
	v_mfma_f32_16x16x32_bf16 v[96:99], v[210:213], v[218:221], v[92:95]
	s_waitcnt lgkmcnt(1)
	v_mfma_f32_16x16x32_bf16 v[92:95], v[222:225], v[198:201], v[178:181]
	v_mfma_f32_16x16x32_bf16 v[88:91], v[222:225], v[206:209], v[182:185]
	v_mfma_f32_16x16x32_bf16 v[84:87], v[222:225], v[214:217], v[202:205]
	v_mfma_f32_16x16x32_bf16 v[80:83], v[222:225], v[218:221], v[194:197]
	s_waitcnt lgkmcnt(0)
	v_mfma_f32_16x16x32_bf16 v[76:79], v[226:229], v[198:201], v[170:173]
	v_mfma_f32_16x16x32_bf16 v[72:75], v[226:229], v[206:209], v[174:177]
	v_mfma_f32_16x16x32_bf16 v[68:71], v[226:229], v[214:217], v[186:189]
	v_mfma_f32_16x16x32_bf16 v[64:67], v[226:229], v[218:221], v[190:193]
	s_setprio 0
	s_add_i32 s31, s31, 2
	s_addk_i32 s30, 0x80
	s_addk_i32 s29, 0x80
	v_add_u32_e32 v161, 0x80, v161
	v_add_u32_e32 v162, 0x80, v162
	v_add_u32_e32 v163, 0x80, v163
	v_add_u32_e32 v164, 0x80, v164
	s_addk_i32 s27, 0x80
	v_add_u32_e32 v165, 0x80, v165
	v_add_u32_e32 v166, 0x80, v166
	v_add_u32_e32 v167, 0x80, v167
	v_add_u32_e32 v168, 0x80, v168
	s_and_b64 vcc, exec, s[16:17]
	s_cbranch_vccnz .LBB0_86
.LBB0_68:
	s_cmp_gt_u32 s31, 12
	s_mov_b64 s[16:17], -1
	s_waitcnt lgkmcnt(0)
	s_barrier
	s_waitcnt vmcnt(15)
	ds_write_b128 v146, v[0:3] offset:40960
	s_waitcnt vmcnt(14)
	ds_write_b128 v146, v[8:11] offset:61440
	s_waitcnt vmcnt(13)
	ds_write_b128 v147, v[16:19] offset:40960
	s_waitcnt vmcnt(12)
	ds_write_b128 v147, v[24:27] offset:61440
	s_waitcnt vmcnt(11)
	ds_write_b128 v148, v[28:31] offset:40960
	s_waitcnt vmcnt(10)
	ds_write_b128 v148, v[36:39] offset:61440
	s_waitcnt vmcnt(9)
	ds_write_b128 v149, v[44:47] offset:40960
	s_waitcnt vmcnt(8)
	ds_write_b128 v149, v[56:59] offset:61440
	s_cbranch_scc0 .LBB0_74
	s_and_b64 vcc, exec, s[12:13]
	s_cbranch_vccz .LBB0_71
	v_mov_b32_e32 v130, v152
	s_mov_b64 s[16:17], 0
	v_lshl_add_u64 v[0:1], v[130:131], 1, s[58:59]
	v_mov_b32_e32 v130, v153
	global_load_dwordx4 v[0:3], v[0:1], off
	s_nop 0
	v_lshl_add_u64 v[8:9], v[130:131], 1, s[88:89]
	v_mov_b32_e32 v130, v154
	global_load_dwordx4 v[8:11], v[8:9], off
	s_nop 0
	v_lshl_add_u64 v[16:17], v[130:131], 1, s[58:59]
	v_mov_b32_e32 v130, v155
	global_load_dwordx4 v[16:19], v[16:17], off
	s_nop 0
	v_lshl_add_u64 v[24:25], v[130:131], 1, s[88:89]
	v_mov_b32_e32 v130, v156
	global_load_dwordx4 v[24:27], v[24:25], off
	s_nop 0
	v_lshl_add_u64 v[28:29], v[130:131], 1, s[58:59]
	v_mov_b32_e32 v130, v157
	global_load_dwordx4 v[28:31], v[28:29], off
	s_nop 0
	v_lshl_add_u64 v[36:37], v[130:131], 1, s[88:89]
	v_mov_b32_e32 v130, v158
	global_load_dwordx4 v[36:39], v[36:37], off
	s_nop 0
	v_lshl_add_u64 v[44:45], v[130:131], 1, s[58:59]
	global_load_dwordx4 v[44:47], v[44:45], off
	v_mov_b32_e32 v130, v159
.LBB0_71:
	s_andn2_b64 vcc, exec, s[16:17]
	s_cbranch_vccnz .LBB0_73
	s_waitcnt vmcnt(8)
	v_add_u32_e32 v44, s29, v160
	v_add_u32_e32 v130, 0xfffffcc0, v44
	v_add_u32_e32 v56, s30, v160
	v_lshl_add_u64 v[0:1], v[130:131], 1, s[58:59]
	v_add_u32_e32 v130, 0xfffffcc0, v56
	global_load_dwordx4 v[0:3], v[0:1], off
	s_nop 0
	v_lshl_add_u64 v[8:9], v[130:131], 1, s[88:89]
	v_add_u32_e32 v130, 0x7cc0, v44
	global_load_dwordx4 v[8:11], v[8:9], off
	s_nop 0
	v_lshl_add_u64 v[16:17], v[130:131], 1, s[58:59]
	v_add_u32_e32 v130, 0x7cc0, v56
	global_load_dwordx4 v[16:19], v[16:17], off
	s_nop 0
	v_lshl_add_u64 v[24:25], v[130:131], 1, s[88:89]
	v_add_u32_e32 v130, 0xfcc0, v44
	global_load_dwordx4 v[24:27], v[24:25], off
	s_nop 0
	v_lshl_add_u64 v[28:29], v[130:131], 1, s[58:59]
	v_add_u32_e32 v130, 0xfcc0, v56
	global_load_dwordx4 v[28:31], v[28:29], off
	s_nop 0
	v_lshl_add_u64 v[36:37], v[130:131], 1, s[88:89]
	v_add_u32_e32 v130, 0x17cc0, v44
	global_load_dwordx4 v[36:39], v[36:37], off
	s_nop 0
	v_lshl_add_u64 v[44:45], v[130:131], 1, s[58:59]
	global_load_dwordx4 v[44:47], v[44:45], off
	v_add_u32_e32 v130, 0x17cc0, v56

.LBB0_74:
	s_andn2_b64 vcc, exec, s[16:17]
	v_add_u32_e32 v169, s27, v160
	s_cbranch_vccnz .LBB0_76
	v_add_u32_e32 v130, 0xc0, v169
	s_nop 0
	v_lshl_add_u64 v[0:1], v[130:131], 1, s[58:59]
	v_add_u32_e32 v130, v143, v168
	global_load_dwordx4 v[0:3], v[0:1], off
	s_nop 0
	v_lshl_add_u64 v[8:9], v[130:131], 1, s[88:89]
	v_add_u32_e32 v130, 0x80c0, v169
	global_load_dwordx4 v[8:11], v[8:9], off
	s_nop 0
	v_lshl_add_u64 v[16:17], v[130:131], 1, s[58:59]
	v_add_u32_e32 v130, v143, v167
	global_load_dwordx4 v[16:19], v[16:17], off
	s_nop 0
	v_lshl_add_u64 v[24:25], v[130:131], 1, s[88:89]
	v_add_u32_e32 v130, 0x100c0, v169
	global_load_dwordx4 v[24:27], v[24:25], off
	s_nop 0
	v_lshl_add_u64 v[28:29], v[130:131], 1, s[58:59]
	v_add_u32_e32 v130, v143, v166
	global_load_dwordx4 v[28:31], v[28:29], off
	s_nop 0
	v_lshl_add_u64 v[36:37], v[130:131], 1, s[88:89]
	v_add_u32_e32 v130, 0x180c0, v169
	global_load_dwordx4 v[36:39], v[36:37], off
	s_nop 0
	v_lshl_add_u64 v[44:45], v[130:131], 1, s[58:59]
	global_load_dwordx4 v[44:47], v[44:45], off
	v_add_u32_e32 v130, v143, v165
.LBB0_76:
	s_nop 0
	v_lshl_add_u64 v[56:57], v[130:131], 1, s[88:89]
	global_load_dwordx4 v[56:59], v[56:57], off
	ds_read_b128 v[170:173], v132
	ds_read_b128 v[174:177], v132 offset:2560
	ds_read_b128 v[178:181], v133 offset:20480
	ds_read_b128 v[182:185], v133 offset:23040
	ds_read_b128 v[186:189], v132 offset:5120
	ds_read_b128 v[190:193], v132 offset:7680
	ds_read_b128 v[194:197], v133 offset:25600
	ds_read_b128 v[198:201], v133 offset:28160
	s_setprio 1
	s_waitcnt lgkmcnt(5)
	v_mfma_f32_16x16x32_bf16 v[124:127], v[178:181], v[170:173], v[124:127]
	v_mfma_f32_16x16x32_bf16 v[120:123], v[178:181], v[174:177], v[120:123]
	s_waitcnt lgkmcnt(3)
	v_mfma_f32_16x16x32_bf16 v[116:119], v[178:181], v[186:189], v[116:119]
	s_waitcnt lgkmcnt(2)
	v_mfma_f32_16x16x32_bf16 v[112:115], v[178:181], v[190:193], v[112:115]
	v_mfma_f32_16x16x32_bf16 v[108:111], v[182:185], v[170:173], v[108:111]
	v_mfma_f32_16x16x32_bf16 v[104:107], v[182:185], v[174:177], v[104:107]
	v_mfma_f32_16x16x32_bf16 v[100:103], v[182:185], v[186:189], v[100:103]
	v_mfma_f32_16x16x32_bf16 v[96:99], v[182:185], v[190:193], v[96:99]
	s_waitcnt lgkmcnt(1)
	v_mfma_f32_16x16x32_bf16 v[178:181], v[194:197], v[170:173], v[92:95]
	v_mfma_f32_16x16x32_bf16 v[182:185], v[194:197], v[174:177], v[88:91]
	v_mfma_f32_16x16x32_bf16 v[202:205], v[194:197], v[186:189], v[84:87]
	v_mfma_f32_16x16x32_bf16 v[194:197], v[194:197], v[190:193], v[80:83]
	s_waitcnt lgkmcnt(0)
	v_mfma_f32_16x16x32_bf16 v[170:173], v[198:201], v[170:173], v[76:79]
	v_mfma_f32_16x16x32_bf16 v[174:177], v[198:201], v[174:177], v[72:75]
	v_mfma_f32_16x16x32_bf16 v[186:189], v[198:201], v[186:189], v[68:71]
	v_mfma_f32_16x16x32_bf16 v[190:193], v[198:201], v[190:193], v[64:67]
	s_setprio 0
	ds_read_b128 v[198:201], v132 offset:64
	ds_read_b128 v[206:209], v132 offset:2624
	ds_read_b128 v[76:79], v133 offset:20544
	ds_read_b128 v[92:95], v133 offset:23104
	ds_read_b128 v[210:213], v132 offset:5184
	ds_read_b128 v[214:217], v132 offset:7744
	ds_read_b128 v[218:221], v133 offset:25664
	ds_read_b128 v[222:225], v133 offset:28224
	s_setprio 1
	s_waitcnt lgkmcnt(5)
	v_mfma_f32_16x16x32_bf16 v[64:67], v[76:79], v[198:201], v[124:127]
	v_mfma_f32_16x16x32_bf16 v[68:71], v[76:79], v[206:209], v[120:123]
	s_waitcnt lgkmcnt(3)
	v_mfma_f32_16x16x32_bf16 v[72:75], v[76:79], v[210:213], v[116:119]
	s_waitcnt lgkmcnt(2)
	v_mfma_f32_16x16x32_bf16 v[76:79], v[76:79], v[214:217], v[112:115]
	v_mfma_f32_16x16x32_bf16 v[80:83], v[92:95], v[198:201], v[108:111]
	v_mfma_f32_16x16x32_bf16 v[84:87], v[92:95], v[206:209], v[104:107]
	v_mfma_f32_16x16x32_bf16 v[88:91], v[92:95], v[210:213], v[100:103]
	v_mfma_f32_16x16x32_bf16 v[92:95], v[92:95], v[214:217], v[96:99]
	s_waitcnt lgkmcnt(1)
	v_mfma_f32_16x16x32_bf16 v[96:99], v[218:221], v[198:201], v[178:181]
	v_mfma_f32_16x16x32_bf16 v[100:103], v[218:221], v[206:209], v[182:185]
	v_mfma_f32_16x16x32_bf16 v[104:107], v[218:221], v[210:213], v[202:205]
	v_mfma_f32_16x16x32_bf16 v[108:111], v[218:221], v[214:217], v[194:197]
	s_waitcnt lgkmcnt(0)
	v_mfma_f32_16x16x32_bf16 v[112:115], v[222:225], v[198:201], v[170:173]
	v_mfma_f32_16x16x32_bf16 v[116:119], v[222:225], v[206:209], v[174:177]
	v_mfma_f32_16x16x32_bf16 v[120:123], v[222:225], v[210:213], v[186:189]
	v_mfma_f32_16x16x32_bf16 v[124:127], v[222:225], v[214:217], v[190:193]
	s_setprio 0
	s_cmp_gt_u32 s31, 13
	s_cselect_b64 s[16:17], -1, 0
	s_cmp_lt_u32 s31, 14
	s_cselect_b64 s[4:5], -1, 0
	s_or_b64 s[4:5], s[14:15], s[4:5]
	s_andn2_b64 vcc, exec, s[4:5]
	s_barrier
	s_cbranch_vccnz .LBB0_78
	s_waitcnt vmcnt(15)
	ds_write_b128 v146, v[4:7]
	s_waitcnt vmcnt(14)
	ds_write_b128 v146, v[12:15] offset:20480
	s_waitcnt vmcnt(13)
	ds_write_b128 v147, v[20:23]
	s_waitcnt vmcnt(12)
	ds_write_b128 v147, v[32:35] offset:20480
	s_waitcnt vmcnt(11)
	ds_write_b128 v148, v[40:43]
	s_waitcnt vmcnt(10)
	ds_write_b128 v148, v[48:51] offset:20480
	s_waitcnt vmcnt(9)
	ds_write_b128 v149, v[52:55]
	s_waitcnt vmcnt(8)
	ds_write_b128 v149, v[60:63] offset:20480
.LBB0_78:
	s_cmp_gt_u32 s31, 11
	s_mov_b64 s[18:19], -1
	s_cbranch_scc0 .LBB0_84
	s_and_b64 vcc, exec, s[12:13]
	s_cbranch_vccz .LBB0_81
	v_mov_b32_e32 v130, v152
	s_mov_b64 s[18:19], 0
	s_waitcnt vmcnt(8)
	v_lshl_add_u64 v[4:5], v[130:131], 1, s[58:59]
	v_mov_b32_e32 v130, v153
	global_load_dwordx4 v[4:7], v[4:5], off
	s_nop 0
	v_lshl_add_u64 v[12:13], v[130:131], 1, s[88:89]
	v_mov_b32_e32 v130, v154
	global_load_dwordx4 v[12:15], v[12:13], off
	s_nop 0
	v_lshl_add_u64 v[20:21], v[130:131], 1, s[58:59]
	v_mov_b32_e32 v130, v155
	global_load_dwordx4 v[20:23], v[20:21], off
	s_nop 0
	v_lshl_add_u64 v[32:33], v[130:131], 1, s[88:89]
	v_mov_b32_e32 v130, v156
	global_load_dwordx4 v[32:35], v[32:33], off
	s_nop 0
	v_lshl_add_u64 v[40:41], v[130:131], 1, s[58:59]
	v_mov_b32_e32 v130, v157
	global_load_dwordx4 v[40:43], v[40:41], off
	s_nop 0
	v_lshl_add_u64 v[48:49], v[130:131], 1, s[88:89]
	v_mov_b32_e32 v130, v158
	global_load_dwordx4 v[48:51], v[48:49], off
	s_nop 0
	v_lshl_add_u64 v[52:53], v[130:131], 1, s[58:59]
	global_load_dwordx4 v[52:55], v[52:53], off
	v_mov_b32_e32 v130, v159
.LBB0_81:
	s_andn2_b64 vcc, exec, s[18:19]
	s_cbranch_vccnz .LBB0_83
	s_waitcnt vmcnt(8)
	v_add_u32_e32 v52, s29, v160
	v_add_u32_e32 v130, 0xfffffd00, v52
	v_add_u32_e32 v60, s30, v160
	v_lshl_add_u64 v[4:5], v[130:131], 1, s[58:59]
	v_add_u32_e32 v130, 0xfffffd00, v60
	global_load_dwordx4 v[4:7], v[4:5], off
	s_nop 0
	v_lshl_add_u64 v[12:13], v[130:131], 1, s[88:89]
	v_add_u32_e32 v130, 0x7d00, v52
	global_load_dwordx4 v[12:15], v[12:13], off
	s_nop 0
	v_lshl_add_u64 v[20:21], v[130:131], 1, s[58:59]
	v_add_u32_e32 v130, 0x7d00, v60
	global_load_dwordx4 v[20:23], v[20:21], off
	s_nop 0
	v_lshl_add_u64 v[32:33], v[130:131], 1, s[88:89]
	v_add_u32_e32 v130, 0xfd00, v52
	global_load_dwordx4 v[32:35], v[32:33], off
	s_nop 0
	v_lshl_add_u64 v[40:41], v[130:131], 1, s[58:59]
	v_add_u32_e32 v130, 0xfd00, v60
	global_load_dwordx4 v[40:43], v[40:41], off
	s_nop 0
	v_lshl_add_u64 v[48:49], v[130:131], 1, s[88:89]
	v_add_u32_e32 v130, 0x17d00, v52
	global_load_dwordx4 v[48:51], v[48:49], off
	s_nop 0
	v_lshl_add_u64 v[52:53], v[130:131], 1, s[58:59]
	global_load_dwordx4 v[52:55], v[52:53], off
	v_add_u32_e32 v130, 0x17d00, v60

.LBB0_85:
	v_add_u32_e32 v130, 0x100, v169
	s_waitcnt vmcnt(8)
	v_lshl_add_u64 v[4:5], v[130:131], 1, s[58:59]
	v_add_u32_e32 v130, v143, v164
	global_load_dwordx4 v[4:7], v[4:5], off
	s_nop 0
	v_lshl_add_u64 v[12:13], v[130:131], 1, s[88:89]
	v_add_u32_e32 v130, 0x8100, v169
	global_load_dwordx4 v[12:15], v[12:13], off
	s_nop 0
	v_lshl_add_u64 v[20:21], v[130:131], 1, s[58:59]
	v_add_u32_e32 v130, v143, v163
	global_load_dwordx4 v[20:23], v[20:21], off
	s_nop 0
	v_lshl_add_u64 v[32:33], v[130:131], 1, s[88:89]
	v_add_u32_e32 v130, 0x10100, v169
	global_load_dwordx4 v[32:35], v[32:33], off
	s_nop 0
	v_lshl_add_u64 v[40:41], v[130:131], 1, s[58:59]
	v_add_u32_e32 v130, v143, v162
	global_load_dwordx4 v[40:43], v[40:41], off
	s_nop 0
	v_lshl_add_u64 v[48:49], v[130:131], 1, s[88:89]
	v_add_u32_e32 v130, 0x18100, v169
	global_load_dwordx4 v[48:51], v[48:49], off
	s_nop 0
	v_lshl_add_u64 v[52:53], v[130:131], 1, s[58:59]
	global_load_dwordx4 v[52:55], v[52:53], off
	v_add_u32_e32 v130, v143, v161
	s_branch .LBB0_67

.LBB0_389:
	s_waitcnt vmcnt(14)
	v_mov_b32_e32 v132, v9
	v_mov_b32_e32 v133, v10
	v_mul_f32_e32 v9, 0xbfb8aa3b, v120
	v_exp_f32_e32 v9, v9
	v_mul_f32_e32 v10, 0xbfb8aa3b, v121
	v_exp_f32_e32 v10, v10
	v_mul_f32_e32 v121, 0xbfb8aa3b, v123
	v_add_f32_e32 v9, 1.0, v9
	v_rcp_f32_e32 v120, v9
	v_mul_f32_e32 v9, 0xbfb8aa3b, v122
	v_exp_f32_e32 v9, v9
	v_exp_f32_e32 v123, v121
	v_add_f32_e32 v10, 1.0, v10
	v_rcp_f32_e32 v121, v10
	v_mul_f32_e32 v10, 0xbfb8aa3b, v112
	v_add_f32_e32 v9, 1.0, v9
	v_exp_f32_e32 v10, v10
	v_mul_f32_e32 v112, 0xbfb8aa3b, v113
	v_rcp_f32_e32 v122, v9
	v_add_f32_e32 v9, 1.0, v123
	v_exp_f32_e32 v113, v112
	v_rcp_f32_e32 v123, v9
	v_lshlrev_b32_e32 v9, 6, v139
	v_lshl_or_b32 v9, v140, 3, v9
	v_lshl_or_b32 v130, s18, 7, v9
	v_add_f32_e32 v9, 1.0, v10
	v_mul_f32_e32 v10, 0xbfb8aa3b, v114
	v_rcp_f32_e32 v112, v9
	v_add_f32_e32 v9, 1.0, v113
	v_exp_f32_e32 v10, v10
	v_mul_f32_e32 v113, 0xbfb8aa3b, v115
	v_exp_f32_e32 v115, v113
	v_rcp_f32_e32 v113, v9
	v_add_f32_e32 v9, 1.0, v10
	v_rcp_f32_e32 v114, v9
	v_add_f32_e32 v9, 1.0, v115
	v_rcp_f32_e32 v115, v9
	v_mul_f32_e32 v9, 0xbfb8aa3b, v104
	v_exp_f32_e32 v9, v9
	v_mul_f32_e32 v10, 0xbfb8aa3b, v105
	v_pk_mul_f32 v[120:121], v[124:125], v[120:121]
	v_lshl_add_u32 v124, s19, 7, v141
	v_exp_f32_e32 v10, v10
	v_pk_mul_f32 v[112:113], v[116:117], v[112:113]
	v_add_u32_e32 v116, 16, v124
	v_pk_mul_f32 v[114:115], v[118:119], v[114:115]
	v_ashrrev_i32_e32 v117, 31, v116
	v_cvt_pk_bf16_f32 v112, v112, v113
	v_cvt_pk_bf16_f32 v113, v114, v115
	v_lshlrev_b64 v[114:115], 11, v[116:117]
	v_add_f32_e32 v9, 1.0, v9
	v_lshl_add_u64 v[104:105], s[78:79], 0, v[114:115]
	v_rcp_f32_e32 v114, v9
	v_add_f32_e32 v9, 1.0, v10
	v_mul_f32_e32 v10, 0xbfb8aa3b, v106
	v_exp_f32_e32 v10, v10
	v_mul_f32_e32 v106, 0xbfb8aa3b, v107
	v_exp_f32_e32 v107, v106
	v_rcp_f32_e32 v115, v9
	v_add_f32_e32 v9, 1.0, v10
	v_rcp_f32_e32 v106, v9
	v_add_f32_e32 v9, 1.0, v107
	v_rcp_f32_e32 v107, v9
	v_mul_f32_e32 v9, 0xbfb8aa3b, v96
	v_exp_f32_e32 v9, v9
	v_mul_f32_e32 v10, 0xbfb8aa3b, v97
	v_exp_f32_e32 v10, v10
	v_pk_mul_f32 v[106:107], v[110:111], v[106:107]
	v_add_u32_e32 v110, 32, v124
	v_pk_mul_f32 v[108:109], v[108:109], v[114:115]
	v_ashrrev_i32_e32 v111, 31, v110
	v_cvt_pk_bf16_f32 v108, v108, v109
	v_cvt_pk_bf16_f32 v109, v106, v107
	v_lshlrev_b64 v[106:107], 11, v[110:111]
	v_add_f32_e32 v9, 1.0, v9
	v_lshl_add_u64 v[96:97], s[78:79], 0, v[106:107]
	v_rcp_f32_e32 v106, v9
	v_add_f32_e32 v9, 1.0, v10
	v_mul_f32_e32 v10, 0xbfb8aa3b, v98
	v_exp_f32_e32 v10, v10
	v_mul_f32_e32 v98, 0xbfb8aa3b, v99
	v_exp_f32_e32 v99, v98
	v_rcp_f32_e32 v107, v9
	v_add_f32_e32 v9, 1.0, v10
	v_rcp_f32_e32 v98, v9
	v_add_f32_e32 v9, 1.0, v99
	v_rcp_f32_e32 v99, v9
	v_mul_f32_e32 v9, 0xbfb8aa3b, v88
	v_exp_f32_e32 v9, v9
	v_mul_f32_e32 v10, 0xbfb8aa3b, v89
	v_exp_f32_e32 v10, v10
	v_pk_mul_f32 v[98:99], v[102:103], v[98:99]
	v_add_u32_e32 v102, 48, v124
	v_pk_mul_f32 v[100:101], v[100:101], v[106:107]
	v_ashrrev_i32_e32 v103, 31, v102
	v_cvt_pk_bf16_f32 v100, v100, v101
	v_cvt_pk_bf16_f32 v101, v98, v99
	v_lshlrev_b64 v[98:99], 11, v[102:103]
	v_add_f32_e32 v9, 1.0, v9
	v_lshl_add_u64 v[88:89], s[78:79], 0, v[98:99]
	v_rcp_f32_e32 v98, v9
	v_add_f32_e32 v9, 1.0, v10
	v_mul_f32_e32 v10, 0xbfb8aa3b, v90
	v_exp_f32_e32 v10, v10
	v_mul_f32_e32 v90, 0xbfb8aa3b, v91
	v_exp_f32_e32 v91, v90
	v_rcp_f32_e32 v99, v9
	v_add_f32_e32 v9, 1.0, v10
	v_rcp_f32_e32 v90, v9
	v_add_f32_e32 v9, 1.0, v91
	v_rcp_f32_e32 v91, v9
	v_mul_f32_e32 v9, 0xbfb8aa3b, v80
	v_exp_f32_e32 v9, v9
	v_mul_f32_e32 v10, 0xbfb8aa3b, v81
	v_exp_f32_e32 v10, v10
	v_pk_mul_f32 v[92:93], v[92:93], v[98:99]
	v_add_f32_e32 v9, 1.0, v9
	v_cvt_pk_bf16_f32 v80, v92, v93
	v_rcp_f32_e32 v92, v9
	v_add_f32_e32 v9, 1.0, v10
	v_mul_f32_e32 v10, 0xbfb8aa3b, v82
	v_exp_f32_e32 v10, v10
	v_mul_f32_e32 v81, 0xbfb8aa3b, v83
	v_exp_f32_e32 v81, v81
	v_rcp_f32_e32 v93, v9
	v_add_f32_e32 v9, 1.0, v10
	v_rcp_f32_e32 v82, v9
	v_add_f32_e32 v9, 1.0, v81
	v_rcp_f32_e32 v83, v9
	v_mul_f32_e32 v9, 0xbfb8aa3b, v72
	v_pk_mul_f32 v[122:123], v[126:127], v[122:123]
	v_ashrrev_i32_e32 v125, 31, v124
	v_exp_f32_e32 v9, v9
	v_mul_f32_e32 v10, 0xbfb8aa3b, v73
	v_cvt_pk_bf16_f32 v120, v120, v121
	v_cvt_pk_bf16_f32 v121, v122, v123
	v_lshlrev_b64 v[122:123], 11, v[124:125]
	v_exp_f32_e32 v10, v10
	v_lshl_add_u64 v[122:123], s[78:79], 0, v[122:123]
	v_pk_mul_f32 v[90:91], v[94:95], v[90:91]
	v_lshl_add_u64 v[122:123], v[122:123], 0, v[130:131]
	v_cvt_pk_bf16_f32 v81, v90, v91
	global_store_dwordx2 v[122:123], v[80:81], off offset:1056
	v_pk_mul_f32 v[80:81], v[84:85], v[92:93]
	v_add_f32_e32 v9, 1.0, v9
	v_cvt_pk_bf16_f32 v72, v80, v81
	v_rcp_f32_e32 v80, v9
	v_add_f32_e32 v9, 1.0, v10
	v_mul_f32_e32 v10, 0xbfb8aa3b, v74
	v_exp_f32_e32 v10, v10
	v_mul_f32_e32 v73, 0xbfb8aa3b, v75
	v_exp_f32_e32 v73, v73
	v_rcp_f32_e32 v81, v9
	v_add_f32_e32 v9, 1.0, v10
	v_rcp_f32_e32 v74, v9
	v_add_f32_e32 v9, 1.0, v73
	v_rcp_f32_e32 v75, v9
	v_mul_f32_e32 v9, 0xbfb8aa3b, v64
	v_exp_f32_e32 v9, v9
	v_mul_f32_e32 v10, 0xbfb8aa3b, v65
	v_exp_f32_e32 v10, v10
	v_pk_mul_f32 v[82:83], v[86:87], v[82:83]
	v_lshl_add_u64 v[104:105], v[104:105], 0, v[130:131]
	v_cvt_pk_bf16_f32 v73, v82, v83
	global_store_dwordx2 v[104:105], v[72:73], off offset:1056
	v_pk_mul_f32 v[72:73], v[76:77], v[80:81]
	v_add_f32_e32 v9, 1.0, v9
	v_cvt_pk_bf16_f32 v64, v72, v73
	v_rcp_f32_e32 v72, v9
	v_add_f32_e32 v9, 1.0, v10
	v_mul_f32_e32 v10, 0xbfb8aa3b, v66
	v_exp_f32_e32 v10, v10
	v_mul_f32_e32 v65, 0xbfb8aa3b, v67
	v_exp_f32_e32 v65, v65
	v_rcp_f32_e32 v73, v9
	v_add_f32_e32 v9, 1.0, v10
	v_rcp_f32_e32 v66, v9
	v_add_f32_e32 v9, 1.0, v65
	v_rcp_f32_e32 v67, v9
	v_pk_mul_f32 v[74:75], v[78:79], v[74:75]
	v_lshl_add_u64 v[96:97], v[96:97], 0, v[130:131]
	v_cvt_pk_bf16_f32 v65, v74, v75
	global_store_dwordx2 v[96:97], v[64:65], off offset:1056
	v_pk_mul_f32 v[64:65], v[68:69], v[72:73]
	v_pk_mul_f32 v[66:67], v[70:71], v[66:67]
	v_lshl_add_u64 v[88:89], v[88:89], 0, v[130:131]
	v_cvt_pk_bf16_f32 v64, v64, v65
	v_cvt_pk_bf16_f32 v65, v66, v67
	s_add_i32 s17, s17, s90
	s_mov_b64 s[2:3], 0
	s_andn2_b64 vcc, exec, s[0:1]
	s_mov_b32 s6, s20
	global_store_dwordx2 v[122:123], v[120:121], off offset:1024
	global_store_dwordx2 v[104:105], v[112:113], off offset:1024
	global_store_dwordx2 v[96:97], v[108:109], off offset:1024
	global_store_dwordx2 v[88:89], v[100:101], off offset:1024
	global_store_dwordx2 v[88:89], v[64:65], off offset:1056
	s_cbranch_vccz .LBB0_414

.LBB0_394:
	s_and_b32 s0, s17, 7
	s_add_i32 s20, s6, s90
	s_cmpk_gt_i32 s20, 0x7ff
	v_lshl_add_u32 v142, s0, 16, v136
	s_cselect_b64 s[0:1], -1, 0
	s_cmpk_lt_i32 s20, 0x800
	s_cselect_b64 s[2:3], -1, 0
	s_and_b64 s[4:5], s[2:3], exec
	v_lshlrev_b32_e32 v10, 1, v138
	s_cselect_b32 s4, s20, s6
	v_bfe_u32 v139, v64, 6, 1
	v_and_b32_e32 v9, 15, v64
	v_lshl_add_u32 v145, v71, 1, v10
	v_lshl_add_u32 v146, v68, 1, v10
	v_lshl_add_u32 v147, v69, 1, v10
	v_lshl_add_u32 v148, v70, 1, v10
	v_ashrrev_i32_e32 v10, 1, v64
	s_lshl_b32 s5, s4, 4
	s_lshl_b32 s4, s4, 7
	v_bfe_u32 v140, v64, 4, 2
	v_and_or_b32 v141, v10, s15, v9
	v_lshl_or_b32 v9, v139, 6, v9
	s_and_b32 s5, s5, 0x7fff80
	s_and_b32 s4, s4, 0x380
	v_lshlrev_b32_e32 v10, 4, v140
	v_mul_u32_u24_e32 v9, 0x50, v9
	v_add_lshl_u32 v143, s5, v129, 9
	v_add_lshl_u32 v144, s4, v129, 9
	v_mad_u64_u32 v[134:135], s[4:5], v141, s16, v[10:11]
	v_lshlrev_b32_e32 v9, 1, v9
	v_or_b32_e32 v66, 0x1c0, v138
	v_add_u32_e32 v135, v10, v9
	v_or_b32_e32 v64, 0xf000, v10
	v_add_u32_e32 v67, 0x1400, v9
	v_add_u32_e32 v9, 0x1e00, v9
	v_add_u32_e32 v149, v64, v67
	v_add_u32_e32 v150, v64, v9
	v_or_b32_e32 v10, 0xf040, v10
	v_add_u32_e32 v153, v66, v137
	v_add_u32_e32 v154, v66, v65
	v_mov_b32_e32 v64, 0
	v_add_u32_e32 v151, v10, v67
	v_add_u32_e32 v152, v10, v9
	v_add_u32_e32 v155, 0x4000, v153
	v_add_u32_e32 v156, 0x4000, v154
	v_add_u32_e32 v157, 0x8000, v153
	v_add_u32_e32 v158, 0x8000, v154
	v_add_u32_e32 v159, 0xc000, v153
	v_add_u32_e32 v160, 0xc000, v154
	s_mov_b32 s21, 0
	v_mov_b32_e32 v65, v64
	v_mov_b32_e32 v66, v64
	v_mov_b32_e32 v67, v64
	v_mov_b32_e32 v72, v64
	v_mov_b32_e32 v73, v64
	v_mov_b32_e32 v74, v64
	v_mov_b32_e32 v75, v64
	v_mov_b32_e32 v80, v64
	v_mov_b32_e32 v81, v64
	v_mov_b32_e32 v82, v64
	v_mov_b32_e32 v83, v64
	v_mov_b32_e32 v88, v64
	v_mov_b32_e32 v89, v64
	v_mov_b32_e32 v90, v64
	v_mov_b32_e32 v91, v64
	v_mov_b32_e32 v96, v64
	v_mov_b32_e32 v97, v64
	v_mov_b32_e32 v98, v64
	v_mov_b32_e32 v99, v64
	v_mov_b32_e32 v104, v64
	v_mov_b32_e32 v105, v64
	v_mov_b32_e32 v106, v64
	v_mov_b32_e32 v107, v64
	v_mov_b32_e32 v112, v64
	v_mov_b32_e32 v113, v64
	v_mov_b32_e32 v114, v64
	v_mov_b32_e32 v115, v64
	v_mov_b32_e32 v120, v64
	v_mov_b32_e32 v121, v64
	v_mov_b32_e32 v122, v64
	v_mov_b32_e32 v123, v64
	v_mov_b32_e32 v68, v64
	v_mov_b32_e32 v69, v64
	v_mov_b32_e32 v70, v64
	v_mov_b32_e32 v71, v64
	v_mov_b32_e32 v76, v64
	v_mov_b32_e32 v77, v64
	v_mov_b32_e32 v78, v64
	v_mov_b32_e32 v79, v64
	v_mov_b32_e32 v84, v64
	v_mov_b32_e32 v85, v64
	v_mov_b32_e32 v86, v64
	v_mov_b32_e32 v87, v64
	v_mov_b32_e32 v92, v64
	v_mov_b32_e32 v93, v64
	v_mov_b32_e32 v94, v64
	v_mov_b32_e32 v95, v64
	v_mov_b32_e32 v100, v64
	v_mov_b32_e32 v101, v64
	v_mov_b32_e32 v102, v64
	v_mov_b32_e32 v103, v64
	v_mov_b32_e32 v108, v64
	v_mov_b32_e32 v109, v64
	v_mov_b32_e32 v110, v64
	v_mov_b32_e32 v111, v64
	v_mov_b32_e32 v116, v64
	v_mov_b32_e32 v117, v64
	v_mov_b32_e32 v118, v64
	v_mov_b32_e32 v119, v64
	v_mov_b32_e32 v124, v64
	v_mov_b32_e32 v125, v64
	v_mov_b32_e32 v126, v64
	v_mov_b32_e32 v127, v64
	v_mov_b32_e32 v9, v132
	v_mov_b32_e32 v10, v133
	s_branch .LBB0_396
.LBB0_395:
	s_waitcnt vmcnt(15)
	v_lshl_add_u64 v[60:61], v[130:131], 1, s[10:11]
	global_load_dwordx4 v[60:63], v[60:61], off
	ds_read_b128 v[162:165], v134 offset:40960
	ds_read_b128 v[166:169], v134 offset:43520
	ds_read_b128 v[170:173], v135 offset:61440
	ds_read_b128 v[174:177], v135 offset:64000
	ds_read_b128 v[178:181], v134 offset:46080
	ds_read_b128 v[182:185], v134 offset:48640
	ds_read_b128 v[186:189], v149
	ds_read_b128 v[190:193], v150
	s_setprio 1
	s_waitcnt lgkmcnt(5)
	v_mfma_f32_16x16x32_bf16 v[64:67], v[170:173], v[162:165], v[64:67]
	v_mfma_f32_16x16x32_bf16 v[68:71], v[170:173], v[166:169], v[68:71]
	s_waitcnt lgkmcnt(3)
	v_mfma_f32_16x16x32_bf16 v[72:75], v[170:173], v[178:181], v[72:75]
	s_waitcnt lgkmcnt(2)
	v_mfma_f32_16x16x32_bf16 v[76:79], v[170:173], v[182:185], v[76:79]
	v_mfma_f32_16x16x32_bf16 v[80:83], v[174:177], v[162:165], v[80:83]
	v_mfma_f32_16x16x32_bf16 v[84:87], v[174:177], v[166:169], v[84:87]
	v_mfma_f32_16x16x32_bf16 v[88:91], v[174:177], v[178:181], v[88:91]
	s_waitcnt lgkmcnt(1)
	v_mfma_f32_16x16x32_bf16 v[96:99], v[186:189], v[162:165], v[96:99]
	v_mfma_f32_16x16x32_bf16 v[104:107], v[186:189], v[178:181], v[104:107]
	v_mfma_f32_16x16x32_bf16 v[170:173], v[174:177], v[182:185], v[92:95]
	v_mfma_f32_16x16x32_bf16 v[174:177], v[186:189], v[166:169], v[100:103]
	v_mfma_f32_16x16x32_bf16 v[186:189], v[186:189], v[182:185], v[108:111]
	s_waitcnt lgkmcnt(0)
	v_mfma_f32_16x16x32_bf16 v[162:165], v[190:193], v[162:165], v[112:115]
	v_mfma_f32_16x16x32_bf16 v[166:169], v[190:193], v[166:169], v[116:119]
	v_mfma_f32_16x16x32_bf16 v[178:181], v[190:193], v[178:181], v[120:123]
	v_mfma_f32_16x16x32_bf16 v[182:185], v[190:193], v[182:185], v[124:127]
	s_setprio 0
	ds_read_b128 v[190:193], v134 offset:41024
	ds_read_b128 v[194:197], v134 offset:43584
	ds_read_b128 v[92:95], v135 offset:61504
	ds_read_b128 v[112:115], v135 offset:64064
	ds_read_b128 v[198:201], v134 offset:46144
	ds_read_b128 v[202:205], v134 offset:48704
	ds_read_b128 v[206:209], v151
	ds_read_b128 v[210:213], v152
	s_setprio 1
	s_waitcnt lgkmcnt(5)
	v_mfma_f32_16x16x32_bf16 v[124:127], v[92:95], v[190:193], v[64:67]
	v_mfma_f32_16x16x32_bf16 v[116:119], v[92:95], v[194:197], v[68:71]
	s_waitcnt lgkmcnt(3)
	v_mfma_f32_16x16x32_bf16 v[108:111], v[92:95], v[198:201], v[72:75]
	s_waitcnt lgkmcnt(2)
	v_mfma_f32_16x16x32_bf16 v[100:103], v[92:95], v[202:205], v[76:79]
	v_mfma_f32_16x16x32_bf16 v[92:95], v[112:115], v[190:193], v[80:83]
	v_mfma_f32_16x16x32_bf16 v[84:87], v[112:115], v[194:197], v[84:87]
	v_mfma_f32_16x16x32_bf16 v[76:79], v[112:115], v[198:201], v[88:91]
	v_mfma_f32_16x16x32_bf16 v[68:71], v[112:115], v[202:205], v[170:173]
	s_waitcnt lgkmcnt(1)
	v_mfma_f32_16x16x32_bf16 v[120:123], v[206:209], v[190:193], v[96:99]
	v_mfma_f32_16x16x32_bf16 v[112:115], v[206:209], v[194:197], v[174:177]
	v_mfma_f32_16x16x32_bf16 v[104:107], v[206:209], v[198:201], v[104:107]
	v_mfma_f32_16x16x32_bf16 v[96:99], v[206:209], v[202:205], v[186:189]
	s_waitcnt lgkmcnt(0)
	v_mfma_f32_16x16x32_bf16 v[88:91], v[210:213], v[190:193], v[162:165]
	v_mfma_f32_16x16x32_bf16 v[80:83], v[210:213], v[194:197], v[166:169]
	v_mfma_f32_16x16x32_bf16 v[72:75], v[210:213], v[198:201], v[178:181]
	v_mfma_f32_16x16x32_bf16 v[64:67], v[210:213], v[202:205], v[182:185]
	s_setprio 0
	s_add_i32 s21, s21, 2
	v_add_u32_e32 v144, 0x80, v144
	v_add_u32_e32 v143, 0x80, v143
	v_add_u32_e32 v142, 0x80, v142
	s_andn2_b64 vcc, exec, s[6:7]
	v_add_u32_e32 v137, 0x80, v137
	s_cbranch_vccz .LBB0_389
.LBB0_396:
	s_cmp_gt_u32 s21, 4
	s_mov_b64 s[6:7], -1
	s_waitcnt lgkmcnt(0)
	s_barrier
	s_waitcnt vmcnt(15)
	ds_write_b128 v145, v[0:3] offset:40960
	s_waitcnt vmcnt(14)
	ds_write_b128 v145, v[8:11] offset:61440
	s_waitcnt vmcnt(13)
	ds_write_b128 v146, v[16:19] offset:40960
	s_waitcnt vmcnt(12)
	ds_write_b128 v146, v[24:27] offset:61440
	s_waitcnt vmcnt(11)
	ds_write_b128 v147, v[28:31] offset:40960
	s_waitcnt vmcnt(10)
	ds_write_b128 v147, v[36:39] offset:61440
	s_waitcnt vmcnt(9)
	ds_write_b128 v148, v[44:47] offset:40960
	s_waitcnt vmcnt(8)
	ds_write_b128 v148, v[56:59] offset:61440
	s_cbranch_scc0 .LBB0_402
	s_and_b64 vcc, exec, s[0:1]
	s_cbranch_vccz .LBB0_399
	v_mov_b32_e32 v130, v153
	s_mov_b64 s[6:7], 0
	v_lshl_add_u64 v[0:1], v[130:131], 1, s[80:81]
	v_mov_b32_e32 v130, v154
	global_load_dwordx4 v[0:3], v[0:1], off
	s_nop 0
	v_lshl_add_u64 v[8:9], v[130:131], 1, s[10:11]
	v_mov_b32_e32 v130, v155
	global_load_dwordx4 v[8:11], v[8:9], off
	s_nop 0
	s_nop 0
	v_lshl_add_u64 v[16:17], v[130:131], 1, s[80:81]
	v_mov_b32_e32 v130, v156
	global_load_dwordx4 v[16:19], v[16:17], off
	s_nop 0
	v_lshl_add_u64 v[24:25], v[130:131], 1, s[10:11]
	v_mov_b32_e32 v130, v157
	global_load_dwordx4 v[24:27], v[24:25], off
	s_nop 0
	v_lshl_add_u64 v[28:29], v[130:131], 1, s[80:81]
	v_mov_b32_e32 v130, v158
	global_load_dwordx4 v[28:31], v[28:29], off
	s_nop 0
	v_lshl_add_u64 v[36:37], v[130:131], 1, s[10:11]
	v_mov_b32_e32 v130, v159
	global_load_dwordx4 v[36:39], v[36:37], off
	s_nop 0
	v_lshl_add_u64 v[44:45], v[130:131], 1, s[80:81]
	global_load_dwordx4 v[44:47], v[44:45], off
	v_mov_b32_e32 v130, v160
.LBB0_399:
	s_andn2_b64 vcc, exec, s[6:7]
	s_cbranch_vccnz .LBB0_401
	s_waitcnt vmcnt(8)
	v_add_u32_e32 v44, v138, v143
	v_add_u32_e32 v130, 0xfffffec0, v44
	v_add_u32_e32 v56, v138, v144
	v_lshl_add_u64 v[0:1], v[130:131], 1, s[80:81]
	v_add_u32_e32 v130, 0xfffffec0, v56
	global_load_dwordx4 v[0:3], v[0:1], off
	s_nop 0
	v_lshl_add_u64 v[8:9], v[130:131], 1, s[10:11]
	v_add_u32_e32 v130, 0x3ec0, v44
	global_load_dwordx4 v[8:11], v[8:9], off
	s_nop 0
	s_nop 0
	v_lshl_add_u64 v[16:17], v[130:131], 1, s[80:81]
	v_add_u32_e32 v130, 0x3ec0, v56
	global_load_dwordx4 v[16:19], v[16:17], off
	s_nop 0
	v_lshl_add_u64 v[24:25], v[130:131], 1, s[10:11]
	v_add_u32_e32 v130, 0x7ec0, v44
	global_load_dwordx4 v[24:27], v[24:25], off
	s_nop 0
	v_lshl_add_u64 v[28:29], v[130:131], 1, s[80:81]
	v_add_u32_e32 v130, 0x7ec0, v56
	global_load_dwordx4 v[28:31], v[28:29], off
	s_nop 0
	v_lshl_add_u64 v[36:37], v[130:131], 1, s[10:11]
	v_add_u32_e32 v130, 0xbec0, v44
	global_load_dwordx4 v[36:39], v[36:37], off
	s_nop 0
	v_lshl_add_u64 v[44:45], v[130:131], 1, s[80:81]
	global_load_dwordx4 v[44:47], v[44:45], off
	v_add_u32_e32 v130, 0xbec0, v56

.LBB0_402:
	s_andn2_b64 vcc, exec, s[6:7]
	v_add_u32_e32 v162, v138, v137
	v_add_u32_e32 v161, v138, v142
	s_cbranch_vccnz .LBB0_404
	v_add_u32_e32 v130, 0xc0, v162
	s_nop 0
	v_lshl_add_u64 v[0:1], v[130:131], 1, s[80:81]
	v_add_u32_e32 v130, 0xc0, v161
	global_load_dwordx4 v[0:3], v[0:1], off
	s_nop 0
	v_lshl_add_u64 v[8:9], v[130:131], 1, s[10:11]
	v_add_u32_e32 v130, 0x40c0, v162
	global_load_dwordx4 v[8:11], v[8:9], off
	s_nop 0
	s_nop 0
	v_lshl_add_u64 v[16:17], v[130:131], 1, s[80:81]
	v_add_u32_e32 v130, 0x40c0, v161
	global_load_dwordx4 v[16:19], v[16:17], off
	s_nop 0
	v_lshl_add_u64 v[24:25], v[130:131], 1, s[10:11]
	v_add_u32_e32 v130, 0x80c0, v162
	global_load_dwordx4 v[24:27], v[24:25], off
	s_nop 0
	v_lshl_add_u64 v[28:29], v[130:131], 1, s[80:81]
	v_add_u32_e32 v130, 0x80c0, v161
	global_load_dwordx4 v[28:31], v[28:29], off
	s_nop 0
	v_lshl_add_u64 v[36:37], v[130:131], 1, s[10:11]
	v_add_u32_e32 v130, 0xc0c0, v162
	global_load_dwordx4 v[36:39], v[36:37], off
	s_nop 0
	v_lshl_add_u64 v[44:45], v[130:131], 1, s[80:81]
	global_load_dwordx4 v[44:47], v[44:45], off
	v_add_u32_e32 v130, 0xc0c0, v161
.LBB0_404:
	s_nop 0
	v_lshl_add_u64 v[56:57], v[130:131], 1, s[10:11]
	global_load_dwordx4 v[56:59], v[56:57], off
	ds_read_b128 v[164:167], v134
	ds_read_b128 v[168:171], v134 offset:2560
	ds_read_b128 v[172:175], v135 offset:20480
	ds_read_b128 v[176:179], v135 offset:23040
	ds_read_b128 v[180:183], v134 offset:5120
	ds_read_b128 v[184:187], v134 offset:7680
	ds_read_b128 v[188:191], v135 offset:25600
	ds_read_b128 v[192:195], v135 offset:28160
	s_setprio 1
	s_waitcnt lgkmcnt(5)
	v_mfma_f32_16x16x32_bf16 v[124:127], v[172:175], v[164:167], v[124:127]
	v_mfma_f32_16x16x32_bf16 v[116:119], v[172:175], v[168:171], v[116:119]
	s_waitcnt lgkmcnt(3)
	v_mfma_f32_16x16x32_bf16 v[108:111], v[172:175], v[180:183], v[108:111]
	s_waitcnt lgkmcnt(2)
	v_mfma_f32_16x16x32_bf16 v[100:103], v[172:175], v[184:187], v[100:103]
	v_mfma_f32_16x16x32_bf16 v[92:95], v[176:179], v[164:167], v[92:95]
	v_mfma_f32_16x16x32_bf16 v[84:87], v[176:179], v[168:171], v[84:87]
	s_waitcnt lgkmcnt(1)
	v_mfma_f32_16x16x32_bf16 v[120:123], v[188:191], v[164:167], v[120:123]
	v_mfma_f32_16x16x32_bf16 v[112:115], v[188:191], v[168:171], v[112:115]
	v_mfma_f32_16x16x32_bf16 v[104:107], v[188:191], v[180:183], v[104:107]
	v_mfma_f32_16x16x32_bf16 v[172:175], v[176:179], v[180:183], v[76:79]
	v_mfma_f32_16x16x32_bf16 v[176:179], v[176:179], v[184:187], v[68:71]
	v_mfma_f32_16x16x32_bf16 v[188:191], v[188:191], v[184:187], v[96:99]
	s_waitcnt lgkmcnt(0)
	v_mfma_f32_16x16x32_bf16 v[164:167], v[192:195], v[164:167], v[88:91]
	v_mfma_f32_16x16x32_bf16 v[168:171], v[192:195], v[168:171], v[80:83]
	v_mfma_f32_16x16x32_bf16 v[180:183], v[192:195], v[180:183], v[72:75]
	v_mfma_f32_16x16x32_bf16 v[184:187], v[192:195], v[184:187], v[64:67]
	s_setprio 0
	ds_read_b128 v[192:195], v134 offset:64
	ds_read_b128 v[196:199], v134 offset:2624
	ds_read_b128 v[76:79], v135 offset:20544
	ds_read_b128 v[96:99], v135 offset:23104
	ds_read_b128 v[200:203], v134 offset:5184
	ds_read_b128 v[204:207], v134 offset:7744
	ds_read_b128 v[208:211], v135 offset:25664
	ds_read_b128 v[212:215], v135 offset:28224
	s_setprio 1
	s_waitcnt lgkmcnt(5)
	v_mfma_f32_16x16x32_bf16 v[64:67], v[76:79], v[192:195], v[124:127]
	v_mfma_f32_16x16x32_bf16 v[68:71], v[76:79], v[196:199], v[116:119]
	s_waitcnt lgkmcnt(3)
	v_mfma_f32_16x16x32_bf16 v[72:75], v[76:79], v[200:203], v[108:111]
	s_waitcnt lgkmcnt(2)
	v_mfma_f32_16x16x32_bf16 v[76:79], v[76:79], v[204:207], v[100:103]
	v_mfma_f32_16x16x32_bf16 v[80:83], v[96:99], v[192:195], v[92:95]
	v_mfma_f32_16x16x32_bf16 v[84:87], v[96:99], v[196:199], v[84:87]
	v_mfma_f32_16x16x32_bf16 v[88:91], v[96:99], v[200:203], v[172:175]
	v_mfma_f32_16x16x32_bf16 v[92:95], v[96:99], v[204:207], v[176:179]
	s_waitcnt lgkmcnt(1)
	v_mfma_f32_16x16x32_bf16 v[96:99], v[208:211], v[192:195], v[120:123]
	v_mfma_f32_16x16x32_bf16 v[100:103], v[208:211], v[196:199], v[112:115]
	v_mfma_f32_16x16x32_bf16 v[104:107], v[208:211], v[200:203], v[104:107]
	v_mfma_f32_16x16x32_bf16 v[108:111], v[208:211], v[204:207], v[188:191]
	s_waitcnt lgkmcnt(0)
	v_mfma_f32_16x16x32_bf16 v[112:115], v[212:215], v[192:195], v[164:167]
	v_mfma_f32_16x16x32_bf16 v[116:119], v[212:215], v[196:199], v[168:171]
	v_mfma_f32_16x16x32_bf16 v[120:123], v[212:215], v[200:203], v[180:183]
	v_mfma_f32_16x16x32_bf16 v[124:127], v[212:215], v[204:207], v[184:187]
	s_setprio 0
	s_cmp_gt_u32 s21, 5
	s_cselect_b64 s[6:7], -1, 0
	s_cmp_lt_u32 s21, 6
	s_cselect_b64 s[4:5], -1, 0
	s_or_b64 s[4:5], s[2:3], s[4:5]
	s_andn2_b64 vcc, exec, s[4:5]
	s_barrier
	s_cbranch_vccnz .LBB0_406
	s_waitcnt vmcnt(15)
	ds_write_b128 v145, v[4:7]
	s_waitcnt vmcnt(14)
	ds_write_b128 v145, v[12:15] offset:20480
	s_waitcnt vmcnt(13)
	ds_write_b128 v146, v[20:23]
	s_waitcnt vmcnt(12)
	ds_write_b128 v146, v[32:35] offset:20480
	s_waitcnt vmcnt(11)
	ds_write_b128 v147, v[40:43]
	s_waitcnt vmcnt(10)
	ds_write_b128 v147, v[48:51] offset:20480
	s_waitcnt vmcnt(9)
	ds_write_b128 v148, v[52:55]
	s_waitcnt vmcnt(8)
	ds_write_b128 v148, v[60:63] offset:20480
.LBB0_406:
	s_cmp_gt_u32 s21, 3
	s_mov_b64 s[12:13], -1
	s_cbranch_scc0 .LBB0_412
	s_and_b64 vcc, exec, s[0:1]
	s_cbranch_vccz .LBB0_409
	v_mov_b32_e32 v130, v153
	s_mov_b64 s[12:13], 0
	s_waitcnt vmcnt(8)
	v_lshl_add_u64 v[4:5], v[130:131], 1, s[80:81]
	v_mov_b32_e32 v130, v154
	global_load_dwordx4 v[4:7], v[4:5], off
	s_nop 0
	v_lshl_add_u64 v[12:13], v[130:131], 1, s[10:11]
	v_mov_b32_e32 v130, v155
	global_load_dwordx4 v[12:15], v[12:13], off
	s_nop 0
	v_lshl_add_u64 v[20:21], v[130:131], 1, s[80:81]
	v_mov_b32_e32 v130, v156
	global_load_dwordx4 v[20:23], v[20:21], off
	s_nop 0
	v_lshl_add_u64 v[32:33], v[130:131], 1, s[10:11]
	v_mov_b32_e32 v130, v157
	global_load_dwordx4 v[32:35], v[32:33], off
	s_nop 0
	v_lshl_add_u64 v[40:41], v[130:131], 1, s[80:81]
	v_mov_b32_e32 v130, v158
	global_load_dwordx4 v[40:43], v[40:41], off
	s_nop 0
	v_lshl_add_u64 v[48:49], v[130:131], 1, s[10:11]
	v_mov_b32_e32 v130, v159
	global_load_dwordx4 v[48:51], v[48:49], off
	s_nop 0
	v_lshl_add_u64 v[52:53], v[130:131], 1, s[80:81]
	global_load_dwordx4 v[52:55], v[52:53], off
	v_mov_b32_e32 v130, v160
.LBB0_409:
	s_andn2_b64 vcc, exec, s[12:13]
	s_cbranch_vccnz .LBB0_411
	v_add_u32_e32 v132, v138, v143
	v_add_u32_e32 v130, 0xffffff00, v132
	v_add_u32_e32 v133, v138, v144
	s_waitcnt vmcnt(8)
	v_lshl_add_u64 v[4:5], v[130:131], 1, s[80:81]
	v_add_u32_e32 v130, 0xffffff00, v133
	global_load_dwordx4 v[4:7], v[4:5], off
	s_nop 0
	v_lshl_add_u64 v[12:13], v[130:131], 1, s[10:11]
	v_add_u32_e32 v130, 0x3f00, v132
	global_load_dwordx4 v[12:15], v[12:13], off
	s_nop 0
	v_lshl_add_u64 v[20:21], v[130:131], 1, s[80:81]
	v_add_u32_e32 v130, 0x3f00, v133
	global_load_dwordx4 v[20:23], v[20:21], off
	s_nop 0
	v_lshl_add_u64 v[32:33], v[130:131], 1, s[10:11]
	v_add_u32_e32 v130, 0x7f00, v132
	global_load_dwordx4 v[32:35], v[32:33], off
	s_nop 0
	v_lshl_add_u64 v[40:41], v[130:131], 1, s[80:81]
	v_add_u32_e32 v130, 0x7f00, v133
	global_load_dwordx4 v[40:43], v[40:41], off
	s_nop 0
	v_lshl_add_u64 v[48:49], v[130:131], 1, s[10:11]
	v_add_u32_e32 v130, 0xbf00, v132
	global_load_dwordx4 v[48:51], v[48:49], off
	s_nop 0
	v_lshl_add_u64 v[52:53], v[130:131], 1, s[80:81]
	global_load_dwordx4 v[52:55], v[52:53], off
	v_add_u32_e32 v130, 0xbf00, v133

.LBB0_413:
	v_add_u32_e32 v130, 0x100, v162
	s_waitcnt vmcnt(8)
	v_lshl_add_u64 v[4:5], v[130:131], 1, s[80:81]
	v_add_u32_e32 v130, 0x100, v161
	global_load_dwordx4 v[4:7], v[4:5], off
	s_nop 0
	v_lshl_add_u64 v[12:13], v[130:131], 1, s[10:11]
	v_add_u32_e32 v130, 0x4100, v162
	global_load_dwordx4 v[12:15], v[12:13], off
	s_nop 0
	v_lshl_add_u64 v[20:21], v[130:131], 1, s[80:81]
	v_add_u32_e32 v130, 0x4100, v161
	global_load_dwordx4 v[20:23], v[20:21], off
	s_nop 0
	v_lshl_add_u64 v[32:33], v[130:131], 1, s[10:11]
	v_add_u32_e32 v130, 0x8100, v162
	global_load_dwordx4 v[32:35], v[32:33], off
	s_nop 0
	v_lshl_add_u64 v[40:41], v[130:131], 1, s[80:81]
	v_add_u32_e32 v130, 0x8100, v161
	global_load_dwordx4 v[40:43], v[40:41], off
	s_nop 0
	v_lshl_add_u64 v[48:49], v[130:131], 1, s[10:11]
	v_add_u32_e32 v130, 0xc100, v162
	global_load_dwordx4 v[48:51], v[48:49], off
	s_nop 0
	v_lshl_add_u64 v[52:53], v[130:131], 1, s[80:81]
	global_load_dwordx4 v[52:55], v[52:53], off
	v_add_u32_e32 v130, 0xc100, v161
	s_branch .LBB0_395

.LBB0_468:
	s_waitcnt vmcnt(14)
	v_mov_b32_e32 v132, v9
	v_mov_b32_e32 v133, v10
	v_and_b32_e32 v9, 64, v137
	v_lshl_add_u32 v134, s17, 7, v148
	v_ashrrev_i32_e32 v135, 31, v134
	v_readlane_b32 s2, v237, 40
	v_lshlrev_b32_e32 v9, 1, v9
	v_cvt_pk_bf16_f32 v124, v124, v125
	v_cvt_pk_bf16_f32 v125, v126, v127
	v_lshlrev_b64 v[126:127], 11, v[134:135]
	v_readlane_b32 s3, v237, 41
	v_lshl_or_b32 v9, v141, 3, v9
	v_lshl_or_b32 v130, s16, 8, v9
	v_lshl_add_u64 v[126:127], s[2:3], 0, v[126:127]
	v_lshl_add_u64 v[126:127], v[126:127], 0, v[130:131]
	global_store_dwordx2 v[126:127], v[124:125], off
	v_add_u32_e32 v124, 16, v134
	v_ashrrev_i32_e32 v125, 31, v124
	v_cvt_pk_bf16_f32 v120, v120, v121
	v_cvt_pk_bf16_f32 v121, v122, v123
	v_lshlrev_b64 v[122:123], 11, v[124:125]
	v_lshl_add_u64 v[122:123], s[2:3], 0, v[122:123]
	v_lshl_add_u64 v[122:123], v[122:123], 0, v[130:131]
	global_store_dwordx2 v[122:123], v[120:121], off
	v_add_u32_e32 v120, 32, v134
	v_ashrrev_i32_e32 v121, 31, v120
	v_cvt_pk_bf16_f32 v116, v116, v117
	v_cvt_pk_bf16_f32 v117, v118, v119
	v_lshlrev_b64 v[118:119], 11, v[120:121]
	v_lshl_add_u64 v[118:119], s[2:3], 0, v[118:119]
	v_lshl_add_u64 v[118:119], v[118:119], 0, v[130:131]
	global_store_dwordx2 v[118:119], v[116:117], off
	v_add_u32_e32 v116, 48, v134
	v_ashrrev_i32_e32 v117, 31, v116
	v_cvt_pk_bf16_f32 v112, v112, v113
	v_cvt_pk_bf16_f32 v113, v114, v115
	v_lshlrev_b64 v[114:115], 11, v[116:117]
	v_lshl_add_u64 v[114:115], s[2:3], 0, v[114:115]
	v_lshl_add_u64 v[114:115], v[114:115], 0, v[130:131]
	v_cvt_pk_bf16_f32 v108, v108, v109
	v_cvt_pk_bf16_f32 v109, v110, v111
	v_cvt_pk_bf16_f32 v104, v104, v105
	v_cvt_pk_bf16_f32 v105, v106, v107
	v_cvt_pk_bf16_f32 v100, v100, v101
	v_cvt_pk_bf16_f32 v101, v102, v103
	v_cvt_pk_bf16_f32 v96, v96, v97
	v_cvt_pk_bf16_f32 v97, v98, v99
	v_cvt_pk_bf16_f32 v92, v92, v93
	v_cvt_pk_bf16_f32 v93, v94, v95
	v_cvt_pk_bf16_f32 v88, v88, v89
	v_cvt_pk_bf16_f32 v89, v90, v91
	v_cvt_pk_bf16_f32 v84, v84, v85
	v_cvt_pk_bf16_f32 v85, v86, v87
	v_cvt_pk_bf16_f32 v80, v80, v81
	v_cvt_pk_bf16_f32 v81, v82, v83
	v_cvt_pk_bf16_f32 v76, v76, v77
	v_cvt_pk_bf16_f32 v77, v78, v79
	v_cvt_pk_bf16_f32 v72, v72, v73
	v_cvt_pk_bf16_f32 v73, v74, v75
	v_cvt_pk_bf16_f32 v68, v68, v69
	v_cvt_pk_bf16_f32 v69, v70, v71
	v_cvt_pk_bf16_f32 v64, v64, v65
	v_cvt_pk_bf16_f32 v65, v66, v67
	s_add_i32 s15, s15, s90
	s_mov_b64 s[2:3], 0
	s_andn2_b64 vcc, exec, s[0:1]
	s_mov_b32 s6, s18
	global_store_dwordx2 v[114:115], v[112:113], off
	global_store_dwordx2 v[126:127], v[108:109], off offset:32
	global_store_dwordx2 v[122:123], v[104:105], off offset:32
	global_store_dwordx2 v[118:119], v[100:101], off offset:32
	global_store_dwordx2 v[114:115], v[96:97], off offset:32
	global_store_dwordx2 v[126:127], v[92:93], off offset:64
	global_store_dwordx2 v[122:123], v[88:89], off offset:64
	global_store_dwordx2 v[118:119], v[84:85], off offset:64
	global_store_dwordx2 v[114:115], v[80:81], off offset:64
	global_store_dwordx2 v[126:127], v[76:77], off offset:96
	global_store_dwordx2 v[122:123], v[72:73], off offset:96
	global_store_dwordx2 v[118:119], v[68:69], off offset:96
	global_store_dwordx2 v[114:115], v[64:65], off offset:96
	s_cbranch_vccz .LBB0_493

.LBB0_473:
	s_and_b32 s0, s15, 7
	s_add_i32 s18, s6, s90
	s_cmpk_gt_i32 s18, 0x7ff
	v_lshl_add_u32 v140, s0, 17, v136
	s_cselect_b64 s[0:1], -1, 0
	s_cmpk_lt_i32 s18, 0x800
	s_cselect_b64 s[2:3], -1, 0
	s_and_b64 s[4:5], s[2:3], exec
	s_cselect_b32 s4, s18, s6
	v_lshlrev_b32_e32 v10, 1, v139
	s_lshl_b32 s5, s4, 4
	s_lshl_b32 s4, s4, 7
	v_and_b32_e32 v9, 15, v137
	v_bfe_u32 v141, v137, 4, 2
	v_lshl_add_u32 v144, v70, 1, v10
	v_lshl_add_u32 v145, v67, 1, v10
	v_lshl_add_u32 v146, v68, 1, v10
	v_lshl_add_u32 v147, v69, 1, v10
	v_ashrrev_i32_e32 v10, 1, v137
	s_and_b32 s5, s5, 0x3fff80
	s_and_b32 s4, s4, 0x380
	v_and_or_b32 v148, v10, s13, v9
	v_lshlrev_b32_e32 v10, 4, v141
	v_and_b32_e32 v9, 0x4f, v137
	v_add_lshl_u32 v142, s5, v129, 10
	v_add_lshl_u32 v143, s4, v129, 10
	v_or_b32_e32 v65, 0x3c0, v139
	v_mad_u64_u32 v[134:135], s[4:5], v148, s14, v[10:11]
	v_mul_u32_u24_e32 v9, 0x50, v9
	v_lshl_add_u32 v135, v9, 1, v10
	v_add_u32_e32 v151, v65, v138
	v_add_u32_e32 v152, v65, v64
	v_mov_b32_e32 v64, 0
	v_add_u32_e32 v149, 0xf000, v135
	v_add_u32_e32 v150, 0xf040, v135
	v_add_u32_e32 v153, 0x8000, v151
	v_add_u32_e32 v154, 0x8000, v152
	v_add_u32_e32 v155, 0x10000, v151
	v_add_u32_e32 v156, 0x10000, v152
	v_add_u32_e32 v157, 0x18000, v151
	v_add_u32_e32 v158, 0x18000, v152
	s_mov_b32 s19, 0
	v_mov_b32_e32 v65, v64
	v_mov_b32_e32 v66, v64
	v_mov_b32_e32 v67, v64
	v_mov_b32_e32 v68, v64
	v_mov_b32_e32 v69, v64
	v_mov_b32_e32 v70, v64
	v_mov_b32_e32 v71, v64
	v_mov_b32_e32 v72, v64
	v_mov_b32_e32 v73, v64
	v_mov_b32_e32 v74, v64
	v_mov_b32_e32 v75, v64
	v_mov_b32_e32 v76, v64
	v_mov_b32_e32 v77, v64
	v_mov_b32_e32 v78, v64
	v_mov_b32_e32 v79, v64
	v_mov_b32_e32 v80, v64
	v_mov_b32_e32 v81, v64
	v_mov_b32_e32 v82, v64
	v_mov_b32_e32 v83, v64
	v_mov_b32_e32 v84, v64
	v_mov_b32_e32 v85, v64
	v_mov_b32_e32 v86, v64
	v_mov_b32_e32 v87, v64
	v_mov_b32_e32 v88, v64
	v_mov_b32_e32 v89, v64
	v_mov_b32_e32 v90, v64
	v_mov_b32_e32 v91, v64
	v_mov_b32_e32 v92, v64
	v_mov_b32_e32 v93, v64
	v_mov_b32_e32 v94, v64
	v_mov_b32_e32 v95, v64
	v_mov_b32_e32 v96, v64
	v_mov_b32_e32 v97, v64
	v_mov_b32_e32 v98, v64
	v_mov_b32_e32 v99, v64
	v_mov_b32_e32 v100, v64
	v_mov_b32_e32 v101, v64
	v_mov_b32_e32 v102, v64
	v_mov_b32_e32 v103, v64
	v_mov_b32_e32 v104, v64
	v_mov_b32_e32 v105, v64
	v_mov_b32_e32 v106, v64
	v_mov_b32_e32 v107, v64
	v_mov_b32_e32 v108, v64
	v_mov_b32_e32 v109, v64
	v_mov_b32_e32 v110, v64
	v_mov_b32_e32 v111, v64
	v_mov_b32_e32 v112, v64
	v_mov_b32_e32 v113, v64
	v_mov_b32_e32 v114, v64
	v_mov_b32_e32 v115, v64
	v_mov_b32_e32 v116, v64
	v_mov_b32_e32 v117, v64
	v_mov_b32_e32 v118, v64
	v_mov_b32_e32 v119, v64
	v_mov_b32_e32 v120, v64
	v_mov_b32_e32 v121, v64
	v_mov_b32_e32 v122, v64
	v_mov_b32_e32 v123, v64
	v_mov_b32_e32 v124, v64
	v_mov_b32_e32 v125, v64
	v_mov_b32_e32 v126, v64
	v_mov_b32_e32 v127, v64
	v_mov_b32_e32 v9, v132
	v_mov_b32_e32 v10, v133
	s_branch .LBB0_475
.LBB0_474:
	s_waitcnt vmcnt(15)
	v_lshl_add_u64 v[60:61], v[130:131], 1, s[8:9]
	global_load_dwordx4 v[60:63], v[60:61], off
	ds_read_b128 v[160:163], v134 offset:40960
	ds_read_b128 v[164:167], v134 offset:43520
	ds_read_b128 v[168:171], v135 offset:61440
	ds_read_b128 v[172:175], v135 offset:64000
	ds_read_b128 v[176:179], v134 offset:46080
	ds_read_b128 v[180:183], v134 offset:48640
	ds_read_b128 v[184:187], v149 offset:5120
	ds_read_b128 v[188:191], v149 offset:7680
	s_setprio 1
	s_waitcnt lgkmcnt(5)
	v_mfma_f32_16x16x32_bf16 v[64:67], v[168:171], v[160:163], v[64:67]
	v_mfma_f32_16x16x32_bf16 v[68:71], v[168:171], v[164:167], v[68:71]
	s_waitcnt lgkmcnt(3)
	v_mfma_f32_16x16x32_bf16 v[72:75], v[168:171], v[176:179], v[72:75]
	s_waitcnt lgkmcnt(2)
	v_mfma_f32_16x16x32_bf16 v[76:79], v[168:171], v[180:183], v[76:79]
	v_mfma_f32_16x16x32_bf16 v[80:83], v[172:175], v[160:163], v[80:83]
	v_mfma_f32_16x16x32_bf16 v[84:87], v[172:175], v[164:167], v[84:87]
	v_mfma_f32_16x16x32_bf16 v[88:91], v[172:175], v[176:179], v[88:91]
	v_mfma_f32_16x16x32_bf16 v[92:95], v[172:175], v[180:183], v[92:95]
	s_waitcnt lgkmcnt(1)
	v_mfma_f32_16x16x32_bf16 v[168:171], v[184:187], v[160:163], v[96:99]
	v_mfma_f32_16x16x32_bf16 v[172:175], v[184:187], v[164:167], v[100:103]
	v_mfma_f32_16x16x32_bf16 v[192:195], v[184:187], v[176:179], v[104:107]
	v_mfma_f32_16x16x32_bf16 v[184:187], v[184:187], v[180:183], v[108:111]
	s_waitcnt lgkmcnt(0)
	v_mfma_f32_16x16x32_bf16 v[160:163], v[188:191], v[160:163], v[112:115]
	v_mfma_f32_16x16x32_bf16 v[164:167], v[188:191], v[164:167], v[116:119]
	v_mfma_f32_16x16x32_bf16 v[176:179], v[188:191], v[176:179], v[120:123]
	v_mfma_f32_16x16x32_bf16 v[180:183], v[188:191], v[180:183], v[124:127]
	s_setprio 0
	ds_read_b128 v[188:191], v134 offset:41024
	ds_read_b128 v[196:199], v134 offset:43584
	ds_read_b128 v[96:99], v135 offset:61504
	ds_read_b128 v[200:203], v135 offset:64064
	ds_read_b128 v[204:207], v134 offset:46144
	ds_read_b128 v[208:211], v134 offset:48704
	ds_read_b128 v[212:215], v150 offset:5120
	ds_read_b128 v[216:219], v150 offset:7680
	s_setprio 1
	s_waitcnt lgkmcnt(5)
	v_mfma_f32_16x16x32_bf16 v[124:127], v[96:99], v[188:191], v[64:67]
	v_mfma_f32_16x16x32_bf16 v[120:123], v[96:99], v[196:199], v[68:71]
	s_waitcnt lgkmcnt(3)
	v_mfma_f32_16x16x32_bf16 v[116:119], v[96:99], v[204:207], v[72:75]
	s_waitcnt lgkmcnt(2)
	v_mfma_f32_16x16x32_bf16 v[112:115], v[96:99], v[208:211], v[76:79]
	v_mfma_f32_16x16x32_bf16 v[108:111], v[200:203], v[188:191], v[80:83]
	v_mfma_f32_16x16x32_bf16 v[104:107], v[200:203], v[196:199], v[84:87]
	v_mfma_f32_16x16x32_bf16 v[100:103], v[200:203], v[204:207], v[88:91]
	v_mfma_f32_16x16x32_bf16 v[96:99], v[200:203], v[208:211], v[92:95]
	s_waitcnt lgkmcnt(1)
	v_mfma_f32_16x16x32_bf16 v[92:95], v[212:215], v[188:191], v[168:171]
	v_mfma_f32_16x16x32_bf16 v[88:91], v[212:215], v[196:199], v[172:175]
	v_mfma_f32_16x16x32_bf16 v[84:87], v[212:215], v[204:207], v[192:195]
	v_mfma_f32_16x16x32_bf16 v[80:83], v[212:215], v[208:211], v[184:187]
	s_waitcnt lgkmcnt(0)
	v_mfma_f32_16x16x32_bf16 v[76:79], v[216:219], v[188:191], v[160:163]
	v_mfma_f32_16x16x32_bf16 v[72:75], v[216:219], v[196:199], v[164:167]
	v_mfma_f32_16x16x32_bf16 v[68:71], v[216:219], v[204:207], v[176:179]
	v_mfma_f32_16x16x32_bf16 v[64:67], v[216:219], v[208:211], v[180:183]
	s_setprio 0
	s_add_i32 s19, s19, 2
	v_add_u32_e32 v143, 0x80, v143
	v_add_u32_e32 v142, 0x80, v142
	v_add_u32_e32 v140, 0x80, v140
	s_andn2_b64 vcc, exec, s[6:7]
	v_add_u32_e32 v138, 0x80, v138
	s_cbranch_vccz .LBB0_468
.LBB0_475:
	s_cmp_gt_u32 s19, 12
	s_mov_b64 s[6:7], -1
	s_waitcnt lgkmcnt(0)
	s_barrier
	s_waitcnt vmcnt(15)
	ds_write_b128 v144, v[0:3] offset:40960
	s_waitcnt vmcnt(14)
	ds_write_b128 v144, v[8:11] offset:61440
	s_waitcnt vmcnt(13)
	ds_write_b128 v145, v[16:19] offset:40960
	s_waitcnt vmcnt(12)
	ds_write_b128 v145, v[24:27] offset:61440
	s_waitcnt vmcnt(11)
	ds_write_b128 v146, v[28:31] offset:40960
	s_waitcnt vmcnt(10)
	ds_write_b128 v146, v[36:39] offset:61440
	s_waitcnt vmcnt(9)
	ds_write_b128 v147, v[44:47] offset:40960
	s_waitcnt vmcnt(8)
	ds_write_b128 v147, v[56:59] offset:61440
	s_cbranch_scc0 .LBB0_481
	s_and_b64 vcc, exec, s[0:1]
	s_cbranch_vccz .LBB0_478
	v_mov_b32_e32 v130, v151
	s_mov_b64 s[6:7], 0
	v_lshl_add_u64 v[0:1], v[130:131], 1, s[78:79]
	v_mov_b32_e32 v130, v152
	global_load_dwordx4 v[0:3], v[0:1], off
	s_nop 0
	v_lshl_add_u64 v[8:9], v[130:131], 1, s[8:9]
	v_mov_b32_e32 v130, v153
	global_load_dwordx4 v[8:11], v[8:9], off
	s_nop 0
	s_nop 0
	v_lshl_add_u64 v[16:17], v[130:131], 1, s[78:79]
	v_mov_b32_e32 v130, v154
	global_load_dwordx4 v[16:19], v[16:17], off
	s_nop 0
	v_lshl_add_u64 v[24:25], v[130:131], 1, s[8:9]
	v_mov_b32_e32 v130, v155
	global_load_dwordx4 v[24:27], v[24:25], off
	s_nop 0
	v_lshl_add_u64 v[28:29], v[130:131], 1, s[78:79]
	v_mov_b32_e32 v130, v156
	global_load_dwordx4 v[28:31], v[28:29], off
	s_nop 0
	v_lshl_add_u64 v[36:37], v[130:131], 1, s[8:9]
	v_mov_b32_e32 v130, v157
	global_load_dwordx4 v[36:39], v[36:37], off
	s_nop 0
	v_lshl_add_u64 v[44:45], v[130:131], 1, s[78:79]
	global_load_dwordx4 v[44:47], v[44:45], off
	v_mov_b32_e32 v130, v158
.LBB0_478:
	s_andn2_b64 vcc, exec, s[6:7]
	s_cbranch_vccnz .LBB0_480
	s_waitcnt vmcnt(8)
	v_add_u32_e32 v44, v139, v142
	v_add_u32_e32 v130, 0xfffffcc0, v44
	v_add_u32_e32 v56, v139, v143
	v_lshl_add_u64 v[0:1], v[130:131], 1, s[78:79]
	v_add_u32_e32 v130, 0xfffffcc0, v56
	global_load_dwordx4 v[0:3], v[0:1], off
	s_nop 0
	v_lshl_add_u64 v[8:9], v[130:131], 1, s[8:9]
	v_add_u32_e32 v130, 0x7cc0, v44
	global_load_dwordx4 v[8:11], v[8:9], off
	s_nop 0
	s_nop 0
	v_lshl_add_u64 v[16:17], v[130:131], 1, s[78:79]
	v_add_u32_e32 v130, 0x7cc0, v56
	global_load_dwordx4 v[16:19], v[16:17], off
	s_nop 0
	v_lshl_add_u64 v[24:25], v[130:131], 1, s[8:9]
	v_add_u32_e32 v130, 0xfcc0, v44
	global_load_dwordx4 v[24:27], v[24:25], off
	s_nop 0
	v_lshl_add_u64 v[28:29], v[130:131], 1, s[78:79]
	v_add_u32_e32 v130, 0xfcc0, v56
	global_load_dwordx4 v[28:31], v[28:29], off
	s_nop 0
	v_lshl_add_u64 v[36:37], v[130:131], 1, s[8:9]
	v_add_u32_e32 v130, 0x17cc0, v44
	global_load_dwordx4 v[36:39], v[36:37], off
	s_nop 0
	v_lshl_add_u64 v[44:45], v[130:131], 1, s[78:79]
	global_load_dwordx4 v[44:47], v[44:45], off
	v_add_u32_e32 v130, 0x17cc0, v56

.LBB0_481:
	s_andn2_b64 vcc, exec, s[6:7]
	v_add_u32_e32 v160, v139, v138
	v_add_u32_e32 v159, v139, v140
	s_cbranch_vccnz .LBB0_483
	v_add_u32_e32 v130, 0xc0, v160
	s_nop 0
	v_lshl_add_u64 v[0:1], v[130:131], 1, s[78:79]
	v_add_u32_e32 v130, 0xc0, v159
	global_load_dwordx4 v[0:3], v[0:1], off
	s_nop 0
	v_lshl_add_u64 v[8:9], v[130:131], 1, s[8:9]
	v_add_u32_e32 v130, 0x80c0, v160
	global_load_dwordx4 v[8:11], v[8:9], off
	s_nop 0
	s_nop 0
	v_lshl_add_u64 v[16:17], v[130:131], 1, s[78:79]
	v_add_u32_e32 v130, 0x80c0, v159
	global_load_dwordx4 v[16:19], v[16:17], off
	s_nop 0
	v_lshl_add_u64 v[24:25], v[130:131], 1, s[8:9]
	v_add_u32_e32 v130, 0x100c0, v160
	global_load_dwordx4 v[24:27], v[24:25], off
	s_nop 0
	v_lshl_add_u64 v[28:29], v[130:131], 1, s[78:79]
	v_add_u32_e32 v130, 0x100c0, v159
	global_load_dwordx4 v[28:31], v[28:29], off
	s_nop 0
	v_lshl_add_u64 v[36:37], v[130:131], 1, s[8:9]
	v_add_u32_e32 v130, 0x180c0, v160
	global_load_dwordx4 v[36:39], v[36:37], off
	s_nop 0
	v_lshl_add_u64 v[44:45], v[130:131], 1, s[78:79]
	global_load_dwordx4 v[44:47], v[44:45], off
	v_add_u32_e32 v130, 0x180c0, v159
.LBB0_483:
	s_nop 0
	v_lshl_add_u64 v[56:57], v[130:131], 1, s[8:9]
	global_load_dwordx4 v[56:59], v[56:57], off
	ds_read_b128 v[162:165], v134
	ds_read_b128 v[166:169], v134 offset:2560
	ds_read_b128 v[170:173], v135 offset:20480
	ds_read_b128 v[174:177], v135 offset:23040
	ds_read_b128 v[178:181], v134 offset:5120
	ds_read_b128 v[182:185], v134 offset:7680
	ds_read_b128 v[186:189], v135 offset:25600
	ds_read_b128 v[190:193], v135 offset:28160
	s_setprio 1
	s_waitcnt lgkmcnt(5)
	v_mfma_f32_16x16x32_bf16 v[124:127], v[170:173], v[162:165], v[124:127]
	v_mfma_f32_16x16x32_bf16 v[120:123], v[170:173], v[166:169], v[120:123]
	s_waitcnt lgkmcnt(3)
	v_mfma_f32_16x16x32_bf16 v[116:119], v[170:173], v[178:181], v[116:119]
	s_waitcnt lgkmcnt(2)
	v_mfma_f32_16x16x32_bf16 v[112:115], v[170:173], v[182:185], v[112:115]
	v_mfma_f32_16x16x32_bf16 v[108:111], v[174:177], v[162:165], v[108:111]
	v_mfma_f32_16x16x32_bf16 v[104:107], v[174:177], v[166:169], v[104:107]
	v_mfma_f32_16x16x32_bf16 v[100:103], v[174:177], v[178:181], v[100:103]
	v_mfma_f32_16x16x32_bf16 v[96:99], v[174:177], v[182:185], v[96:99]
	s_waitcnt lgkmcnt(1)
	v_mfma_f32_16x16x32_bf16 v[170:173], v[186:189], v[162:165], v[92:95]
	v_mfma_f32_16x16x32_bf16 v[174:177], v[186:189], v[166:169], v[88:91]
	v_mfma_f32_16x16x32_bf16 v[194:197], v[186:189], v[178:181], v[84:87]
	v_mfma_f32_16x16x32_bf16 v[186:189], v[186:189], v[182:185], v[80:83]
	s_waitcnt lgkmcnt(0)
	v_mfma_f32_16x16x32_bf16 v[162:165], v[190:193], v[162:165], v[76:79]
	v_mfma_f32_16x16x32_bf16 v[166:169], v[190:193], v[166:169], v[72:75]
	v_mfma_f32_16x16x32_bf16 v[178:181], v[190:193], v[178:181], v[68:71]
	v_mfma_f32_16x16x32_bf16 v[182:185], v[190:193], v[182:185], v[64:67]
	s_setprio 0
	ds_read_b128 v[190:193], v134 offset:64
	ds_read_b128 v[198:201], v134 offset:2624
	ds_read_b128 v[76:79], v135 offset:20544
	ds_read_b128 v[92:95], v135 offset:23104
	ds_read_b128 v[202:205], v134 offset:5184
	ds_read_b128 v[206:209], v134 offset:7744
	ds_read_b128 v[210:213], v135 offset:25664
	ds_read_b128 v[214:217], v135 offset:28224
	s_setprio 1
	s_waitcnt lgkmcnt(5)
	v_mfma_f32_16x16x32_bf16 v[64:67], v[76:79], v[190:193], v[124:127]
	v_mfma_f32_16x16x32_bf16 v[68:71], v[76:79], v[198:201], v[120:123]
	s_waitcnt lgkmcnt(3)
	v_mfma_f32_16x16x32_bf16 v[72:75], v[76:79], v[202:205], v[116:119]
	s_waitcnt lgkmcnt(2)
	v_mfma_f32_16x16x32_bf16 v[76:79], v[76:79], v[206:209], v[112:115]
	v_mfma_f32_16x16x32_bf16 v[80:83], v[92:95], v[190:193], v[108:111]
	v_mfma_f32_16x16x32_bf16 v[84:87], v[92:95], v[198:201], v[104:107]
	v_mfma_f32_16x16x32_bf16 v[88:91], v[92:95], v[202:205], v[100:103]
	v_mfma_f32_16x16x32_bf16 v[92:95], v[92:95], v[206:209], v[96:99]
	s_waitcnt lgkmcnt(1)
	v_mfma_f32_16x16x32_bf16 v[96:99], v[210:213], v[190:193], v[170:173]
	v_mfma_f32_16x16x32_bf16 v[100:103], v[210:213], v[198:201], v[174:177]
	v_mfma_f32_16x16x32_bf16 v[104:107], v[210:213], v[202:205], v[194:197]
	v_mfma_f32_16x16x32_bf16 v[108:111], v[210:213], v[206:209], v[186:189]
	s_waitcnt lgkmcnt(0)
	v_mfma_f32_16x16x32_bf16 v[112:115], v[214:217], v[190:193], v[162:165]
	v_mfma_f32_16x16x32_bf16 v[116:119], v[214:217], v[198:201], v[166:169]
	v_mfma_f32_16x16x32_bf16 v[120:123], v[214:217], v[202:205], v[178:181]
	v_mfma_f32_16x16x32_bf16 v[124:127], v[214:217], v[206:209], v[182:185]
	s_setprio 0
	s_cmp_gt_u32 s19, 13
	s_cselect_b64 s[6:7], -1, 0
	s_cmp_lt_u32 s19, 14
	s_cselect_b64 s[4:5], -1, 0
	s_or_b64 s[4:5], s[2:3], s[4:5]
	s_andn2_b64 vcc, exec, s[4:5]
	s_barrier
	s_cbranch_vccnz .LBB0_485
	s_waitcnt vmcnt(15)
	ds_write_b128 v144, v[4:7]
	s_waitcnt vmcnt(14)
	ds_write_b128 v144, v[12:15] offset:20480
	s_waitcnt vmcnt(13)
	ds_write_b128 v145, v[20:23]
	s_waitcnt vmcnt(12)
	ds_write_b128 v145, v[32:35] offset:20480
	s_waitcnt vmcnt(11)
	ds_write_b128 v146, v[40:43]
	s_waitcnt vmcnt(10)
	ds_write_b128 v146, v[48:51] offset:20480
	s_waitcnt vmcnt(9)
	ds_write_b128 v147, v[52:55]
	s_waitcnt vmcnt(8)
	ds_write_b128 v147, v[60:63] offset:20480
.LBB0_485:
	s_cmp_gt_u32 s19, 11
	s_mov_b64 s[10:11], -1
	s_cbranch_scc0 .LBB0_491
	s_and_b64 vcc, exec, s[0:1]
	s_cbranch_vccz .LBB0_488
	v_mov_b32_e32 v130, v151
	s_mov_b64 s[10:11], 0
	s_waitcnt vmcnt(8)
	v_lshl_add_u64 v[4:5], v[130:131], 1, s[78:79]
	v_mov_b32_e32 v130, v152
	global_load_dwordx4 v[4:7], v[4:5], off
	s_nop 0
	v_lshl_add_u64 v[12:13], v[130:131], 1, s[8:9]
	v_mov_b32_e32 v130, v153
	global_load_dwordx4 v[12:15], v[12:13], off
	s_nop 0
	v_lshl_add_u64 v[20:21], v[130:131], 1, s[78:79]
	v_mov_b32_e32 v130, v154
	global_load_dwordx4 v[20:23], v[20:21], off
	s_nop 0
	v_lshl_add_u64 v[32:33], v[130:131], 1, s[8:9]
	v_mov_b32_e32 v130, v155
	global_load_dwordx4 v[32:35], v[32:33], off
	s_nop 0
	v_lshl_add_u64 v[40:41], v[130:131], 1, s[78:79]
	v_mov_b32_e32 v130, v156
	global_load_dwordx4 v[40:43], v[40:41], off
	s_nop 0
	v_lshl_add_u64 v[48:49], v[130:131], 1, s[8:9]
	v_mov_b32_e32 v130, v157
	global_load_dwordx4 v[48:51], v[48:49], off
	s_nop 0
	v_lshl_add_u64 v[52:53], v[130:131], 1, s[78:79]
	global_load_dwordx4 v[52:55], v[52:53], off
	v_mov_b32_e32 v130, v158
.LBB0_488:
	s_andn2_b64 vcc, exec, s[10:11]
	s_cbranch_vccnz .LBB0_490
	v_add_u32_e32 v132, v139, v142
	v_add_u32_e32 v130, 0xfffffd00, v132
	v_add_u32_e32 v133, v139, v143
	s_waitcnt vmcnt(8)
	v_lshl_add_u64 v[4:5], v[130:131], 1, s[78:79]
	v_add_u32_e32 v130, 0xfffffd00, v133
	global_load_dwordx4 v[4:7], v[4:5], off
	s_nop 0
	v_lshl_add_u64 v[12:13], v[130:131], 1, s[8:9]
	v_add_u32_e32 v130, 0x7d00, v132
	global_load_dwordx4 v[12:15], v[12:13], off
	s_nop 0
	v_lshl_add_u64 v[20:21], v[130:131], 1, s[78:79]
	v_add_u32_e32 v130, 0x7d00, v133
	global_load_dwordx4 v[20:23], v[20:21], off
	s_nop 0
	v_lshl_add_u64 v[32:33], v[130:131], 1, s[8:9]
	v_add_u32_e32 v130, 0xfd00, v132
	global_load_dwordx4 v[32:35], v[32:33], off
	s_nop 0
	v_lshl_add_u64 v[40:41], v[130:131], 1, s[78:79]
	v_add_u32_e32 v130, 0xfd00, v133
	global_load_dwordx4 v[40:43], v[40:41], off
	s_nop 0
	v_lshl_add_u64 v[48:49], v[130:131], 1, s[8:9]
	v_add_u32_e32 v130, 0x17d00, v132
	global_load_dwordx4 v[48:51], v[48:49], off
	s_nop 0
	v_lshl_add_u64 v[52:53], v[130:131], 1, s[78:79]
	global_load_dwordx4 v[52:55], v[52:53], off
	v_add_u32_e32 v130, 0x17d00, v133

.LBB0_492:
	v_add_u32_e32 v130, 0x100, v160
	s_waitcnt vmcnt(8)
	v_lshl_add_u64 v[4:5], v[130:131], 1, s[78:79]
	v_add_u32_e32 v130, 0x100, v159
	global_load_dwordx4 v[4:7], v[4:5], off
	s_nop 0
	v_lshl_add_u64 v[12:13], v[130:131], 1, s[8:9]
	v_add_u32_e32 v130, 0x8100, v160
	global_load_dwordx4 v[12:15], v[12:13], off
	s_nop 0
	v_lshl_add_u64 v[20:21], v[130:131], 1, s[78:79]
	v_add_u32_e32 v130, 0x8100, v159
	global_load_dwordx4 v[20:23], v[20:21], off
	s_nop 0
	v_lshl_add_u64 v[32:33], v[130:131], 1, s[8:9]
	v_add_u32_e32 v130, 0x10100, v160
	global_load_dwordx4 v[32:35], v[32:33], off
	s_nop 0
	v_lshl_add_u64 v[40:41], v[130:131], 1, s[78:79]
	v_add_u32_e32 v130, 0x10100, v159
	global_load_dwordx4 v[40:43], v[40:41], off
	s_nop 0
	v_lshl_add_u64 v[48:49], v[130:131], 1, s[8:9]
	v_add_u32_e32 v130, 0x18100, v160
	global_load_dwordx4 v[48:51], v[48:49], off
	s_nop 0
	v_lshl_add_u64 v[52:53], v[130:131], 1, s[78:79]
	global_load_dwordx4 v[52:55], v[52:53], off
	v_add_u32_e32 v130, 0x18100, v159
	s_branch .LBB0_474

.LBB0_704:
	s_waitcnt vmcnt(15)
	v_lshl_add_u64 v[60:61], v[130:131], 1, s[12:13]
	global_load_dwordx4 v[60:63], v[60:61], off
	ds_read_b128 v[184:187], v136 offset:40960
	ds_read_b128 v[188:191], v136 offset:43520
	ds_read_b128 v[192:195], v137 offset:61440
	ds_read_b128 v[196:199], v137 offset:64000
	ds_read_b128 v[200:203], v136 offset:46080
	ds_read_b128 v[204:207], v136 offset:48640
	ds_read_b128 v[208:211], v161
	ds_read_b128 v[212:215], v162
	s_setprio 1
	s_waitcnt lgkmcnt(5)
	v_mfma_f32_16x16x32_bf16 v[64:67], v[192:195], v[184:187], v[64:67]
	v_mfma_f32_16x16x32_bf16 v[68:71], v[192:195], v[188:191], v[68:71]
	s_waitcnt lgkmcnt(3)
	v_mfma_f32_16x16x32_bf16 v[72:75], v[192:195], v[200:203], v[72:75]
	s_waitcnt lgkmcnt(2)
	v_mfma_f32_16x16x32_bf16 v[76:79], v[192:195], v[204:207], v[76:79]
	v_mfma_f32_16x16x32_bf16 v[80:83], v[196:199], v[184:187], v[80:83]
	v_mfma_f32_16x16x32_bf16 v[84:87], v[196:199], v[188:191], v[84:87]
	v_mfma_f32_16x16x32_bf16 v[88:91], v[196:199], v[200:203], v[88:91]
	s_waitcnt lgkmcnt(1)
	v_mfma_f32_16x16x32_bf16 v[96:99], v[208:211], v[184:187], v[96:99]
	s_waitcnt lgkmcnt(0)
	v_mfma_f32_16x16x32_bf16 v[112:115], v[212:215], v[184:187], v[112:115]
	v_mfma_f32_16x16x32_bf16 v[192:195], v[196:199], v[204:207], v[92:95]
	v_mfma_f32_16x16x32_bf16 v[196:199], v[208:211], v[188:191], v[100:103]
	v_mfma_f32_16x16x32_bf16 v[216:219], v[208:211], v[200:203], v[104:107]
	v_mfma_f32_16x16x32_bf16 v[208:211], v[208:211], v[204:207], v[108:111]
	v_mfma_f32_16x16x32_bf16 v[184:187], v[212:215], v[188:191], v[116:119]
	v_mfma_f32_16x16x32_bf16 v[188:191], v[212:215], v[200:203], v[120:123]
	v_mfma_f32_16x16x32_bf16 v[200:203], v[212:215], v[204:207], v[124:127]
	s_setprio 0
	ds_read_b128 v[204:207], v136 offset:41024
	ds_read_b128 v[212:215], v136 offset:43584
	ds_read_b128 v[100:103], v137 offset:61504
	ds_read_b128 v[104:107], v137 offset:64064
	ds_read_b128 v[220:223], v136 offset:46144
	ds_read_b128 v[224:227], v136 offset:48704
	ds_read_b128 v[228:231], v163
	ds_read_b128 v[232:235], v164
	s_setprio 1
	s_waitcnt lgkmcnt(5)
	v_mfma_f32_16x16x32_bf16 v[124:127], v[100:103], v[204:207], v[64:67]
	v_mfma_f32_16x16x32_bf16 v[108:111], v[100:103], v[212:215], v[68:71]
	s_waitcnt lgkmcnt(3)
	v_mfma_f32_16x16x32_bf16 v[92:95], v[100:103], v[220:223], v[72:75]
	s_waitcnt lgkmcnt(2)
	v_mfma_f32_16x16x32_bf16 v[76:79], v[100:103], v[224:227], v[76:79]
	v_mfma_f32_16x16x32_bf16 v[116:119], v[104:107], v[204:207], v[80:83]
	v_mfma_f32_16x16x32_bf16 v[100:103], v[104:107], v[212:215], v[84:87]
	v_mfma_f32_16x16x32_bf16 v[84:87], v[104:107], v[220:223], v[88:91]
	v_mfma_f32_16x16x32_bf16 v[68:71], v[104:107], v[224:227], v[192:195]
	s_waitcnt lgkmcnt(1)
	v_mfma_f32_16x16x32_bf16 v[120:123], v[228:231], v[204:207], v[96:99]
	v_mfma_f32_16x16x32_bf16 v[104:107], v[228:231], v[212:215], v[196:199]
	v_mfma_f32_16x16x32_bf16 v[88:91], v[228:231], v[220:223], v[216:219]
	v_mfma_f32_16x16x32_bf16 v[72:75], v[228:231], v[224:227], v[208:211]
	s_waitcnt lgkmcnt(0)
	v_mfma_f32_16x16x32_bf16 v[112:115], v[232:235], v[204:207], v[112:115]
	v_mfma_f32_16x16x32_bf16 v[96:99], v[232:235], v[212:215], v[184:187]
	v_mfma_f32_16x16x32_bf16 v[80:83], v[232:235], v[220:223], v[188:191]
	v_mfma_f32_16x16x32_bf16 v[64:67], v[232:235], v[224:227], v[200:203]
	s_setprio 0
	s_add_i32 s2, s2, 2
	v_add_u32_e32 v182, 0x80, v182
	v_add_u32_e32 v181, 0x80, v181
	v_add_u32_e32 v180, 0x80, v180
	v_add_u32_e32 v179, 0x80, v179
	v_add_u32_e32 v178, 0x80, v178
	v_add_u32_e32 v177, 0x80, v177
	v_add_u32_e32 v176, 0x80, v176
	v_add_u32_e32 v175, 0x80, v175
	v_add_u32_e32 v174, 0x80, v174
	v_add_u32_e32 v173, 0x80, v173
	s_and_b64 vcc, exec, s[0:1]
	s_cbranch_vccnz .LBB0_723
.LBB0_705:
	s_cmp_gt_u32 s2, 12
	s_mov_b64 s[0:1], -1
	s_waitcnt lgkmcnt(0)
	s_barrier
	s_waitcnt vmcnt(15)
	ds_write_b128 v141, v[0:3] offset:40960
	s_waitcnt vmcnt(14)
	ds_write_b128 v141, v[8:11] offset:61440
	s_waitcnt vmcnt(13)
	ds_write_b128 v158, v[16:19] offset:40960
	s_waitcnt vmcnt(12)
	ds_write_b128 v158, v[24:27] offset:61440
	s_waitcnt vmcnt(11)
	ds_write_b128 v159, v[28:31] offset:40960
	s_waitcnt vmcnt(10)
	ds_write_b128 v159, v[36:39] offset:61440
	s_waitcnt vmcnt(9)
	ds_write_b128 v160, v[44:47] offset:40960
	s_waitcnt vmcnt(8)
	ds_write_b128 v160, v[56:59] offset:61440
	s_cbranch_scc0 .LBB0_711
	s_and_b64 vcc, exec, s[8:9]
	s_cbranch_vccz .LBB0_708
	v_mov_b32_e32 v130, v165
	s_mov_b64 s[0:1], 0
	v_lshl_add_u64 v[0:1], v[130:131], 1, s[76:77]
	v_mov_b32_e32 v130, v166
	global_load_dwordx4 v[0:3], v[0:1], off
	s_nop 0
	v_lshl_add_u64 v[8:9], v[130:131], 1, s[12:13]
	v_mov_b32_e32 v130, v167
	global_load_dwordx4 v[8:11], v[8:9], off
	s_nop 0
	v_lshl_add_u64 v[16:17], v[130:131], 1, s[76:77]
	v_mov_b32_e32 v130, v168
	global_load_dwordx4 v[16:19], v[16:17], off
	s_nop 0
	v_lshl_add_u64 v[24:25], v[130:131], 1, s[12:13]
	v_mov_b32_e32 v130, v169
	global_load_dwordx4 v[24:27], v[24:25], off
	s_nop 0
	v_lshl_add_u64 v[28:29], v[130:131], 1, s[76:77]
	v_mov_b32_e32 v130, v170
	global_load_dwordx4 v[28:31], v[28:29], off
	s_nop 0
	v_lshl_add_u64 v[36:37], v[130:131], 1, s[12:13]
	v_mov_b32_e32 v130, v171
	global_load_dwordx4 v[36:39], v[36:37], off
	s_nop 0
	v_lshl_add_u64 v[44:45], v[130:131], 1, s[76:77]
	global_load_dwordx4 v[44:47], v[44:45], off
	v_mov_b32_e32 v130, v172
.LBB0_708:
	s_andn2_b64 vcc, exec, s[0:1]
	s_cbranch_vccnz .LBB0_710
	v_add3_u32 v130, v133, v178, s33
	v_add_u32_e32 v56, v133, v179
	s_nop 0
	v_lshl_add_u64 v[0:1], v[130:131], 1, s[76:77]
	v_add_u32_e32 v130, 0xfffffcc0, v56
	global_load_dwordx4 v[0:3], v[0:1], off
	s_nop 0
	v_lshl_add_u64 v[8:9], v[130:131], 1, s[12:13]
	v_add3_u32 v130, v133, v180, s33
	global_load_dwordx4 v[8:11], v[8:9], off
	s_nop 0
	v_lshl_add_u64 v[16:17], v[130:131], 1, s[76:77]
	v_add_u32_e32 v130, 0x7cc0, v56
	global_load_dwordx4 v[16:19], v[16:17], off
	s_nop 0
	v_lshl_add_u64 v[24:25], v[130:131], 1, s[12:13]
	v_add3_u32 v130, v133, v181, s33
	global_load_dwordx4 v[24:27], v[24:25], off
	s_nop 0
	v_lshl_add_u64 v[28:29], v[130:131], 1, s[76:77]
	v_add_u32_e32 v130, 0xfcc0, v56
	global_load_dwordx4 v[28:31], v[28:29], off
	s_nop 0
	v_lshl_add_u64 v[36:37], v[130:131], 1, s[12:13]
	v_add3_u32 v130, v133, v182, s33
	global_load_dwordx4 v[36:39], v[36:37], off
	s_nop 0
	v_lshl_add_u64 v[44:45], v[130:131], 1, s[76:77]
	global_load_dwordx4 v[44:47], v[44:45], off
	v_add_u32_e32 v130, 0x17cc0, v56

.LBB0_711:
	s_andn2_b64 vcc, exec, s[0:1]
	v_add_u32_e32 v183, v133, v174
	s_cbranch_vccnz .LBB0_713
	v_add3_u32 v130, v133, v173, s96
	s_nop 0
	v_lshl_add_u64 v[0:1], v[130:131], 1, s[76:77]
	v_add_u32_e32 v130, 0xc0, v183
	global_load_dwordx4 v[0:3], v[0:1], off
	s_nop 0
	v_lshl_add_u64 v[8:9], v[130:131], 1, s[12:13]
	v_add3_u32 v130, v133, v175, s96
	global_load_dwordx4 v[8:11], v[8:9], off
	s_nop 0
	v_lshl_add_u64 v[16:17], v[130:131], 1, s[76:77]
	v_add_u32_e32 v130, 0x80c0, v183
	global_load_dwordx4 v[16:19], v[16:17], off
	s_nop 0
	v_lshl_add_u64 v[24:25], v[130:131], 1, s[12:13]
	v_add3_u32 v130, v133, v176, s96
	global_load_dwordx4 v[24:27], v[24:25], off
	s_nop 0
	v_lshl_add_u64 v[28:29], v[130:131], 1, s[76:77]
	v_add_u32_e32 v130, 0x100c0, v183
	global_load_dwordx4 v[28:31], v[28:29], off
	s_nop 0
	v_lshl_add_u64 v[36:37], v[130:131], 1, s[12:13]
	v_add3_u32 v130, v133, v177, s96
	global_load_dwordx4 v[36:39], v[36:37], off
	s_nop 0
	v_lshl_add_u64 v[44:45], v[130:131], 1, s[76:77]
	global_load_dwordx4 v[44:47], v[44:45], off
	v_add_u32_e32 v130, 0x180c0, v183
.LBB0_713:
	s_nop 0
	v_lshl_add_u64 v[56:57], v[130:131], 1, s[12:13]
	global_load_dwordx4 v[56:59], v[56:57], off
	ds_read_b128 v[184:187], v136
	ds_read_b128 v[188:191], v136 offset:2560
	ds_read_b128 v[192:195], v137 offset:20480
	ds_read_b128 v[196:199], v137 offset:23040
	ds_read_b128 v[200:203], v136 offset:5120
	ds_read_b128 v[204:207], v136 offset:7680
	ds_read_b128 v[208:211], v137 offset:25600
	ds_read_b128 v[212:215], v137 offset:28160
	s_setprio 1
	s_waitcnt lgkmcnt(5)
	v_mfma_f32_16x16x32_bf16 v[124:127], v[192:195], v[184:187], v[124:127]
	v_mfma_f32_16x16x32_bf16 v[108:111], v[192:195], v[188:191], v[108:111]
	s_waitcnt lgkmcnt(3)
	v_mfma_f32_16x16x32_bf16 v[92:95], v[192:195], v[200:203], v[92:95]
	s_waitcnt lgkmcnt(2)
	v_mfma_f32_16x16x32_bf16 v[76:79], v[192:195], v[204:207], v[76:79]
	v_mfma_f32_16x16x32_bf16 v[116:119], v[196:199], v[184:187], v[116:119]
	v_mfma_f32_16x16x32_bf16 v[100:103], v[196:199], v[188:191], v[100:103]
	s_waitcnt lgkmcnt(1)
	v_mfma_f32_16x16x32_bf16 v[120:123], v[208:211], v[184:187], v[120:123]
	v_mfma_f32_16x16x32_bf16 v[104:107], v[208:211], v[188:191], v[104:107]
	s_waitcnt lgkmcnt(0)
	v_mfma_f32_16x16x32_bf16 v[112:115], v[212:215], v[184:187], v[112:115]
	v_mfma_f32_16x16x32_bf16 v[192:195], v[196:199], v[200:203], v[84:87]
	v_mfma_f32_16x16x32_bf16 v[196:199], v[196:199], v[204:207], v[68:71]
	v_mfma_f32_16x16x32_bf16 v[216:219], v[208:211], v[200:203], v[88:91]
	v_mfma_f32_16x16x32_bf16 v[208:211], v[208:211], v[204:207], v[72:75]
	v_mfma_f32_16x16x32_bf16 v[184:187], v[212:215], v[188:191], v[96:99]
	v_mfma_f32_16x16x32_bf16 v[188:191], v[212:215], v[200:203], v[80:83]
	v_mfma_f32_16x16x32_bf16 v[200:203], v[212:215], v[204:207], v[64:67]
	s_setprio 0
	ds_read_b128 v[204:207], v136 offset:64
	ds_read_b128 v[212:215], v136 offset:2624
	ds_read_b128 v[80:83], v137 offset:20544
	ds_read_b128 v[96:99], v137 offset:23104
	ds_read_b128 v[220:223], v136 offset:5184
	ds_read_b128 v[224:227], v136 offset:7744
	ds_read_b128 v[228:231], v137 offset:25664
	ds_read_b128 v[232:235], v137 offset:28224
	s_setprio 1
	s_waitcnt lgkmcnt(5)
	v_mfma_f32_16x16x32_bf16 v[64:67], v[80:83], v[204:207], v[124:127]
	v_mfma_f32_16x16x32_bf16 v[68:71], v[80:83], v[212:215], v[108:111]
	s_waitcnt lgkmcnt(3)
	v_mfma_f32_16x16x32_bf16 v[72:75], v[80:83], v[220:223], v[92:95]
	s_waitcnt lgkmcnt(2)
	v_mfma_f32_16x16x32_bf16 v[76:79], v[80:83], v[224:227], v[76:79]
	v_mfma_f32_16x16x32_bf16 v[80:83], v[96:99], v[204:207], v[116:119]
	v_mfma_f32_16x16x32_bf16 v[84:87], v[96:99], v[212:215], v[100:103]
	v_mfma_f32_16x16x32_bf16 v[88:91], v[96:99], v[220:223], v[192:195]
	v_mfma_f32_16x16x32_bf16 v[92:95], v[96:99], v[224:227], v[196:199]
	s_waitcnt lgkmcnt(1)
	v_mfma_f32_16x16x32_bf16 v[96:99], v[228:231], v[204:207], v[120:123]
	v_mfma_f32_16x16x32_bf16 v[100:103], v[228:231], v[212:215], v[104:107]
	v_mfma_f32_16x16x32_bf16 v[104:107], v[228:231], v[220:223], v[216:219]
	v_mfma_f32_16x16x32_bf16 v[108:111], v[228:231], v[224:227], v[208:211]
	s_waitcnt lgkmcnt(0)
	v_mfma_f32_16x16x32_bf16 v[112:115], v[232:235], v[204:207], v[112:115]
	v_mfma_f32_16x16x32_bf16 v[116:119], v[232:235], v[212:215], v[184:187]
	v_mfma_f32_16x16x32_bf16 v[120:123], v[232:235], v[220:223], v[188:191]
	v_mfma_f32_16x16x32_bf16 v[124:127], v[232:235], v[224:227], v[200:203]
	s_setprio 0
	s_cmp_gt_u32 s2, 13
	s_cselect_b64 s[0:1], -1, 0
	s_cmp_lt_u32 s2, 14
	s_cselect_b64 s[4:5], -1, 0
	s_or_b64 s[4:5], s[10:11], s[4:5]
	s_andn2_b64 vcc, exec, s[4:5]
	s_barrier
	s_cbranch_vccnz .LBB0_715
	s_waitcnt vmcnt(15)
	ds_write_b128 v141, v[4:7]
	s_waitcnt vmcnt(14)
	ds_write_b128 v141, v[12:15] offset:20480
	s_waitcnt vmcnt(13)
	ds_write_b128 v158, v[20:23]
	s_waitcnt vmcnt(12)
	ds_write_b128 v158, v[32:35] offset:20480
	s_waitcnt vmcnt(11)
	ds_write_b128 v159, v[40:43]
	s_waitcnt vmcnt(10)
	ds_write_b128 v159, v[48:51] offset:20480
	s_waitcnt vmcnt(9)
	ds_write_b128 v160, v[52:55]
	s_waitcnt vmcnt(8)
	ds_write_b128 v160, v[60:63] offset:20480
.LBB0_715:
	s_cmp_gt_u32 s2, 11
	s_mov_b64 s[6:7], -1
	s_cbranch_scc0 .LBB0_721
	s_and_b64 vcc, exec, s[8:9]
	s_cbranch_vccz .LBB0_718
	v_mov_b32_e32 v130, v165
	s_mov_b64 s[6:7], 0
	s_waitcnt vmcnt(8)
	v_lshl_add_u64 v[4:5], v[130:131], 1, s[76:77]
	v_mov_b32_e32 v130, v166
	global_load_dwordx4 v[4:7], v[4:5], off
	s_nop 0
	v_lshl_add_u64 v[12:13], v[130:131], 1, s[12:13]
	v_mov_b32_e32 v130, v167
	global_load_dwordx4 v[12:15], v[12:13], off
	s_nop 0
	v_lshl_add_u64 v[20:21], v[130:131], 1, s[76:77]
	v_mov_b32_e32 v130, v168
	global_load_dwordx4 v[20:23], v[20:21], off
	s_nop 0
	v_lshl_add_u64 v[32:33], v[130:131], 1, s[12:13]
	v_mov_b32_e32 v130, v169
	global_load_dwordx4 v[32:35], v[32:33], off
	s_nop 0
	v_lshl_add_u64 v[40:41], v[130:131], 1, s[76:77]
	v_mov_b32_e32 v130, v170
	global_load_dwordx4 v[40:43], v[40:41], off
	s_nop 0
	v_lshl_add_u64 v[48:49], v[130:131], 1, s[12:13]
	v_mov_b32_e32 v130, v171
	global_load_dwordx4 v[48:51], v[48:49], off
	s_nop 0
	v_lshl_add_u64 v[52:53], v[130:131], 1, s[76:77]
	global_load_dwordx4 v[52:55], v[52:53], off
	v_mov_b32_e32 v130, v172
.LBB0_718:
	s_andn2_b64 vcc, exec, s[6:7]
	s_cbranch_vccnz .LBB0_720
	v_add3_u32 v130, v133, v178, s97
	s_waitcnt vmcnt(8)
	v_add_u32_e32 v60, v133, v179
	s_nop 0
	v_lshl_add_u64 v[4:5], v[130:131], 1, s[76:77]
	v_add_u32_e32 v130, 0xfffffd00, v60
	global_load_dwordx4 v[4:7], v[4:5], off
	s_nop 0
	v_lshl_add_u64 v[12:13], v[130:131], 1, s[12:13]
	v_add3_u32 v130, v133, v180, s97
	global_load_dwordx4 v[12:15], v[12:13], off
	s_nop 0
	v_lshl_add_u64 v[20:21], v[130:131], 1, s[76:77]
	v_add_u32_e32 v130, 0x7d00, v60
	global_load_dwordx4 v[20:23], v[20:21], off
	s_nop 0
	v_lshl_add_u64 v[32:33], v[130:131], 1, s[12:13]
	v_add3_u32 v130, v133, v181, s97
	global_load_dwordx4 v[32:35], v[32:33], off
	s_nop 0
	v_lshl_add_u64 v[40:41], v[130:131], 1, s[76:77]
	v_add_u32_e32 v130, 0xfd00, v60
	global_load_dwordx4 v[40:43], v[40:41], off
	s_nop 0
	v_lshl_add_u64 v[48:49], v[130:131], 1, s[12:13]
	v_add3_u32 v130, v133, v182, s97
	global_load_dwordx4 v[48:51], v[48:49], off
	s_nop 0
	v_lshl_add_u64 v[52:53], v[130:131], 1, s[76:77]
	global_load_dwordx4 v[52:55], v[52:53], off
	v_add_u32_e32 v130, 0x17d00, v60

.LBB0_722:
	v_add3_u32 v130, v133, v173, s16
	s_waitcnt vmcnt(8)
	v_lshl_add_u64 v[4:5], v[130:131], 1, s[76:77]
	v_add_u32_e32 v130, 0x100, v183
	global_load_dwordx4 v[4:7], v[4:5], off
	s_nop 0
	v_lshl_add_u64 v[12:13], v[130:131], 1, s[12:13]
	v_add3_u32 v130, v133, v175, s16
	global_load_dwordx4 v[12:15], v[12:13], off
	s_nop 0
	v_lshl_add_u64 v[20:21], v[130:131], 1, s[76:77]
	v_add_u32_e32 v130, 0x8100, v183
	global_load_dwordx4 v[20:23], v[20:21], off
	s_nop 0
	v_lshl_add_u64 v[32:33], v[130:131], 1, s[12:13]
	v_add3_u32 v130, v133, v176, s16
	global_load_dwordx4 v[32:35], v[32:33], off
	s_nop 0
	v_lshl_add_u64 v[40:41], v[130:131], 1, s[76:77]
	v_add_u32_e32 v130, 0x10100, v183
	global_load_dwordx4 v[40:43], v[40:41], off
	s_nop 0
	v_lshl_add_u64 v[48:49], v[130:131], 1, s[12:13]
	v_add3_u32 v130, v133, v177, s16
	global_load_dwordx4 v[48:51], v[48:49], off
	s_nop 0
	v_lshl_add_u64 v[52:53], v[130:131], 1, s[76:77]
	global_load_dwordx4 v[52:55], v[52:53], off
	v_add_u32_e32 v130, 0x18100, v183
	s_branch .LBB0_704

.LBB0_844:
	s_waitcnt vmcnt(15)
	v_lshl_add_u64 v[60:61], v[132:133], 1, s[18:19]
	global_load_dwordx4 v[60:63], v[60:61], off
	ds_read_b128 v[176:179], v134 offset:40960
	ds_read_b128 v[180:183], v134 offset:43520
	ds_read_b128 v[184:187], v135 offset:61440
	ds_read_b128 v[188:191], v135 offset:64000
	ds_read_b128 v[192:195], v134 offset:46080
	ds_read_b128 v[196:199], v134 offset:48640
	ds_read_b128 v[200:203], v160 offset:5120
	ds_read_b128 v[204:207], v160 offset:7680
	s_setprio 1
	s_waitcnt lgkmcnt(5)
	v_mfma_f32_16x16x32_bf16 v[64:67], v[184:187], v[176:179], v[64:67]
	v_mfma_f32_16x16x32_bf16 v[68:71], v[184:187], v[180:183], v[68:71]
	s_waitcnt lgkmcnt(3)
	v_mfma_f32_16x16x32_bf16 v[72:75], v[184:187], v[192:195], v[72:75]
	s_waitcnt lgkmcnt(2)
	v_mfma_f32_16x16x32_bf16 v[76:79], v[184:187], v[196:199], v[76:79]
	v_mfma_f32_16x16x32_bf16 v[80:83], v[188:191], v[176:179], v[80:83]
	v_mfma_f32_16x16x32_bf16 v[84:87], v[188:191], v[180:183], v[84:87]
	v_mfma_f32_16x16x32_bf16 v[88:91], v[188:191], v[192:195], v[88:91]
	s_waitcnt lgkmcnt(1)
	v_mfma_f32_16x16x32_bf16 v[96:99], v[200:203], v[176:179], v[96:99]
	v_mfma_f32_16x16x32_bf16 v[100:103], v[200:203], v[180:183], v[100:103]
	s_waitcnt lgkmcnt(0)
	v_mfma_f32_16x16x32_bf16 v[112:115], v[204:207], v[176:179], v[112:115]
	v_mfma_f32_16x16x32_bf16 v[184:187], v[188:191], v[196:199], v[92:95]
	v_mfma_f32_16x16x32_bf16 v[188:191], v[200:203], v[192:195], v[104:107]
	v_mfma_f32_16x16x32_bf16 v[200:203], v[200:203], v[196:199], v[108:111]
	v_mfma_f32_16x16x32_bf16 v[176:179], v[204:207], v[180:183], v[116:119]
	v_mfma_f32_16x16x32_bf16 v[180:183], v[204:207], v[192:195], v[120:123]
	v_mfma_f32_16x16x32_bf16 v[192:195], v[204:207], v[196:199], v[124:127]
	s_setprio 0
	ds_read_b128 v[196:199], v134 offset:41024
	ds_read_b128 v[204:207], v134 offset:43584
	ds_read_b128 v[104:107], v135 offset:61504
	ds_read_b128 v[116:119], v135 offset:64064
	ds_read_b128 v[208:211], v134 offset:46144
	ds_read_b128 v[212:215], v134 offset:48704
	ds_read_b128 v[216:219], v161 offset:5120
	ds_read_b128 v[220:223], v161 offset:7680
	s_setprio 1
	s_waitcnt lgkmcnt(5)
	v_mfma_f32_16x16x32_bf16 v[124:127], v[104:107], v[196:199], v[64:67]
	v_mfma_f32_16x16x32_bf16 v[108:111], v[104:107], v[204:207], v[68:71]
	s_waitcnt lgkmcnt(3)
	v_mfma_f32_16x16x32_bf16 v[92:95], v[104:107], v[208:211], v[72:75]
	s_waitcnt lgkmcnt(2)
	v_mfma_f32_16x16x32_bf16 v[76:79], v[104:107], v[212:215], v[76:79]
	v_mfma_f32_16x16x32_bf16 v[120:123], v[116:119], v[196:199], v[80:83]
	v_mfma_f32_16x16x32_bf16 v[104:107], v[116:119], v[204:207], v[84:87]
	v_mfma_f32_16x16x32_bf16 v[88:91], v[116:119], v[208:211], v[88:91]
	v_mfma_f32_16x16x32_bf16 v[72:75], v[116:119], v[212:215], v[184:187]
	s_waitcnt lgkmcnt(1)
	v_mfma_f32_16x16x32_bf16 v[116:119], v[216:219], v[196:199], v[96:99]
	v_mfma_f32_16x16x32_bf16 v[100:103], v[216:219], v[204:207], v[100:103]
	v_mfma_f32_16x16x32_bf16 v[84:87], v[216:219], v[208:211], v[188:191]
	v_mfma_f32_16x16x32_bf16 v[68:71], v[216:219], v[212:215], v[200:203]
	s_waitcnt lgkmcnt(0)
	v_mfma_f32_16x16x32_bf16 v[112:115], v[220:223], v[196:199], v[112:115]
	v_mfma_f32_16x16x32_bf16 v[96:99], v[220:223], v[204:207], v[176:179]
	v_mfma_f32_16x16x32_bf16 v[80:83], v[220:223], v[208:211], v[180:183]
	v_mfma_f32_16x16x32_bf16 v[64:67], v[220:223], v[212:215], v[192:195]
	s_setprio 0
	s_add_i32 s2, s2, 2
	s_addk_i32 s14, 0x80
	s_and_b64 vcc, exec, s[0:1]
	s_cbranch_vccnz .LBB0_863
.LBB0_845:
	s_cmp_gt_u32 s2, 4
	s_mov_b64 s[0:1], -1
	s_barrier
	s_waitcnt vmcnt(15)
	ds_write_b128 v155, v[0:3] offset:40960
	s_waitcnt vmcnt(14)
	ds_write_b128 v155, v[8:11] offset:61440
	s_waitcnt vmcnt(13)
	ds_write_b128 v156, v[16:19] offset:40960
	s_waitcnt vmcnt(12)
	ds_write_b128 v156, v[24:27] offset:61440
	s_waitcnt vmcnt(11)
	ds_write_b128 v157, v[28:31] offset:40960
	s_waitcnt vmcnt(10)
	ds_write_b128 v157, v[36:39] offset:61440
	s_waitcnt vmcnt(9)
	ds_write_b128 v158, v[44:47] offset:40960
	s_waitcnt vmcnt(8)
	ds_write_b128 v158, v[56:59] offset:61440
	s_cbranch_scc0 .LBB0_851
	s_and_b64 vcc, exec, s[8:9]
	s_cbranch_vccz .LBB0_848
	v_mov_b32_e32 v132, v163
	s_mov_b64 s[0:1], 0
	v_lshl_add_u64 v[0:1], v[132:133], 1, s[88:89]
	v_mov_b32_e32 v132, v164
	global_load_dwordx4 v[0:3], v[0:1], off
	s_nop 0
	v_lshl_add_u64 v[8:9], v[132:133], 1, s[18:19]
	v_mov_b32_e32 v132, v165
	global_load_dwordx4 v[8:11], v[8:9], off
	s_nop 0
	v_lshl_add_u64 v[16:17], v[132:133], 1, s[88:89]
	v_mov_b32_e32 v132, v167
	global_load_dwordx4 v[16:19], v[16:17], off
	s_nop 0
	v_lshl_add_u64 v[24:25], v[132:133], 1, s[18:19]
	v_mov_b32_e32 v132, v168
	global_load_dwordx4 v[24:27], v[24:25], off
	s_nop 0
	v_lshl_add_u64 v[28:29], v[132:133], 1, s[88:89]
	v_mov_b32_e32 v132, v169
	global_load_dwordx4 v[28:31], v[28:29], off
	s_nop 0
	v_lshl_add_u64 v[36:37], v[132:133], 1, s[18:19]
	v_mov_b32_e32 v132, v170
	global_load_dwordx4 v[36:39], v[36:37], off
	s_nop 0
	v_lshl_add_u64 v[44:45], v[132:133], 1, s[88:89]
	global_load_dwordx4 v[44:47], v[44:45], off
	v_mov_b32_e32 v132, v171
.LBB0_848:
	s_andn2_b64 vcc, exec, s[0:1]
	s_cbranch_vccnz .LBB0_850
	s_add_i32 s0, s14, 0xffffff40
	s_waitcnt vmcnt(8)
	v_add_u32_e32 v44, s14, v175
	s_and_b32 s0, s0, 0xc0
	v_add_u32_e32 v132, 0xffffff40, v44
	v_or_b32_e32 v56, s0, v136
	v_lshl_add_u64 v[0:1], v[132:133], 1, s[88:89]
	v_add_u32_e32 v132, v56, v153
	global_load_dwordx4 v[0:3], v[0:1], off
	s_nop 0
	v_lshl_add_u64 v[8:9], v[132:133], 1, s[18:19]
	v_add_u32_e32 v132, 0x3f40, v44
	global_load_dwordx4 v[8:11], v[8:9], off
	s_nop 0
	v_lshl_add_u64 v[16:17], v[132:133], 1, s[88:89]
	v_add_u32_e32 v132, v56, v172
	global_load_dwordx4 v[16:19], v[16:17], off
	s_nop 0
	v_lshl_add_u64 v[24:25], v[132:133], 1, s[18:19]
	v_add_u32_e32 v132, 0x7f40, v44
	global_load_dwordx4 v[24:27], v[24:25], off
	s_nop 0
	v_lshl_add_u64 v[28:29], v[132:133], 1, s[88:89]
	v_add_u32_e32 v132, v56, v173
	global_load_dwordx4 v[28:31], v[28:29], off
	s_nop 0
	v_lshl_add_u64 v[36:37], v[132:133], 1, s[18:19]
	v_add_u32_e32 v132, 0xbf40, v44
	global_load_dwordx4 v[36:39], v[36:37], off
	s_nop 0
	v_lshl_add_u64 v[44:45], v[132:133], 1, s[88:89]
	global_load_dwordx4 v[44:47], v[44:45], off
	v_add_u32_e32 v132, v56, v174

.LBB0_851:
	s_andn2_b64 vcc, exec, s[0:1]
	v_add_u32_e32 v176, s14, v162
	s_cbranch_vccnz .LBB0_853
	s_add_i32 s0, s14, 0x140
	s_and_b32 s0, s0, 0xc0
	v_add_u32_e32 v132, 0x140, v176
	s_nop 0
	v_or_b32_e32 v8, s0, v136
	v_add_u32_e32 v56, v8, v143
	v_lshl_add_u64 v[0:1], v[132:133], 1, s[88:89]
	v_add_u32_e32 v132, v56, v144
	global_load_dwordx4 v[0:3], v[0:1], off
	s_nop 0
	v_lshl_add_u64 v[8:9], v[132:133], 1, s[18:19]
	v_add_u32_e32 v132, 0x4140, v176
	global_load_dwordx4 v[8:11], v[8:9], off
	s_nop 0
	v_lshl_add_u64 v[16:17], v[132:133], 1, s[88:89]
	v_add_u32_e32 v132, v56, v137
	global_load_dwordx4 v[16:19], v[16:17], off
	s_nop 0
	v_lshl_add_u64 v[24:25], v[132:133], 1, s[18:19]
	v_add_u32_e32 v132, 0x8140, v176
	global_load_dwordx4 v[24:27], v[24:25], off
	s_nop 0
	v_lshl_add_u64 v[28:29], v[132:133], 1, s[88:89]
	v_add_u32_e32 v132, v56, v148
	global_load_dwordx4 v[28:31], v[28:29], off
	s_nop 0
	v_lshl_add_u64 v[36:37], v[132:133], 1, s[18:19]
	v_add_u32_e32 v132, 0xc140, v176
	global_load_dwordx4 v[36:39], v[36:37], off
	s_nop 0
	v_lshl_add_u64 v[44:45], v[132:133], 1, s[88:89]
	global_load_dwordx4 v[44:47], v[44:45], off
	v_add_u32_e32 v132, v56, v149
.LBB0_853:
	s_nop 0
	v_lshl_add_u64 v[56:57], v[132:133], 1, s[18:19]
	global_load_dwordx4 v[56:59], v[56:57], off
	ds_read_b128 v[178:181], v134
	ds_read_b128 v[182:185], v134 offset:2560
	ds_read_b128 v[186:189], v135 offset:20480
	ds_read_b128 v[190:193], v135 offset:23040
	ds_read_b128 v[194:197], v134 offset:5120
	ds_read_b128 v[198:201], v134 offset:7680
	ds_read_b128 v[202:205], v135 offset:25600
	ds_read_b128 v[206:209], v135 offset:28160
	s_setprio 1
	s_waitcnt lgkmcnt(5)
	v_mfma_f32_16x16x32_bf16 v[124:127], v[186:189], v[178:181], v[124:127]
	v_mfma_f32_16x16x32_bf16 v[108:111], v[186:189], v[182:185], v[108:111]
	s_waitcnt lgkmcnt(3)
	v_mfma_f32_16x16x32_bf16 v[92:95], v[186:189], v[194:197], v[92:95]
	s_waitcnt lgkmcnt(2)
	v_mfma_f32_16x16x32_bf16 v[76:79], v[186:189], v[198:201], v[76:79]
	v_mfma_f32_16x16x32_bf16 v[120:123], v[190:193], v[178:181], v[120:123]
	v_mfma_f32_16x16x32_bf16 v[104:107], v[190:193], v[182:185], v[104:107]
	v_mfma_f32_16x16x32_bf16 v[88:91], v[190:193], v[194:197], v[88:91]
	s_waitcnt lgkmcnt(1)
	v_mfma_f32_16x16x32_bf16 v[116:119], v[202:205], v[178:181], v[116:119]
	v_mfma_f32_16x16x32_bf16 v[100:103], v[202:205], v[182:185], v[100:103]
	s_waitcnt lgkmcnt(0)
	v_mfma_f32_16x16x32_bf16 v[112:115], v[206:209], v[178:181], v[112:115]
	v_mfma_f32_16x16x32_bf16 v[186:189], v[190:193], v[198:201], v[72:75]
	v_mfma_f32_16x16x32_bf16 v[190:193], v[202:205], v[194:197], v[84:87]
	v_mfma_f32_16x16x32_bf16 v[202:205], v[202:205], v[198:201], v[68:71]
	v_mfma_f32_16x16x32_bf16 v[178:181], v[206:209], v[182:185], v[96:99]
	v_mfma_f32_16x16x32_bf16 v[182:185], v[206:209], v[194:197], v[80:83]
	v_mfma_f32_16x16x32_bf16 v[194:197], v[206:209], v[198:201], v[64:67]
	s_setprio 0
	ds_read_b128 v[198:201], v134 offset:64
	ds_read_b128 v[206:209], v134 offset:2624
	ds_read_b128 v[80:83], v135 offset:20544
	ds_read_b128 v[96:99], v135 offset:23104
	ds_read_b128 v[210:213], v134 offset:5184
	ds_read_b128 v[214:217], v134 offset:7744
	ds_read_b128 v[218:221], v135 offset:25664
	ds_read_b128 v[222:225], v135 offset:28224
	s_setprio 1
	s_waitcnt lgkmcnt(5)
	v_mfma_f32_16x16x32_bf16 v[64:67], v[80:83], v[198:201], v[124:127]
	v_mfma_f32_16x16x32_bf16 v[68:71], v[80:83], v[206:209], v[108:111]
	s_waitcnt lgkmcnt(3)
	v_mfma_f32_16x16x32_bf16 v[72:75], v[80:83], v[210:213], v[92:95]
	s_waitcnt lgkmcnt(2)
	v_mfma_f32_16x16x32_bf16 v[76:79], v[80:83], v[214:217], v[76:79]
	v_mfma_f32_16x16x32_bf16 v[80:83], v[96:99], v[198:201], v[120:123]
	v_mfma_f32_16x16x32_bf16 v[84:87], v[96:99], v[206:209], v[104:107]
	v_mfma_f32_16x16x32_bf16 v[88:91], v[96:99], v[210:213], v[88:91]
	v_mfma_f32_16x16x32_bf16 v[92:95], v[96:99], v[214:217], v[186:189]
	s_waitcnt lgkmcnt(1)
	v_mfma_f32_16x16x32_bf16 v[96:99], v[218:221], v[198:201], v[116:119]
	v_mfma_f32_16x16x32_bf16 v[100:103], v[218:221], v[206:209], v[100:103]
	v_mfma_f32_16x16x32_bf16 v[104:107], v[218:221], v[210:213], v[190:193]
	v_mfma_f32_16x16x32_bf16 v[108:111], v[218:221], v[214:217], v[202:205]
	s_waitcnt lgkmcnt(0)
	v_mfma_f32_16x16x32_bf16 v[112:115], v[222:225], v[198:201], v[112:115]
	v_mfma_f32_16x16x32_bf16 v[116:119], v[222:225], v[206:209], v[178:181]
	v_mfma_f32_16x16x32_bf16 v[120:123], v[222:225], v[210:213], v[182:185]
	v_mfma_f32_16x16x32_bf16 v[124:127], v[222:225], v[214:217], v[194:197]
	s_setprio 0
	s_cmp_gt_u32 s2, 5
	s_cselect_b64 s[0:1], -1, 0
	s_cmp_lt_u32 s2, 6
	s_cselect_b64 s[4:5], -1, 0
	s_or_b64 s[4:5], s[10:11], s[4:5]
	s_andn2_b64 vcc, exec, s[4:5]
	s_barrier
	s_cbranch_vccnz .LBB0_855
	s_waitcnt vmcnt(15)
	ds_write_b128 v155, v[4:7]
	s_waitcnt vmcnt(14)
	ds_write_b128 v155, v[12:15] offset:20480
	s_waitcnt vmcnt(13)
	ds_write_b128 v156, v[20:23]
	s_waitcnt vmcnt(12)
	ds_write_b128 v156, v[32:35] offset:20480
	s_waitcnt vmcnt(11)
	ds_write_b128 v157, v[40:43]
	s_waitcnt vmcnt(10)
	ds_write_b128 v157, v[48:51] offset:20480
	s_waitcnt vmcnt(9)
	ds_write_b128 v158, v[52:55]
	s_waitcnt vmcnt(8)
	ds_write_b128 v158, v[60:63] offset:20480
.LBB0_855:
	s_cmp_gt_u32 s2, 3
	s_mov_b64 s[4:5], -1
	s_cbranch_scc0 .LBB0_861
	s_and_b64 vcc, exec, s[8:9]
	s_cbranch_vccz .LBB0_858
	v_mov_b32_e32 v132, v163
	s_mov_b64 s[4:5], 0
	s_waitcnt vmcnt(8)
	v_lshl_add_u64 v[4:5], v[132:133], 1, s[88:89]
	v_mov_b32_e32 v132, v164
	global_load_dwordx4 v[4:7], v[4:5], off
	s_nop 0
	v_lshl_add_u64 v[12:13], v[132:133], 1, s[18:19]
	v_mov_b32_e32 v132, v165
	global_load_dwordx4 v[12:15], v[12:13], off
	s_nop 0
	v_lshl_add_u64 v[20:21], v[132:133], 1, s[88:89]
	v_mov_b32_e32 v132, v167
	global_load_dwordx4 v[20:23], v[20:21], off
	s_nop 0
	v_lshl_add_u64 v[32:33], v[132:133], 1, s[18:19]
	v_mov_b32_e32 v132, v168
	global_load_dwordx4 v[32:35], v[32:33], off
	s_nop 0
	v_lshl_add_u64 v[40:41], v[132:133], 1, s[88:89]
	v_mov_b32_e32 v132, v169
	global_load_dwordx4 v[40:43], v[40:41], off
	s_nop 0
	v_lshl_add_u64 v[48:49], v[132:133], 1, s[18:19]
	v_mov_b32_e32 v132, v170
	global_load_dwordx4 v[48:51], v[48:49], off
	s_nop 0
	v_lshl_add_u64 v[52:53], v[132:133], 1, s[88:89]
	global_load_dwordx4 v[52:55], v[52:53], off
	v_mov_b32_e32 v132, v171
.LBB0_858:
	s_andn2_b64 vcc, exec, s[4:5]
	s_cbranch_vccnz .LBB0_860
	s_add_i32 s4, s14, 0x80
	s_waitcnt vmcnt(8)
	v_add_u32_e32 v52, s14, v175
	s_and_b32 s4, s4, 0x80
	v_add_u32_e32 v132, 0xffffff80, v52
	v_or_b32_e32 v60, s4, v136
	v_lshl_add_u64 v[4:5], v[132:133], 1, s[88:89]
	v_add_u32_e32 v132, v60, v153
	global_load_dwordx4 v[4:7], v[4:5], off
	s_nop 0
	v_lshl_add_u64 v[12:13], v[132:133], 1, s[18:19]
	v_add_u32_e32 v132, 0x3f80, v52
	global_load_dwordx4 v[12:15], v[12:13], off
	s_nop 0
	v_lshl_add_u64 v[20:21], v[132:133], 1, s[88:89]
	v_add_u32_e32 v132, v60, v172
	global_load_dwordx4 v[20:23], v[20:21], off
	s_nop 0
	v_lshl_add_u64 v[32:33], v[132:133], 1, s[18:19]
	v_add_u32_e32 v132, 0x7f80, v52
	global_load_dwordx4 v[32:35], v[32:33], off
	s_nop 0
	v_lshl_add_u64 v[40:41], v[132:133], 1, s[88:89]
	v_add_u32_e32 v132, v60, v173
	global_load_dwordx4 v[40:43], v[40:41], off
	s_nop 0
	v_lshl_add_u64 v[48:49], v[132:133], 1, s[18:19]
	v_add_u32_e32 v132, 0xbf80, v52
	global_load_dwordx4 v[48:51], v[48:49], off
	s_nop 0
	v_lshl_add_u64 v[52:53], v[132:133], 1, s[88:89]
	global_load_dwordx4 v[52:55], v[52:53], off
	v_add_u32_e32 v132, v60, v174

.LBB0_862:
	v_add_u32_e32 v132, 0x180, v176
	s_waitcnt vmcnt(8)
	v_add_u32_e32 v60, s14, v166
	v_lshl_add_u64 v[4:5], v[132:133], 1, s[88:89]
	v_add_u32_e32 v132, 0x80, v60
	global_load_dwordx4 v[4:7], v[4:5], off
	s_nop 0
	v_lshl_add_u64 v[12:13], v[132:133], 1, s[18:19]
	v_add_u32_e32 v132, 0x4180, v176
	global_load_dwordx4 v[12:15], v[12:13], off
	s_nop 0
	v_lshl_add_u64 v[20:21], v[132:133], 1, s[88:89]
	v_add_u32_e32 v132, 0x2080, v60
	global_load_dwordx4 v[20:23], v[20:21], off
	s_nop 0
	v_lshl_add_u64 v[32:33], v[132:133], 1, s[18:19]
	v_add_u32_e32 v132, 0x8180, v176
	global_load_dwordx4 v[32:35], v[32:33], off
	s_nop 0
	v_lshl_add_u64 v[40:41], v[132:133], 1, s[88:89]
	v_add_u32_e32 v132, 0x4080, v60
	global_load_dwordx4 v[40:43], v[40:41], off
	s_nop 0
	v_lshl_add_u64 v[48:49], v[132:133], 1, s[18:19]
	v_add_u32_e32 v132, 0xc180, v176
	global_load_dwordx4 v[48:51], v[48:49], off
	s_nop 0
	v_lshl_add_u64 v[52:53], v[132:133], 1, s[88:89]
	global_load_dwordx4 v[52:55], v[52:53], off
	v_add_u32_e32 v132, 0x6080, v60
	s_branch .LBB0_844

.LBB0_988:
	s_waitcnt vmcnt(15)
	v_lshl_add_u64 v[60:61], v[130:131], 1, s[86:87]
	global_load_dwordx4 v[60:63], v[60:61], off
	ds_read_b128 v[170:173], v132 offset:40960
	ds_read_b128 v[174:177], v132 offset:43520
	ds_read_b128 v[178:181], v133 offset:61440
	ds_read_b128 v[182:185], v133 offset:64000
	ds_read_b128 v[186:189], v132 offset:46080
	ds_read_b128 v[190:193], v132 offset:48640
	ds_read_b128 v[194:197], v150 offset:5120
	ds_read_b128 v[198:201], v150 offset:7680
	s_setprio 1
	s_waitcnt lgkmcnt(5)
	v_mfma_f32_16x16x32_bf16 v[64:67], v[178:181], v[170:173], v[64:67]
	v_mfma_f32_16x16x32_bf16 v[68:71], v[178:181], v[174:177], v[68:71]
	s_waitcnt lgkmcnt(3)
	v_mfma_f32_16x16x32_bf16 v[72:75], v[178:181], v[186:189], v[72:75]
	s_waitcnt lgkmcnt(2)
	v_mfma_f32_16x16x32_bf16 v[76:79], v[178:181], v[190:193], v[76:79]
	v_mfma_f32_16x16x32_bf16 v[80:83], v[182:185], v[170:173], v[80:83]
	v_mfma_f32_16x16x32_bf16 v[84:87], v[182:185], v[174:177], v[84:87]
	v_mfma_f32_16x16x32_bf16 v[88:91], v[182:185], v[186:189], v[88:91]
	v_mfma_f32_16x16x32_bf16 v[92:95], v[182:185], v[190:193], v[92:95]
	s_waitcnt lgkmcnt(1)
	v_mfma_f32_16x16x32_bf16 v[178:181], v[194:197], v[170:173], v[96:99]
	v_mfma_f32_16x16x32_bf16 v[182:185], v[194:197], v[174:177], v[100:103]
	v_mfma_f32_16x16x32_bf16 v[202:205], v[194:197], v[186:189], v[104:107]
	v_mfma_f32_16x16x32_bf16 v[194:197], v[194:197], v[190:193], v[108:111]
	s_waitcnt lgkmcnt(0)
	v_mfma_f32_16x16x32_bf16 v[170:173], v[198:201], v[170:173], v[112:115]
	v_mfma_f32_16x16x32_bf16 v[174:177], v[198:201], v[174:177], v[116:119]
	v_mfma_f32_16x16x32_bf16 v[186:189], v[198:201], v[186:189], v[120:123]
	v_mfma_f32_16x16x32_bf16 v[190:193], v[198:201], v[190:193], v[124:127]
	s_setprio 0
	ds_read_b128 v[198:201], v132 offset:41024
	ds_read_b128 v[206:209], v132 offset:43584
	ds_read_b128 v[96:99], v133 offset:61504
	ds_read_b128 v[210:213], v133 offset:64064
	ds_read_b128 v[214:217], v132 offset:46144
	ds_read_b128 v[218:221], v132 offset:48704
	ds_read_b128 v[222:225], v151 offset:5120
	ds_read_b128 v[226:229], v151 offset:7680
	s_setprio 1
	s_waitcnt lgkmcnt(5)
	v_mfma_f32_16x16x32_bf16 v[124:127], v[96:99], v[198:201], v[64:67]
	v_mfma_f32_16x16x32_bf16 v[120:123], v[96:99], v[206:209], v[68:71]
	s_waitcnt lgkmcnt(3)
	v_mfma_f32_16x16x32_bf16 v[116:119], v[96:99], v[214:217], v[72:75]
	s_waitcnt lgkmcnt(2)
	v_mfma_f32_16x16x32_bf16 v[112:115], v[96:99], v[218:221], v[76:79]
	v_mfma_f32_16x16x32_bf16 v[108:111], v[210:213], v[198:201], v[80:83]
	v_mfma_f32_16x16x32_bf16 v[104:107], v[210:213], v[206:209], v[84:87]
	v_mfma_f32_16x16x32_bf16 v[100:103], v[210:213], v[214:217], v[88:91]
	v_mfma_f32_16x16x32_bf16 v[96:99], v[210:213], v[218:221], v[92:95]
	s_waitcnt lgkmcnt(1)
	v_mfma_f32_16x16x32_bf16 v[92:95], v[222:225], v[198:201], v[178:181]
	v_mfma_f32_16x16x32_bf16 v[88:91], v[222:225], v[206:209], v[182:185]
	v_mfma_f32_16x16x32_bf16 v[84:87], v[222:225], v[214:217], v[202:205]
	v_mfma_f32_16x16x32_bf16 v[80:83], v[222:225], v[218:221], v[194:197]
	s_waitcnt lgkmcnt(0)
	v_mfma_f32_16x16x32_bf16 v[76:79], v[226:229], v[198:201], v[170:173]
	v_mfma_f32_16x16x32_bf16 v[72:75], v[226:229], v[206:209], v[174:177]
	v_mfma_f32_16x16x32_bf16 v[68:71], v[226:229], v[214:217], v[186:189]
	v_mfma_f32_16x16x32_bf16 v[64:67], v[226:229], v[218:221], v[190:193]
	s_setprio 0
	s_add_i32 s23, s23, 2
	s_addk_i32 s22, 0x80
	s_addk_i32 s21, 0x80
	v_add_u32_e32 v161, 0x80, v161
	v_add_u32_e32 v162, 0x80, v162
	v_add_u32_e32 v163, 0x80, v163
	v_add_u32_e32 v164, 0x80, v164
	s_addk_i32 s20, 0x80
	v_add_u32_e32 v165, 0x80, v165
	v_add_u32_e32 v166, 0x80, v166
	v_add_u32_e32 v167, 0x80, v167
	v_add_u32_e32 v168, 0x80, v168
	s_and_b64 vcc, exec, s[8:9]
	s_cbranch_vccnz .LBB0_1007
.LBB0_989:
	s_cmp_gt_u32 s23, 12
	s_mov_b64 s[8:9], -1
	s_waitcnt lgkmcnt(0)
	s_barrier
	s_waitcnt vmcnt(15)
	ds_write_b128 v146, v[0:3] offset:40960
	s_waitcnt vmcnt(14)
	ds_write_b128 v146, v[8:11] offset:61440
	s_waitcnt vmcnt(13)
	ds_write_b128 v147, v[16:19] offset:40960
	s_waitcnt vmcnt(12)
	ds_write_b128 v147, v[24:27] offset:61440
	s_waitcnt vmcnt(11)
	ds_write_b128 v148, v[28:31] offset:40960
	s_waitcnt vmcnt(10)
	ds_write_b128 v148, v[36:39] offset:61440
	s_waitcnt vmcnt(9)
	ds_write_b128 v149, v[44:47] offset:40960
	s_waitcnt vmcnt(8)
	ds_write_b128 v149, v[56:59] offset:61440
	s_cbranch_scc0 .LBB0_995
	s_and_b64 vcc, exec, s[2:3]
	s_cbranch_vccz .LBB0_992
	v_mov_b32_e32 v130, v152
	s_mov_b64 s[8:9], 0
	v_lshl_add_u64 v[0:1], v[130:131], 1, s[4:5]
	v_mov_b32_e32 v130, v153
	global_load_dwordx4 v[0:3], v[0:1], off
	s_nop 0
	v_lshl_add_u64 v[8:9], v[130:131], 1, s[86:87]
	v_mov_b32_e32 v130, v154
	global_load_dwordx4 v[8:11], v[8:9], off
	s_nop 0
	v_lshl_add_u64 v[16:17], v[130:131], 1, s[4:5]
	v_mov_b32_e32 v130, v155
	global_load_dwordx4 v[16:19], v[16:17], off
	s_nop 0
	v_lshl_add_u64 v[24:25], v[130:131], 1, s[86:87]
	v_mov_b32_e32 v130, v156
	global_load_dwordx4 v[24:27], v[24:25], off
	s_nop 0
	v_lshl_add_u64 v[28:29], v[130:131], 1, s[4:5]
	v_mov_b32_e32 v130, v157
	global_load_dwordx4 v[28:31], v[28:29], off
	s_nop 0
	v_lshl_add_u64 v[36:37], v[130:131], 1, s[86:87]
	v_mov_b32_e32 v130, v158
	global_load_dwordx4 v[36:39], v[36:37], off
	s_nop 0
	v_lshl_add_u64 v[44:45], v[130:131], 1, s[4:5]
	global_load_dwordx4 v[44:47], v[44:45], off
	v_mov_b32_e32 v130, v159
.LBB0_992:
	s_andn2_b64 vcc, exec, s[8:9]
	s_cbranch_vccnz .LBB0_994
	s_waitcnt vmcnt(8)
	v_add_u32_e32 v44, s21, v160
	v_add_u32_e32 v130, 0xfffffcc0, v44
	v_add_u32_e32 v56, s22, v160
	v_lshl_add_u64 v[0:1], v[130:131], 1, s[4:5]
	v_add_u32_e32 v130, 0xfffffcc0, v56
	global_load_dwordx4 v[0:3], v[0:1], off
	s_nop 0
	v_lshl_add_u64 v[8:9], v[130:131], 1, s[86:87]
	v_add_u32_e32 v130, 0x7cc0, v44
	global_load_dwordx4 v[8:11], v[8:9], off
	s_nop 0
	v_lshl_add_u64 v[16:17], v[130:131], 1, s[4:5]
	v_add_u32_e32 v130, 0x7cc0, v56
	global_load_dwordx4 v[16:19], v[16:17], off
	s_nop 0
	v_lshl_add_u64 v[24:25], v[130:131], 1, s[86:87]
	v_add_u32_e32 v130, 0xfcc0, v44
	global_load_dwordx4 v[24:27], v[24:25], off
	s_nop 0
	v_lshl_add_u64 v[28:29], v[130:131], 1, s[4:5]
	v_add_u32_e32 v130, 0xfcc0, v56
	global_load_dwordx4 v[28:31], v[28:29], off
	s_nop 0
	v_lshl_add_u64 v[36:37], v[130:131], 1, s[86:87]
	v_add_u32_e32 v130, 0x17cc0, v44
	global_load_dwordx4 v[36:39], v[36:37], off
	s_nop 0
	v_lshl_add_u64 v[44:45], v[130:131], 1, s[4:5]
	global_load_dwordx4 v[44:47], v[44:45], off
	v_add_u32_e32 v130, 0x17cc0, v56

.LBB0_995:
	s_andn2_b64 vcc, exec, s[8:9]
	v_add_u32_e32 v169, s20, v160
	s_cbranch_vccnz .LBB0_997
	v_add_u32_e32 v130, 0xc0, v169
	s_nop 0
	v_lshl_add_u64 v[0:1], v[130:131], 1, s[4:5]
	v_add_u32_e32 v130, v143, v168
	global_load_dwordx4 v[0:3], v[0:1], off
	s_nop 0
	v_lshl_add_u64 v[8:9], v[130:131], 1, s[86:87]
	v_add_u32_e32 v130, 0x80c0, v169
	global_load_dwordx4 v[8:11], v[8:9], off
	s_nop 0
	v_lshl_add_u64 v[16:17], v[130:131], 1, s[4:5]
	v_add_u32_e32 v130, v143, v167
	global_load_dwordx4 v[16:19], v[16:17], off
	s_nop 0
	v_lshl_add_u64 v[24:25], v[130:131], 1, s[86:87]
	v_add_u32_e32 v130, 0x100c0, v169
	global_load_dwordx4 v[24:27], v[24:25], off
	s_nop 0
	v_lshl_add_u64 v[28:29], v[130:131], 1, s[4:5]
	v_add_u32_e32 v130, v143, v166
	global_load_dwordx4 v[28:31], v[28:29], off
	s_nop 0
	v_lshl_add_u64 v[36:37], v[130:131], 1, s[86:87]
	v_add_u32_e32 v130, 0x180c0, v169
	global_load_dwordx4 v[36:39], v[36:37], off
	s_nop 0
	v_lshl_add_u64 v[44:45], v[130:131], 1, s[4:5]
	global_load_dwordx4 v[44:47], v[44:45], off
	v_add_u32_e32 v130, v143, v165
.LBB0_997:
	s_nop 0
	v_lshl_add_u64 v[56:57], v[130:131], 1, s[86:87]
	global_load_dwordx4 v[56:59], v[56:57], off
	ds_read_b128 v[170:173], v132
	ds_read_b128 v[174:177], v132 offset:2560
	ds_read_b128 v[178:181], v133 offset:20480
	ds_read_b128 v[182:185], v133 offset:23040
	ds_read_b128 v[186:189], v132 offset:5120
	ds_read_b128 v[190:193], v132 offset:7680
	ds_read_b128 v[194:197], v133 offset:25600
	ds_read_b128 v[198:201], v133 offset:28160
	s_setprio 1
	s_waitcnt lgkmcnt(5)
	v_mfma_f32_16x16x32_bf16 v[124:127], v[178:181], v[170:173], v[124:127]
	v_mfma_f32_16x16x32_bf16 v[120:123], v[178:181], v[174:177], v[120:123]
	s_waitcnt lgkmcnt(3)
	v_mfma_f32_16x16x32_bf16 v[116:119], v[178:181], v[186:189], v[116:119]
	s_waitcnt lgkmcnt(2)
	v_mfma_f32_16x16x32_bf16 v[112:115], v[178:181], v[190:193], v[112:115]
	v_mfma_f32_16x16x32_bf16 v[108:111], v[182:185], v[170:173], v[108:111]
	v_mfma_f32_16x16x32_bf16 v[104:107], v[182:185], v[174:177], v[104:107]
	v_mfma_f32_16x16x32_bf16 v[100:103], v[182:185], v[186:189], v[100:103]
	v_mfma_f32_16x16x32_bf16 v[96:99], v[182:185], v[190:193], v[96:99]
	s_waitcnt lgkmcnt(1)
	v_mfma_f32_16x16x32_bf16 v[178:181], v[194:197], v[170:173], v[92:95]
	v_mfma_f32_16x16x32_bf16 v[182:185], v[194:197], v[174:177], v[88:91]
	v_mfma_f32_16x16x32_bf16 v[202:205], v[194:197], v[186:189], v[84:87]
	v_mfma_f32_16x16x32_bf16 v[194:197], v[194:197], v[190:193], v[80:83]
	s_waitcnt lgkmcnt(0)
	v_mfma_f32_16x16x32_bf16 v[170:173], v[198:201], v[170:173], v[76:79]
	v_mfma_f32_16x16x32_bf16 v[174:177], v[198:201], v[174:177], v[72:75]
	v_mfma_f32_16x16x32_bf16 v[186:189], v[198:201], v[186:189], v[68:71]
	v_mfma_f32_16x16x32_bf16 v[190:193], v[198:201], v[190:193], v[64:67]
	s_setprio 0
	ds_read_b128 v[198:201], v132 offset:64
	ds_read_b128 v[206:209], v132 offset:2624
	ds_read_b128 v[76:79], v133 offset:20544
	ds_read_b128 v[92:95], v133 offset:23104
	ds_read_b128 v[210:213], v132 offset:5184
	ds_read_b128 v[214:217], v132 offset:7744
	ds_read_b128 v[218:221], v133 offset:25664
	ds_read_b128 v[222:225], v133 offset:28224
	s_setprio 1
	s_waitcnt lgkmcnt(5)
	v_mfma_f32_16x16x32_bf16 v[64:67], v[76:79], v[198:201], v[124:127]
	v_mfma_f32_16x16x32_bf16 v[68:71], v[76:79], v[206:209], v[120:123]
	s_waitcnt lgkmcnt(3)
	v_mfma_f32_16x16x32_bf16 v[72:75], v[76:79], v[210:213], v[116:119]
	s_waitcnt lgkmcnt(2)
	v_mfma_f32_16x16x32_bf16 v[76:79], v[76:79], v[214:217], v[112:115]
	v_mfma_f32_16x16x32_bf16 v[80:83], v[92:95], v[198:201], v[108:111]
	v_mfma_f32_16x16x32_bf16 v[84:87], v[92:95], v[206:209], v[104:107]
	v_mfma_f32_16x16x32_bf16 v[88:91], v[92:95], v[210:213], v[100:103]
	v_mfma_f32_16x16x32_bf16 v[92:95], v[92:95], v[214:217], v[96:99]
	s_waitcnt lgkmcnt(1)
	v_mfma_f32_16x16x32_bf16 v[96:99], v[218:221], v[198:201], v[178:181]
	v_mfma_f32_16x16x32_bf16 v[100:103], v[218:221], v[206:209], v[182:185]
	v_mfma_f32_16x16x32_bf16 v[104:107], v[218:221], v[210:213], v[202:205]
	v_mfma_f32_16x16x32_bf16 v[108:111], v[218:221], v[214:217], v[194:197]
	s_waitcnt lgkmcnt(0)
	v_mfma_f32_16x16x32_bf16 v[112:115], v[222:225], v[198:201], v[170:173]
	v_mfma_f32_16x16x32_bf16 v[116:119], v[222:225], v[206:209], v[174:177]
	v_mfma_f32_16x16x32_bf16 v[120:123], v[222:225], v[210:213], v[186:189]
	v_mfma_f32_16x16x32_bf16 v[124:127], v[222:225], v[214:217], v[190:193]
	s_setprio 0
	s_cmp_gt_u32 s23, 13
	s_cselect_b64 s[8:9], -1, 0
	s_cmp_lt_u32 s23, 14
	s_cselect_b64 s[10:11], -1, 0
	s_or_b64 s[10:11], s[6:7], s[10:11]
	s_andn2_b64 vcc, exec, s[10:11]
	s_barrier
	s_cbranch_vccnz .LBB0_999
	s_waitcnt vmcnt(15)
	ds_write_b128 v146, v[4:7]
	s_waitcnt vmcnt(14)
	ds_write_b128 v146, v[12:15] offset:20480
	s_waitcnt vmcnt(13)
	ds_write_b128 v147, v[20:23]
	s_waitcnt vmcnt(12)
	ds_write_b128 v147, v[32:35] offset:20480
	s_waitcnt vmcnt(11)
	ds_write_b128 v148, v[40:43]
	s_waitcnt vmcnt(10)
	ds_write_b128 v148, v[48:51] offset:20480
	s_waitcnt vmcnt(9)
	ds_write_b128 v149, v[52:55]
	s_waitcnt vmcnt(8)
	ds_write_b128 v149, v[60:63] offset:20480
.LBB0_999:
	s_cmp_gt_u32 s23, 11
	s_mov_b64 s[10:11], -1
	s_cbranch_scc0 .LBB0_1005
	s_and_b64 vcc, exec, s[2:3]
	s_cbranch_vccz .LBB0_1002
	v_mov_b32_e32 v130, v152
	s_mov_b64 s[10:11], 0
	s_waitcnt vmcnt(8)
	v_lshl_add_u64 v[4:5], v[130:131], 1, s[4:5]
	v_mov_b32_e32 v130, v153
	global_load_dwordx4 v[4:7], v[4:5], off
	s_nop 0
	v_lshl_add_u64 v[12:13], v[130:131], 1, s[86:87]
	v_mov_b32_e32 v130, v154
	global_load_dwordx4 v[12:15], v[12:13], off
	s_nop 0
	v_lshl_add_u64 v[20:21], v[130:131], 1, s[4:5]
	v_mov_b32_e32 v130, v155
	global_load_dwordx4 v[20:23], v[20:21], off
	s_nop 0
	v_lshl_add_u64 v[32:33], v[130:131], 1, s[86:87]
	v_mov_b32_e32 v130, v156
	global_load_dwordx4 v[32:35], v[32:33], off
	s_nop 0
	v_lshl_add_u64 v[40:41], v[130:131], 1, s[4:5]
	v_mov_b32_e32 v130, v157
	global_load_dwordx4 v[40:43], v[40:41], off
	s_nop 0
	v_lshl_add_u64 v[48:49], v[130:131], 1, s[86:87]
	v_mov_b32_e32 v130, v158
	global_load_dwordx4 v[48:51], v[48:49], off
	s_nop 0
	v_lshl_add_u64 v[52:53], v[130:131], 1, s[4:5]
	global_load_dwordx4 v[52:55], v[52:53], off
	v_mov_b32_e32 v130, v159
.LBB0_1002:
	s_andn2_b64 vcc, exec, s[10:11]
	s_cbranch_vccnz .LBB0_1004
	s_waitcnt vmcnt(8)
	v_add_u32_e32 v52, s21, v160
	v_add_u32_e32 v130, 0xfffffd00, v52
	v_add_u32_e32 v60, s22, v160
	v_lshl_add_u64 v[4:5], v[130:131], 1, s[4:5]
	v_add_u32_e32 v130, 0xfffffd00, v60
	global_load_dwordx4 v[4:7], v[4:5], off
	s_nop 0
	v_lshl_add_u64 v[12:13], v[130:131], 1, s[86:87]
	v_add_u32_e32 v130, 0x7d00, v52
	global_load_dwordx4 v[12:15], v[12:13], off
	s_nop 0
	v_lshl_add_u64 v[20:21], v[130:131], 1, s[4:5]
	v_add_u32_e32 v130, 0x7d00, v60
	global_load_dwordx4 v[20:23], v[20:21], off
	s_nop 0
	v_lshl_add_u64 v[32:33], v[130:131], 1, s[86:87]
	v_add_u32_e32 v130, 0xfd00, v52
	global_load_dwordx4 v[32:35], v[32:33], off
	s_nop 0
	v_lshl_add_u64 v[40:41], v[130:131], 1, s[4:5]
	v_add_u32_e32 v130, 0xfd00, v60
	global_load_dwordx4 v[40:43], v[40:41], off
	s_nop 0
	v_lshl_add_u64 v[48:49], v[130:131], 1, s[86:87]
	v_add_u32_e32 v130, 0x17d00, v52
	global_load_dwordx4 v[48:51], v[48:49], off
	s_nop 0
	v_lshl_add_u64 v[52:53], v[130:131], 1, s[4:5]
	global_load_dwordx4 v[52:55], v[52:53], off
	v_add_u32_e32 v130, 0x17d00, v60

.LBB0_1006:
	v_add_u32_e32 v130, 0x100, v169
	s_waitcnt vmcnt(8)
	v_lshl_add_u64 v[4:5], v[130:131], 1, s[4:5]
	v_add_u32_e32 v130, v143, v164
	global_load_dwordx4 v[4:7], v[4:5], off
	s_nop 0
	v_lshl_add_u64 v[12:13], v[130:131], 1, s[86:87]
	v_add_u32_e32 v130, 0x8100, v169
	global_load_dwordx4 v[12:15], v[12:13], off
	s_nop 0
	v_lshl_add_u64 v[20:21], v[130:131], 1, s[4:5]
	v_add_u32_e32 v130, v143, v163
	global_load_dwordx4 v[20:23], v[20:21], off
	s_nop 0
	v_lshl_add_u64 v[32:33], v[130:131], 1, s[86:87]
	v_add_u32_e32 v130, 0x10100, v169
	global_load_dwordx4 v[32:35], v[32:33], off
	s_nop 0
	v_lshl_add_u64 v[40:41], v[130:131], 1, s[4:5]
	v_add_u32_e32 v130, v143, v162
	global_load_dwordx4 v[40:43], v[40:41], off
	s_nop 0
	v_lshl_add_u64 v[48:49], v[130:131], 1, s[86:87]
	v_add_u32_e32 v130, 0x18100, v169
	global_load_dwordx4 v[48:51], v[48:49], off
	s_nop 0
	v_lshl_add_u64 v[52:53], v[130:131], 1, s[4:5]
	global_load_dwordx4 v[52:55], v[52:53], off
	v_add_u32_e32 v130, v143, v161
	s_branch .LBB0_988

.LBB0_1592:
	s_waitcnt vmcnt(14)
	v_mov_b32_e32 v132, v9
	v_mov_b32_e32 v133, v10
	v_and_b32_e32 v9, 64, v137
	v_lshl_add_u32 v134, s13, 7, v148
	v_ashrrev_i32_e32 v135, 31, v134
	v_readlane_b32 s2, v237, 40
	v_lshlrev_b32_e32 v9, 1, v9
	v_cvt_pk_bf16_f32 v124, v124, v125
	v_cvt_pk_bf16_f32 v125, v126, v127
	v_lshlrev_b64 v[126:127], 11, v[134:135]
	v_readlane_b32 s3, v237, 41
	v_lshl_or_b32 v9, v141, 3, v9
	v_lshl_or_b32 v130, s12, 8, v9
	v_lshl_add_u64 v[126:127], s[2:3], 0, v[126:127]
	v_lshl_add_u64 v[126:127], v[126:127], 0, v[130:131]
	global_store_dwordx2 v[126:127], v[124:125], off
	v_add_u32_e32 v124, 16, v134
	v_ashrrev_i32_e32 v125, 31, v124
	v_cvt_pk_bf16_f32 v120, v120, v121
	v_cvt_pk_bf16_f32 v121, v122, v123
	v_lshlrev_b64 v[122:123], 11, v[124:125]
	v_lshl_add_u64 v[122:123], s[2:3], 0, v[122:123]
	v_lshl_add_u64 v[122:123], v[122:123], 0, v[130:131]
	global_store_dwordx2 v[122:123], v[120:121], off
	v_add_u32_e32 v120, 32, v134
	v_ashrrev_i32_e32 v121, 31, v120
	v_cvt_pk_bf16_f32 v116, v116, v117
	v_cvt_pk_bf16_f32 v117, v118, v119
	v_lshlrev_b64 v[118:119], 11, v[120:121]
	v_lshl_add_u64 v[118:119], s[2:3], 0, v[118:119]
	v_lshl_add_u64 v[118:119], v[118:119], 0, v[130:131]
	global_store_dwordx2 v[118:119], v[116:117], off
	v_add_u32_e32 v116, 48, v134
	v_ashrrev_i32_e32 v117, 31, v116
	v_cvt_pk_bf16_f32 v112, v112, v113
	v_cvt_pk_bf16_f32 v113, v114, v115
	v_lshlrev_b64 v[114:115], 11, v[116:117]
	v_readlane_b32 s4, v237, 56
	v_lshl_add_u64 v[114:115], s[2:3], 0, v[114:115]
	v_readlane_b32 s6, v237, 58
	v_lshl_add_u64 v[114:115], v[114:115], 0, v[130:131]
	v_cvt_pk_bf16_f32 v108, v108, v109
	v_cvt_pk_bf16_f32 v109, v110, v111
	v_cvt_pk_bf16_f32 v104, v104, v105
	v_cvt_pk_bf16_f32 v105, v106, v107
	v_cvt_pk_bf16_f32 v100, v100, v101
	v_cvt_pk_bf16_f32 v101, v102, v103
	v_cvt_pk_bf16_f32 v96, v96, v97
	v_cvt_pk_bf16_f32 v97, v98, v99
	v_cvt_pk_bf16_f32 v92, v92, v93
	v_cvt_pk_bf16_f32 v93, v94, v95
	v_cvt_pk_bf16_f32 v88, v88, v89
	v_cvt_pk_bf16_f32 v89, v90, v91
	v_cvt_pk_bf16_f32 v84, v84, v85
	v_cvt_pk_bf16_f32 v85, v86, v87
	v_cvt_pk_bf16_f32 v80, v80, v81
	v_cvt_pk_bf16_f32 v81, v82, v83
	v_cvt_pk_bf16_f32 v76, v76, v77
	v_cvt_pk_bf16_f32 v77, v78, v79
	v_cvt_pk_bf16_f32 v72, v72, v73
	v_cvt_pk_bf16_f32 v73, v74, v75
	v_cvt_pk_bf16_f32 v68, v68, v69
	v_cvt_pk_bf16_f32 v69, v70, v71
	v_cvt_pk_bf16_f32 v64, v64, v65
	v_cvt_pk_bf16_f32 v65, v66, v67
	s_add_i32 s11, s11, s6
	s_mov_b64 s[2:3], 0
	s_andn2_b64 vcc, exec, s[0:1]
	s_mov_b32 s4, s14
	global_store_dwordx2 v[114:115], v[112:113], off
	global_store_dwordx2 v[126:127], v[108:109], off offset:32
	global_store_dwordx2 v[122:123], v[104:105], off offset:32
	global_store_dwordx2 v[118:119], v[100:101], off offset:32
	global_store_dwordx2 v[114:115], v[96:97], off offset:32
	global_store_dwordx2 v[126:127], v[92:93], off offset:64
	global_store_dwordx2 v[122:123], v[88:89], off offset:64
	global_store_dwordx2 v[118:119], v[84:85], off offset:64
	global_store_dwordx2 v[114:115], v[80:81], off offset:64
	global_store_dwordx2 v[126:127], v[76:77], off offset:96
	global_store_dwordx2 v[122:123], v[72:73], off offset:96
	global_store_dwordx2 v[118:119], v[68:69], off offset:96
	global_store_dwordx2 v[114:115], v[64:65], off offset:96
	v_readlane_b32 s5, v237, 57
	v_readlane_b32 s7, v237, 59
	s_cbranch_vccz .LBB0_1617

.LBB0_1597:
	s_and_b32 s0, s11, 7
	v_lshl_add_u32 v140, s0, 17, v136
	v_readlane_b32 s0, v237, 56
	v_readlane_b32 s2, v237, 58
	s_add_i32 s14, s4, s2
	v_readlane_b32 s1, v237, 57
	s_cmpk_gt_i32 s14, 0x7ff
	v_readlane_b32 s3, v237, 59
	s_cselect_b64 s[0:1], -1, 0
	s_cmpk_lt_i32 s14, 0x800
	s_cselect_b64 s[2:3], -1, 0
	s_and_b64 s[6:7], s[2:3], exec
	s_cselect_b32 s4, s14, s4
	v_lshlrev_b32_e32 v10, 1, v139
	s_lshl_b32 s5, s4, 4
	s_lshl_b32 s4, s4, 7
	v_and_b32_e32 v9, 15, v137
	v_bfe_u32 v141, v137, 4, 2
	v_lshl_add_u32 v144, v70, 1, v10
	v_lshl_add_u32 v145, v67, 1, v10
	v_lshl_add_u32 v146, v68, 1, v10
	v_lshl_add_u32 v147, v69, 1, v10
	v_ashrrev_i32_e32 v10, 1, v137
	s_and_b32 s5, s5, 0x3fff80
	s_and_b32 s4, s4, 0x380
	v_and_or_b32 v148, v10, s9, v9
	v_lshlrev_b32_e32 v10, 4, v141
	v_and_b32_e32 v9, 0x4f, v137
	v_add_lshl_u32 v142, s5, v129, 10
	v_add_lshl_u32 v143, s4, v129, 10
	v_or_b32_e32 v65, 0x3c0, v139
	v_mad_u64_u32 v[134:135], s[4:5], v148, s10, v[10:11]
	v_mul_u32_u24_e32 v9, 0x50, v9
	v_lshl_add_u32 v135, v9, 1, v10
	v_add_u32_e32 v151, v65, v138
	v_add_u32_e32 v152, v65, v64
	v_mov_b32_e32 v64, 0
	v_add_u32_e32 v149, 0xf000, v135
	v_add_u32_e32 v150, 0xf040, v135
	v_add_u32_e32 v153, 0x8000, v151
	v_add_u32_e32 v154, 0x8000, v152
	v_add_u32_e32 v155, 0x10000, v151
	v_add_u32_e32 v156, 0x10000, v152
	v_add_u32_e32 v157, 0x18000, v151
	v_add_u32_e32 v158, 0x18000, v152
	s_mov_b32 s15, 0
	v_mov_b32_e32 v65, v64
	v_mov_b32_e32 v66, v64
	v_mov_b32_e32 v67, v64
	v_mov_b32_e32 v68, v64
	v_mov_b32_e32 v69, v64
	v_mov_b32_e32 v70, v64
	v_mov_b32_e32 v71, v64
	v_mov_b32_e32 v72, v64
	v_mov_b32_e32 v73, v64
	v_mov_b32_e32 v74, v64
	v_mov_b32_e32 v75, v64
	v_mov_b32_e32 v76, v64
	v_mov_b32_e32 v77, v64
	v_mov_b32_e32 v78, v64
	v_mov_b32_e32 v79, v64
	v_mov_b32_e32 v80, v64
	v_mov_b32_e32 v81, v64
	v_mov_b32_e32 v82, v64
	v_mov_b32_e32 v83, v64
	v_mov_b32_e32 v84, v64
	v_mov_b32_e32 v85, v64
	v_mov_b32_e32 v86, v64
	v_mov_b32_e32 v87, v64
	v_mov_b32_e32 v88, v64
	v_mov_b32_e32 v89, v64
	v_mov_b32_e32 v90, v64
	v_mov_b32_e32 v91, v64
	v_mov_b32_e32 v92, v64
	v_mov_b32_e32 v93, v64
	v_mov_b32_e32 v94, v64
	v_mov_b32_e32 v95, v64
	v_mov_b32_e32 v96, v64
	v_mov_b32_e32 v97, v64
	v_mov_b32_e32 v98, v64
	v_mov_b32_e32 v99, v64
	v_mov_b32_e32 v100, v64
	v_mov_b32_e32 v101, v64
	v_mov_b32_e32 v102, v64
	v_mov_b32_e32 v103, v64
	v_mov_b32_e32 v104, v64
	v_mov_b32_e32 v105, v64
	v_mov_b32_e32 v106, v64
	v_mov_b32_e32 v107, v64
	v_mov_b32_e32 v108, v64
	v_mov_b32_e32 v109, v64
	v_mov_b32_e32 v110, v64
	v_mov_b32_e32 v111, v64
	v_mov_b32_e32 v112, v64
	v_mov_b32_e32 v113, v64
	v_mov_b32_e32 v114, v64
	v_mov_b32_e32 v115, v64
	v_mov_b32_e32 v116, v64
	v_mov_b32_e32 v117, v64
	v_mov_b32_e32 v118, v64
	v_mov_b32_e32 v119, v64
	v_mov_b32_e32 v120, v64
	v_mov_b32_e32 v121, v64
	v_mov_b32_e32 v122, v64
	v_mov_b32_e32 v123, v64
	v_mov_b32_e32 v124, v64
	v_mov_b32_e32 v125, v64
	v_mov_b32_e32 v126, v64
	v_mov_b32_e32 v127, v64
	v_mov_b32_e32 v9, v132
	v_mov_b32_e32 v10, v133
	s_branch .LBB0_1599
.LBB0_1598:
	s_waitcnt vmcnt(15)
	v_lshl_add_u64 v[60:61], v[130:131], 1, s[84:85]
	global_load_dwordx4 v[60:63], v[60:61], off
	ds_read_b128 v[160:163], v134 offset:40960
	ds_read_b128 v[164:167], v134 offset:43520
	ds_read_b128 v[168:171], v135 offset:61440
	ds_read_b128 v[172:175], v135 offset:64000
	ds_read_b128 v[176:179], v134 offset:46080
	ds_read_b128 v[180:183], v134 offset:48640
	ds_read_b128 v[184:187], v149 offset:5120
	ds_read_b128 v[188:191], v149 offset:7680
	s_setprio 1
	s_waitcnt lgkmcnt(5)
	v_mfma_f32_16x16x32_bf16 v[64:67], v[168:171], v[160:163], v[64:67]
	v_mfma_f32_16x16x32_bf16 v[68:71], v[168:171], v[164:167], v[68:71]
	s_waitcnt lgkmcnt(3)
	v_mfma_f32_16x16x32_bf16 v[72:75], v[168:171], v[176:179], v[72:75]
	s_waitcnt lgkmcnt(2)
	v_mfma_f32_16x16x32_bf16 v[76:79], v[168:171], v[180:183], v[76:79]
	v_mfma_f32_16x16x32_bf16 v[80:83], v[172:175], v[160:163], v[80:83]
	v_mfma_f32_16x16x32_bf16 v[84:87], v[172:175], v[164:167], v[84:87]
	v_mfma_f32_16x16x32_bf16 v[88:91], v[172:175], v[176:179], v[88:91]
	v_mfma_f32_16x16x32_bf16 v[92:95], v[172:175], v[180:183], v[92:95]
	s_waitcnt lgkmcnt(1)
	v_mfma_f32_16x16x32_bf16 v[168:171], v[184:187], v[160:163], v[96:99]
	v_mfma_f32_16x16x32_bf16 v[172:175], v[184:187], v[164:167], v[100:103]
	v_mfma_f32_16x16x32_bf16 v[192:195], v[184:187], v[176:179], v[104:107]
	v_mfma_f32_16x16x32_bf16 v[184:187], v[184:187], v[180:183], v[108:111]
	s_waitcnt lgkmcnt(0)
	v_mfma_f32_16x16x32_bf16 v[160:163], v[188:191], v[160:163], v[112:115]
	v_mfma_f32_16x16x32_bf16 v[164:167], v[188:191], v[164:167], v[116:119]
	v_mfma_f32_16x16x32_bf16 v[176:179], v[188:191], v[176:179], v[120:123]
	v_mfma_f32_16x16x32_bf16 v[180:183], v[188:191], v[180:183], v[124:127]
	s_setprio 0
	ds_read_b128 v[188:191], v134 offset:41024
	ds_read_b128 v[196:199], v134 offset:43584
	ds_read_b128 v[96:99], v135 offset:61504
	ds_read_b128 v[200:203], v135 offset:64064
	ds_read_b128 v[204:207], v134 offset:46144
	ds_read_b128 v[208:211], v134 offset:48704
	ds_read_b128 v[212:215], v150 offset:5120
	ds_read_b128 v[216:219], v150 offset:7680
	s_setprio 1
	s_waitcnt lgkmcnt(5)
	v_mfma_f32_16x16x32_bf16 v[124:127], v[96:99], v[188:191], v[64:67]
	v_mfma_f32_16x16x32_bf16 v[120:123], v[96:99], v[196:199], v[68:71]
	s_waitcnt lgkmcnt(3)
	v_mfma_f32_16x16x32_bf16 v[116:119], v[96:99], v[204:207], v[72:75]
	s_waitcnt lgkmcnt(2)
	v_mfma_f32_16x16x32_bf16 v[112:115], v[96:99], v[208:211], v[76:79]
	v_mfma_f32_16x16x32_bf16 v[108:111], v[200:203], v[188:191], v[80:83]
	v_mfma_f32_16x16x32_bf16 v[104:107], v[200:203], v[196:199], v[84:87]
	v_mfma_f32_16x16x32_bf16 v[100:103], v[200:203], v[204:207], v[88:91]
	v_mfma_f32_16x16x32_bf16 v[96:99], v[200:203], v[208:211], v[92:95]
	s_waitcnt lgkmcnt(1)
	v_mfma_f32_16x16x32_bf16 v[92:95], v[212:215], v[188:191], v[168:171]
	v_mfma_f32_16x16x32_bf16 v[88:91], v[212:215], v[196:199], v[172:175]
	v_mfma_f32_16x16x32_bf16 v[84:87], v[212:215], v[204:207], v[192:195]
	v_mfma_f32_16x16x32_bf16 v[80:83], v[212:215], v[208:211], v[184:187]
	s_waitcnt lgkmcnt(0)
	v_mfma_f32_16x16x32_bf16 v[76:79], v[216:219], v[188:191], v[160:163]
	v_mfma_f32_16x16x32_bf16 v[72:75], v[216:219], v[196:199], v[164:167]
	v_mfma_f32_16x16x32_bf16 v[68:71], v[216:219], v[204:207], v[176:179]
	v_mfma_f32_16x16x32_bf16 v[64:67], v[216:219], v[208:211], v[180:183]
	s_setprio 0
	s_add_i32 s15, s15, 2
	v_add_u32_e32 v143, 0x80, v143
	v_add_u32_e32 v142, 0x80, v142
	v_add_u32_e32 v140, 0x80, v140
	s_andn2_b64 vcc, exec, s[4:5]
	v_add_u32_e32 v138, 0x80, v138
	s_cbranch_vccz .LBB0_1592
.LBB0_1599:
	s_cmp_gt_u32 s15, 12
	s_mov_b64 s[4:5], -1
	s_waitcnt lgkmcnt(0)
	s_barrier
	s_waitcnt vmcnt(15)
	ds_write_b128 v144, v[0:3] offset:40960
	s_waitcnt vmcnt(14)
	ds_write_b128 v144, v[8:11] offset:61440
	s_waitcnt vmcnt(13)
	ds_write_b128 v145, v[16:19] offset:40960
	s_waitcnt vmcnt(12)
	ds_write_b128 v145, v[24:27] offset:61440
	s_waitcnt vmcnt(11)
	ds_write_b128 v146, v[28:31] offset:40960
	s_waitcnt vmcnt(10)
	ds_write_b128 v146, v[36:39] offset:61440
	s_waitcnt vmcnt(9)
	ds_write_b128 v147, v[44:47] offset:40960
	s_waitcnt vmcnt(8)
	ds_write_b128 v147, v[56:59] offset:61440
	s_cbranch_scc0 .LBB0_1605
	s_and_b64 vcc, exec, s[0:1]
	s_cbranch_vccz .LBB0_1602
	v_mov_b32_e32 v130, v151
	s_mov_b64 s[4:5], 0
	v_lshl_add_u64 v[0:1], v[130:131], 1, s[78:79]
	v_mov_b32_e32 v130, v152
	global_load_dwordx4 v[0:3], v[0:1], off
	s_nop 0
	v_lshl_add_u64 v[8:9], v[130:131], 1, s[84:85]
	v_mov_b32_e32 v130, v153
	global_load_dwordx4 v[8:11], v[8:9], off
	s_nop 0
	s_nop 0
	v_lshl_add_u64 v[16:17], v[130:131], 1, s[78:79]
	v_mov_b32_e32 v130, v154
	global_load_dwordx4 v[16:19], v[16:17], off
	s_nop 0
	v_lshl_add_u64 v[24:25], v[130:131], 1, s[84:85]
	v_mov_b32_e32 v130, v155
	global_load_dwordx4 v[24:27], v[24:25], off
	s_nop 0
	v_lshl_add_u64 v[28:29], v[130:131], 1, s[78:79]
	v_mov_b32_e32 v130, v156
	global_load_dwordx4 v[28:31], v[28:29], off
	s_nop 0
	v_lshl_add_u64 v[36:37], v[130:131], 1, s[84:85]
	v_mov_b32_e32 v130, v157
	global_load_dwordx4 v[36:39], v[36:37], off
	s_nop 0
	v_lshl_add_u64 v[44:45], v[130:131], 1, s[78:79]
	global_load_dwordx4 v[44:47], v[44:45], off
	v_mov_b32_e32 v130, v158
.LBB0_1602:
	s_andn2_b64 vcc, exec, s[4:5]
	s_cbranch_vccnz .LBB0_1604
	s_waitcnt vmcnt(8)
	v_add_u32_e32 v44, v139, v142
	v_add_u32_e32 v130, 0xfffffcc0, v44
	v_add_u32_e32 v56, v139, v143
	v_lshl_add_u64 v[0:1], v[130:131], 1, s[78:79]
	v_add_u32_e32 v130, 0xfffffcc0, v56
	global_load_dwordx4 v[0:3], v[0:1], off
	s_nop 0
	v_lshl_add_u64 v[8:9], v[130:131], 1, s[84:85]
	v_add_u32_e32 v130, 0x7cc0, v44
	global_load_dwordx4 v[8:11], v[8:9], off
	s_nop 0
	s_nop 0
	v_lshl_add_u64 v[16:17], v[130:131], 1, s[78:79]
	v_add_u32_e32 v130, 0x7cc0, v56
	global_load_dwordx4 v[16:19], v[16:17], off
	s_nop 0
	v_lshl_add_u64 v[24:25], v[130:131], 1, s[84:85]
	v_add_u32_e32 v130, 0xfcc0, v44
	global_load_dwordx4 v[24:27], v[24:25], off
	s_nop 0
	v_lshl_add_u64 v[28:29], v[130:131], 1, s[78:79]
	v_add_u32_e32 v130, 0xfcc0, v56
	global_load_dwordx4 v[28:31], v[28:29], off
	s_nop 0
	v_lshl_add_u64 v[36:37], v[130:131], 1, s[84:85]
	v_add_u32_e32 v130, 0x17cc0, v44
	global_load_dwordx4 v[36:39], v[36:37], off
	s_nop 0
	v_lshl_add_u64 v[44:45], v[130:131], 1, s[78:79]
	global_load_dwordx4 v[44:47], v[44:45], off
	v_add_u32_e32 v130, 0x17cc0, v56

.LBB0_1605:
	s_andn2_b64 vcc, exec, s[4:5]
	v_add_u32_e32 v160, v139, v138
	v_add_u32_e32 v159, v139, v140
	s_cbranch_vccnz .LBB0_1607
	v_add_u32_e32 v130, 0xc0, v160
	s_nop 0
	v_lshl_add_u64 v[0:1], v[130:131], 1, s[78:79]
	v_add_u32_e32 v130, 0xc0, v159
	global_load_dwordx4 v[0:3], v[0:1], off
	s_nop 0
	v_lshl_add_u64 v[8:9], v[130:131], 1, s[84:85]
	v_add_u32_e32 v130, 0x80c0, v160
	global_load_dwordx4 v[8:11], v[8:9], off
	s_nop 0
	s_nop 0
	v_lshl_add_u64 v[16:17], v[130:131], 1, s[78:79]
	v_add_u32_e32 v130, 0x80c0, v159
	global_load_dwordx4 v[16:19], v[16:17], off
	s_nop 0
	v_lshl_add_u64 v[24:25], v[130:131], 1, s[84:85]
	v_add_u32_e32 v130, 0x100c0, v160
	global_load_dwordx4 v[24:27], v[24:25], off
	s_nop 0
	v_lshl_add_u64 v[28:29], v[130:131], 1, s[78:79]
	v_add_u32_e32 v130, 0x100c0, v159
	global_load_dwordx4 v[28:31], v[28:29], off
	s_nop 0
	v_lshl_add_u64 v[36:37], v[130:131], 1, s[84:85]
	v_add_u32_e32 v130, 0x180c0, v160
	global_load_dwordx4 v[36:39], v[36:37], off
	s_nop 0
	v_lshl_add_u64 v[44:45], v[130:131], 1, s[78:79]
	global_load_dwordx4 v[44:47], v[44:45], off
	v_add_u32_e32 v130, 0x180c0, v159
.LBB0_1607:
	s_nop 0
	v_lshl_add_u64 v[56:57], v[130:131], 1, s[84:85]
	global_load_dwordx4 v[56:59], v[56:57], off
	ds_read_b128 v[162:165], v134
	ds_read_b128 v[166:169], v134 offset:2560
	ds_read_b128 v[170:173], v135 offset:20480
	ds_read_b128 v[174:177], v135 offset:23040
	ds_read_b128 v[178:181], v134 offset:5120
	ds_read_b128 v[182:185], v134 offset:7680
	ds_read_b128 v[186:189], v135 offset:25600
	ds_read_b128 v[190:193], v135 offset:28160
	s_setprio 1
	s_waitcnt lgkmcnt(5)
	v_mfma_f32_16x16x32_bf16 v[124:127], v[170:173], v[162:165], v[124:127]
	v_mfma_f32_16x16x32_bf16 v[120:123], v[170:173], v[166:169], v[120:123]
	s_waitcnt lgkmcnt(3)
	v_mfma_f32_16x16x32_bf16 v[116:119], v[170:173], v[178:181], v[116:119]
	s_waitcnt lgkmcnt(2)
	v_mfma_f32_16x16x32_bf16 v[112:115], v[170:173], v[182:185], v[112:115]
	v_mfma_f32_16x16x32_bf16 v[108:111], v[174:177], v[162:165], v[108:111]
	v_mfma_f32_16x16x32_bf16 v[104:107], v[174:177], v[166:169], v[104:107]
	v_mfma_f32_16x16x32_bf16 v[100:103], v[174:177], v[178:181], v[100:103]
	v_mfma_f32_16x16x32_bf16 v[96:99], v[174:177], v[182:185], v[96:99]
	s_waitcnt lgkmcnt(1)
	v_mfma_f32_16x16x32_bf16 v[170:173], v[186:189], v[162:165], v[92:95]
	v_mfma_f32_16x16x32_bf16 v[174:177], v[186:189], v[166:169], v[88:91]
	v_mfma_f32_16x16x32_bf16 v[194:197], v[186:189], v[178:181], v[84:87]
	v_mfma_f32_16x16x32_bf16 v[186:189], v[186:189], v[182:185], v[80:83]
	s_waitcnt lgkmcnt(0)
	v_mfma_f32_16x16x32_bf16 v[162:165], v[190:193], v[162:165], v[76:79]
	v_mfma_f32_16x16x32_bf16 v[166:169], v[190:193], v[166:169], v[72:75]
	v_mfma_f32_16x16x32_bf16 v[178:181], v[190:193], v[178:181], v[68:71]
	v_mfma_f32_16x16x32_bf16 v[182:185], v[190:193], v[182:185], v[64:67]
	s_setprio 0
	ds_read_b128 v[190:193], v134 offset:64
	ds_read_b128 v[198:201], v134 offset:2624
	ds_read_b128 v[76:79], v135 offset:20544
	ds_read_b128 v[92:95], v135 offset:23104
	ds_read_b128 v[202:205], v134 offset:5184
	ds_read_b128 v[206:209], v134 offset:7744
	ds_read_b128 v[210:213], v135 offset:25664
	ds_read_b128 v[214:217], v135 offset:28224
	s_setprio 1
	s_waitcnt lgkmcnt(5)
	v_mfma_f32_16x16x32_bf16 v[64:67], v[76:79], v[190:193], v[124:127]
	v_mfma_f32_16x16x32_bf16 v[68:71], v[76:79], v[198:201], v[120:123]
	s_waitcnt lgkmcnt(3)
	v_mfma_f32_16x16x32_bf16 v[72:75], v[76:79], v[202:205], v[116:119]
	s_waitcnt lgkmcnt(2)
	v_mfma_f32_16x16x32_bf16 v[76:79], v[76:79], v[206:209], v[112:115]
	v_mfma_f32_16x16x32_bf16 v[80:83], v[92:95], v[190:193], v[108:111]
	v_mfma_f32_16x16x32_bf16 v[84:87], v[92:95], v[198:201], v[104:107]
	v_mfma_f32_16x16x32_bf16 v[88:91], v[92:95], v[202:205], v[100:103]
	v_mfma_f32_16x16x32_bf16 v[92:95], v[92:95], v[206:209], v[96:99]
	s_waitcnt lgkmcnt(1)
	v_mfma_f32_16x16x32_bf16 v[96:99], v[210:213], v[190:193], v[170:173]
	v_mfma_f32_16x16x32_bf16 v[100:103], v[210:213], v[198:201], v[174:177]
	v_mfma_f32_16x16x32_bf16 v[104:107], v[210:213], v[202:205], v[194:197]
	v_mfma_f32_16x16x32_bf16 v[108:111], v[210:213], v[206:209], v[186:189]
	s_waitcnt lgkmcnt(0)
	v_mfma_f32_16x16x32_bf16 v[112:115], v[214:217], v[190:193], v[162:165]
	v_mfma_f32_16x16x32_bf16 v[116:119], v[214:217], v[198:201], v[166:169]
	v_mfma_f32_16x16x32_bf16 v[120:123], v[214:217], v[202:205], v[178:181]
	v_mfma_f32_16x16x32_bf16 v[124:127], v[214:217], v[206:209], v[182:185]
	s_setprio 0
	s_cmp_gt_u32 s15, 13
	s_cselect_b64 s[4:5], -1, 0
	s_cmp_lt_u32 s15, 14
	s_cselect_b64 s[6:7], -1, 0
	s_or_b64 s[6:7], s[2:3], s[6:7]
	s_andn2_b64 vcc, exec, s[6:7]
	s_barrier
	s_cbranch_vccnz .LBB0_1609
	s_waitcnt vmcnt(15)
	ds_write_b128 v144, v[4:7]
	s_waitcnt vmcnt(14)
	ds_write_b128 v144, v[12:15] offset:20480
	s_waitcnt vmcnt(13)
	ds_write_b128 v145, v[20:23]
	s_waitcnt vmcnt(12)
	ds_write_b128 v145, v[32:35] offset:20480
	s_waitcnt vmcnt(11)
	ds_write_b128 v146, v[40:43]
	s_waitcnt vmcnt(10)
	ds_write_b128 v146, v[48:51] offset:20480
	s_waitcnt vmcnt(9)
	ds_write_b128 v147, v[52:55]
	s_waitcnt vmcnt(8)
	ds_write_b128 v147, v[60:63] offset:20480
.LBB0_1609:
	s_cmp_gt_u32 s15, 11
	s_mov_b64 s[6:7], -1
	s_cbranch_scc0 .LBB0_1615
	s_and_b64 vcc, exec, s[0:1]
	s_cbranch_vccz .LBB0_1612
	v_mov_b32_e32 v130, v151
	s_mov_b64 s[6:7], 0
	s_waitcnt vmcnt(8)
	v_lshl_add_u64 v[4:5], v[130:131], 1, s[78:79]
	v_mov_b32_e32 v130, v152
	global_load_dwordx4 v[4:7], v[4:5], off
	s_nop 0
	v_lshl_add_u64 v[12:13], v[130:131], 1, s[84:85]
	v_mov_b32_e32 v130, v153
	global_load_dwordx4 v[12:15], v[12:13], off
	s_nop 0
	v_lshl_add_u64 v[20:21], v[130:131], 1, s[78:79]
	v_mov_b32_e32 v130, v154
	global_load_dwordx4 v[20:23], v[20:21], off
	s_nop 0
	v_lshl_add_u64 v[32:33], v[130:131], 1, s[84:85]
	v_mov_b32_e32 v130, v155
	global_load_dwordx4 v[32:35], v[32:33], off
	s_nop 0
	v_lshl_add_u64 v[40:41], v[130:131], 1, s[78:79]
	v_mov_b32_e32 v130, v156
	global_load_dwordx4 v[40:43], v[40:41], off
	s_nop 0
	v_lshl_add_u64 v[48:49], v[130:131], 1, s[84:85]
	v_mov_b32_e32 v130, v157
	global_load_dwordx4 v[48:51], v[48:49], off
	s_nop 0
	v_lshl_add_u64 v[52:53], v[130:131], 1, s[78:79]
	global_load_dwordx4 v[52:55], v[52:53], off
	v_mov_b32_e32 v130, v158
.LBB0_1612:
	s_andn2_b64 vcc, exec, s[6:7]
	s_cbranch_vccnz .LBB0_1614
	v_add_u32_e32 v132, v139, v142
	v_add_u32_e32 v130, 0xfffffd00, v132
	v_add_u32_e32 v133, v139, v143
	s_waitcnt vmcnt(8)
	v_lshl_add_u64 v[4:5], v[130:131], 1, s[78:79]
	v_add_u32_e32 v130, 0xfffffd00, v133
	global_load_dwordx4 v[4:7], v[4:5], off
	s_nop 0
	v_lshl_add_u64 v[12:13], v[130:131], 1, s[84:85]
	v_add_u32_e32 v130, 0x7d00, v132
	global_load_dwordx4 v[12:15], v[12:13], off
	s_nop 0
	v_lshl_add_u64 v[20:21], v[130:131], 1, s[78:79]
	v_add_u32_e32 v130, 0x7d00, v133
	global_load_dwordx4 v[20:23], v[20:21], off
	s_nop 0
	v_lshl_add_u64 v[32:33], v[130:131], 1, s[84:85]
	v_add_u32_e32 v130, 0xfd00, v132
	global_load_dwordx4 v[32:35], v[32:33], off
	s_nop 0
	v_lshl_add_u64 v[40:41], v[130:131], 1, s[78:79]
	v_add_u32_e32 v130, 0xfd00, v133
	global_load_dwordx4 v[40:43], v[40:41], off
	s_nop 0
	v_lshl_add_u64 v[48:49], v[130:131], 1, s[84:85]
	v_add_u32_e32 v130, 0x17d00, v132
	global_load_dwordx4 v[48:51], v[48:49], off
	s_nop 0
	v_lshl_add_u64 v[52:53], v[130:131], 1, s[78:79]
	global_load_dwordx4 v[52:55], v[52:53], off
	v_add_u32_e32 v130, 0x17d00, v133

.LBB0_1616:
	v_add_u32_e32 v130, 0x100, v160
	s_waitcnt vmcnt(8)
	v_lshl_add_u64 v[4:5], v[130:131], 1, s[78:79]
	v_add_u32_e32 v130, 0x100, v159
	global_load_dwordx4 v[4:7], v[4:5], off
	s_nop 0
	v_lshl_add_u64 v[12:13], v[130:131], 1, s[84:85]
	v_add_u32_e32 v130, 0x8100, v160
	global_load_dwordx4 v[12:15], v[12:13], off
	s_nop 0
	v_lshl_add_u64 v[20:21], v[130:131], 1, s[78:79]
	v_add_u32_e32 v130, 0x8100, v159
	global_load_dwordx4 v[20:23], v[20:21], off
	s_nop 0
	v_lshl_add_u64 v[32:33], v[130:131], 1, s[84:85]
	v_add_u32_e32 v130, 0x10100, v160
	global_load_dwordx4 v[32:35], v[32:33], off
	s_nop 0
	v_lshl_add_u64 v[40:41], v[130:131], 1, s[78:79]
	v_add_u32_e32 v130, 0x10100, v159
	global_load_dwordx4 v[40:43], v[40:41], off
	s_nop 0
	v_lshl_add_u64 v[48:49], v[130:131], 1, s[84:85]
	v_add_u32_e32 v130, 0x18100, v160
	global_load_dwordx4 v[48:51], v[48:49], off
	s_nop 0
	v_lshl_add_u64 v[52:53], v[130:131], 1, s[78:79]
	global_load_dwordx4 v[52:55], v[52:53], off
	v_add_u32_e32 v130, 0x18100, v159
	s_branch .LBB0_1598

.LBB0_1828:
	s_waitcnt vmcnt(15)
	v_lshl_add_u64 v[60:61], v[130:131], 1, s[92:93]
	global_load_dwordx4 v[60:63], v[60:61], off
	ds_read_b128 v[184:187], v136 offset:40960
	ds_read_b128 v[188:191], v136 offset:43520
	ds_read_b128 v[192:195], v137 offset:61440
	ds_read_b128 v[196:199], v137 offset:64000
	ds_read_b128 v[200:203], v136 offset:46080
	ds_read_b128 v[204:207], v136 offset:48640
	ds_read_b128 v[208:211], v161
	ds_read_b128 v[212:215], v162
	s_setprio 1
	s_waitcnt lgkmcnt(5)
	v_mfma_f32_16x16x32_bf16 v[64:67], v[192:195], v[184:187], v[64:67]
	v_mfma_f32_16x16x32_bf16 v[68:71], v[192:195], v[188:191], v[68:71]
	s_waitcnt lgkmcnt(3)
	v_mfma_f32_16x16x32_bf16 v[72:75], v[192:195], v[200:203], v[72:75]
	s_waitcnt lgkmcnt(2)
	v_mfma_f32_16x16x32_bf16 v[76:79], v[192:195], v[204:207], v[76:79]
	v_mfma_f32_16x16x32_bf16 v[80:83], v[196:199], v[184:187], v[80:83]
	v_mfma_f32_16x16x32_bf16 v[84:87], v[196:199], v[188:191], v[84:87]
	v_mfma_f32_16x16x32_bf16 v[88:91], v[196:199], v[200:203], v[88:91]
	s_waitcnt lgkmcnt(1)
	v_mfma_f32_16x16x32_bf16 v[96:99], v[208:211], v[184:187], v[96:99]
	v_mfma_f32_16x16x32_bf16 v[100:103], v[208:211], v[188:191], v[100:103]
	s_waitcnt lgkmcnt(0)
	v_mfma_f32_16x16x32_bf16 v[112:115], v[212:215], v[184:187], v[112:115]
	v_mfma_f32_16x16x32_bf16 v[192:195], v[196:199], v[204:207], v[92:95]
	v_mfma_f32_16x16x32_bf16 v[196:199], v[208:211], v[200:203], v[104:107]
	v_mfma_f32_16x16x32_bf16 v[208:211], v[208:211], v[204:207], v[108:111]
	v_mfma_f32_16x16x32_bf16 v[184:187], v[212:215], v[188:191], v[116:119]
	v_mfma_f32_16x16x32_bf16 v[188:191], v[212:215], v[200:203], v[120:123]
	v_mfma_f32_16x16x32_bf16 v[200:203], v[212:215], v[204:207], v[124:127]
	s_setprio 0
	ds_read_b128 v[204:207], v136 offset:41024
	ds_read_b128 v[212:215], v136 offset:43584
	ds_read_b128 v[104:107], v137 offset:61504
	ds_read_b128 v[116:119], v137 offset:64064
	ds_read_b128 v[216:219], v136 offset:46144
	ds_read_b128 v[220:223], v136 offset:48704
	ds_read_b128 v[224:227], v163
	ds_read_b128 v[228:231], v164
	s_setprio 1
	s_waitcnt lgkmcnt(5)
	v_mfma_f32_16x16x32_bf16 v[124:127], v[104:107], v[204:207], v[64:67]
	v_mfma_f32_16x16x32_bf16 v[108:111], v[104:107], v[212:215], v[68:71]
	s_waitcnt lgkmcnt(3)
	v_mfma_f32_16x16x32_bf16 v[92:95], v[104:107], v[216:219], v[72:75]
	s_waitcnt lgkmcnt(2)
	v_mfma_f32_16x16x32_bf16 v[76:79], v[104:107], v[220:223], v[76:79]
	v_mfma_f32_16x16x32_bf16 v[120:123], v[116:119], v[204:207], v[80:83]
	v_mfma_f32_16x16x32_bf16 v[104:107], v[116:119], v[212:215], v[84:87]
	v_mfma_f32_16x16x32_bf16 v[88:91], v[116:119], v[216:219], v[88:91]
	v_mfma_f32_16x16x32_bf16 v[72:75], v[116:119], v[220:223], v[192:195]
	s_waitcnt lgkmcnt(1)
	v_mfma_f32_16x16x32_bf16 v[116:119], v[224:227], v[204:207], v[96:99]
	v_mfma_f32_16x16x32_bf16 v[100:103], v[224:227], v[212:215], v[100:103]
	v_mfma_f32_16x16x32_bf16 v[84:87], v[224:227], v[216:219], v[196:199]
	v_mfma_f32_16x16x32_bf16 v[68:71], v[224:227], v[220:223], v[208:211]
	s_waitcnt lgkmcnt(0)
	v_mfma_f32_16x16x32_bf16 v[112:115], v[228:231], v[204:207], v[112:115]
	v_mfma_f32_16x16x32_bf16 v[96:99], v[228:231], v[212:215], v[184:187]
	v_mfma_f32_16x16x32_bf16 v[80:83], v[228:231], v[216:219], v[188:191]
	v_mfma_f32_16x16x32_bf16 v[64:67], v[228:231], v[220:223], v[200:203]
	s_setprio 0
	s_add_i32 s10, s10, 2
	v_add_u32_e32 v182, 0x80, v182
	v_add_u32_e32 v181, 0x80, v181
	v_add_u32_e32 v180, 0x80, v180
	v_add_u32_e32 v179, 0x80, v179
	v_add_u32_e32 v178, 0x80, v178
	v_add_u32_e32 v177, 0x80, v177
	v_add_u32_e32 v176, 0x80, v176
	v_add_u32_e32 v175, 0x80, v175
	v_add_u32_e32 v174, 0x80, v174
	v_add_u32_e32 v173, 0x80, v173
	s_and_b64 vcc, exec, s[0:1]
	s_cbranch_vccnz .LBB0_1847
.LBB0_1829:
	s_cmp_gt_u32 s10, 12
	s_mov_b64 s[0:1], -1
	s_waitcnt lgkmcnt(0)
	s_barrier
	s_waitcnt vmcnt(15)
	ds_write_b128 v157, v[0:3] offset:40960
	s_waitcnt vmcnt(14)
	ds_write_b128 v157, v[8:11] offset:61440
	s_waitcnt vmcnt(13)
	ds_write_b128 v158, v[16:19] offset:40960
	s_waitcnt vmcnt(12)
	ds_write_b128 v158, v[24:27] offset:61440
	s_waitcnt vmcnt(11)
	ds_write_b128 v159, v[28:31] offset:40960
	s_waitcnt vmcnt(10)
	ds_write_b128 v159, v[36:39] offset:61440
	s_waitcnt vmcnt(9)
	ds_write_b128 v160, v[44:47] offset:40960
	s_waitcnt vmcnt(8)
	ds_write_b128 v160, v[56:59] offset:61440
	s_cbranch_scc0 .LBB0_1835
	s_and_b64 vcc, exec, s[4:5]
	s_cbranch_vccz .LBB0_1832
	v_mov_b32_e32 v130, v165
	s_mov_b64 s[0:1], 0
	v_lshl_add_u64 v[0:1], v[130:131], 1, s[76:77]
	v_mov_b32_e32 v130, v166
	global_load_dwordx4 v[0:3], v[0:1], off
	s_nop 0
	v_lshl_add_u64 v[8:9], v[130:131], 1, s[92:93]
	v_mov_b32_e32 v130, v167
	global_load_dwordx4 v[8:11], v[8:9], off
	s_nop 0
	v_lshl_add_u64 v[16:17], v[130:131], 1, s[76:77]
	v_mov_b32_e32 v130, v168
	global_load_dwordx4 v[16:19], v[16:17], off
	s_nop 0
	v_lshl_add_u64 v[24:25], v[130:131], 1, s[92:93]
	v_mov_b32_e32 v130, v169
	global_load_dwordx4 v[24:27], v[24:25], off
	s_nop 0
	v_lshl_add_u64 v[28:29], v[130:131], 1, s[76:77]
	v_mov_b32_e32 v130, v170
	global_load_dwordx4 v[28:31], v[28:29], off
	s_nop 0
	v_lshl_add_u64 v[36:37], v[130:131], 1, s[92:93]
	v_mov_b32_e32 v130, v171
	global_load_dwordx4 v[36:39], v[36:37], off
	s_nop 0
	v_lshl_add_u64 v[44:45], v[130:131], 1, s[76:77]
	global_load_dwordx4 v[44:47], v[44:45], off
	v_mov_b32_e32 v130, v172
.LBB0_1832:
	s_andn2_b64 vcc, exec, s[0:1]
	s_cbranch_vccnz .LBB0_1834
	v_add3_u32 v130, v133, v178, s33
	v_add_u32_e32 v56, v133, v179
	s_nop 0
	v_lshl_add_u64 v[0:1], v[130:131], 1, s[76:77]
	v_add_u32_e32 v130, 0xfffffcc0, v56
	global_load_dwordx4 v[0:3], v[0:1], off
	s_nop 0
	v_lshl_add_u64 v[8:9], v[130:131], 1, s[92:93]
	v_add3_u32 v130, v133, v180, s33
	global_load_dwordx4 v[8:11], v[8:9], off
	s_nop 0
	v_lshl_add_u64 v[16:17], v[130:131], 1, s[76:77]
	v_add_u32_e32 v130, 0x7cc0, v56
	global_load_dwordx4 v[16:19], v[16:17], off
	s_nop 0
	v_lshl_add_u64 v[24:25], v[130:131], 1, s[92:93]
	v_add3_u32 v130, v133, v181, s33
	global_load_dwordx4 v[24:27], v[24:25], off
	s_nop 0
	v_lshl_add_u64 v[28:29], v[130:131], 1, s[76:77]
	v_add_u32_e32 v130, 0xfcc0, v56
	global_load_dwordx4 v[28:31], v[28:29], off
	s_nop 0
	v_lshl_add_u64 v[36:37], v[130:131], 1, s[92:93]
	v_add3_u32 v130, v133, v182, s33
	global_load_dwordx4 v[36:39], v[36:37], off
	s_nop 0
	v_lshl_add_u64 v[44:45], v[130:131], 1, s[76:77]
	global_load_dwordx4 v[44:47], v[44:45], off
	v_add_u32_e32 v130, 0x17cc0, v56

.LBB0_1835:
	s_andn2_b64 vcc, exec, s[0:1]
	v_add_u32_e32 v183, v133, v174
	s_cbranch_vccnz .LBB0_1837
	v_add3_u32 v130, v133, v173, s96
	s_nop 0
	v_lshl_add_u64 v[0:1], v[130:131], 1, s[76:77]
	v_add_u32_e32 v130, 0xc0, v183
	global_load_dwordx4 v[0:3], v[0:1], off
	s_nop 0
	v_lshl_add_u64 v[8:9], v[130:131], 1, s[92:93]
	v_add3_u32 v130, v133, v175, s96
	global_load_dwordx4 v[8:11], v[8:9], off
	s_nop 0
	v_lshl_add_u64 v[16:17], v[130:131], 1, s[76:77]
	v_add_u32_e32 v130, 0x80c0, v183
	global_load_dwordx4 v[16:19], v[16:17], off
	s_nop 0
	v_lshl_add_u64 v[24:25], v[130:131], 1, s[92:93]
	v_add3_u32 v130, v133, v176, s96
	global_load_dwordx4 v[24:27], v[24:25], off
	s_nop 0
	v_lshl_add_u64 v[28:29], v[130:131], 1, s[76:77]
	v_add_u32_e32 v130, 0x100c0, v183
	global_load_dwordx4 v[28:31], v[28:29], off
	s_nop 0
	v_lshl_add_u64 v[36:37], v[130:131], 1, s[92:93]
	v_add3_u32 v130, v133, v177, s96
	global_load_dwordx4 v[36:39], v[36:37], off
	s_nop 0
	v_lshl_add_u64 v[44:45], v[130:131], 1, s[76:77]
	global_load_dwordx4 v[44:47], v[44:45], off
	v_add_u32_e32 v130, 0x180c0, v183
.LBB0_1837:
	s_nop 0
	v_lshl_add_u64 v[56:57], v[130:131], 1, s[92:93]
	global_load_dwordx4 v[56:59], v[56:57], off
	ds_read_b128 v[184:187], v136
	ds_read_b128 v[188:191], v136 offset:2560
	ds_read_b128 v[192:195], v137 offset:20480
	ds_read_b128 v[196:199], v137 offset:23040
	ds_read_b128 v[200:203], v136 offset:5120
	ds_read_b128 v[204:207], v136 offset:7680
	ds_read_b128 v[208:211], v137 offset:25600
	ds_read_b128 v[212:215], v137 offset:28160
	s_setprio 1
	s_waitcnt lgkmcnt(5)
	v_mfma_f32_16x16x32_bf16 v[124:127], v[192:195], v[184:187], v[124:127]
	v_mfma_f32_16x16x32_bf16 v[108:111], v[192:195], v[188:191], v[108:111]
	s_waitcnt lgkmcnt(3)
	v_mfma_f32_16x16x32_bf16 v[92:95], v[192:195], v[200:203], v[92:95]
	s_waitcnt lgkmcnt(2)
	v_mfma_f32_16x16x32_bf16 v[76:79], v[192:195], v[204:207], v[76:79]
	v_mfma_f32_16x16x32_bf16 v[120:123], v[196:199], v[184:187], v[120:123]
	v_mfma_f32_16x16x32_bf16 v[104:107], v[196:199], v[188:191], v[104:107]
	v_mfma_f32_16x16x32_bf16 v[88:91], v[196:199], v[200:203], v[88:91]
	s_waitcnt lgkmcnt(1)
	v_mfma_f32_16x16x32_bf16 v[116:119], v[208:211], v[184:187], v[116:119]
	v_mfma_f32_16x16x32_bf16 v[100:103], v[208:211], v[188:191], v[100:103]
	s_waitcnt lgkmcnt(0)
	v_mfma_f32_16x16x32_bf16 v[112:115], v[212:215], v[184:187], v[112:115]
	v_mfma_f32_16x16x32_bf16 v[192:195], v[196:199], v[204:207], v[72:75]
	v_mfma_f32_16x16x32_bf16 v[196:199], v[208:211], v[200:203], v[84:87]
	v_mfma_f32_16x16x32_bf16 v[208:211], v[208:211], v[204:207], v[68:71]
	v_mfma_f32_16x16x32_bf16 v[184:187], v[212:215], v[188:191], v[96:99]
	v_mfma_f32_16x16x32_bf16 v[188:191], v[212:215], v[200:203], v[80:83]
	v_mfma_f32_16x16x32_bf16 v[200:203], v[212:215], v[204:207], v[64:67]
	s_setprio 0
	ds_read_b128 v[204:207], v136 offset:64
	ds_read_b128 v[212:215], v136 offset:2624
	ds_read_b128 v[80:83], v137 offset:20544
	ds_read_b128 v[96:99], v137 offset:23104
	ds_read_b128 v[216:219], v136 offset:5184
	ds_read_b128 v[220:223], v136 offset:7744
	ds_read_b128 v[224:227], v137 offset:25664
	ds_read_b128 v[228:231], v137 offset:28224
	s_setprio 1
	s_waitcnt lgkmcnt(5)
	v_mfma_f32_16x16x32_bf16 v[64:67], v[80:83], v[204:207], v[124:127]
	v_mfma_f32_16x16x32_bf16 v[68:71], v[80:83], v[212:215], v[108:111]
	s_waitcnt lgkmcnt(3)
	v_mfma_f32_16x16x32_bf16 v[72:75], v[80:83], v[216:219], v[92:95]
	s_waitcnt lgkmcnt(2)
	v_mfma_f32_16x16x32_bf16 v[76:79], v[80:83], v[220:223], v[76:79]
	v_mfma_f32_16x16x32_bf16 v[80:83], v[96:99], v[204:207], v[120:123]
	v_mfma_f32_16x16x32_bf16 v[84:87], v[96:99], v[212:215], v[104:107]
	v_mfma_f32_16x16x32_bf16 v[88:91], v[96:99], v[216:219], v[88:91]
	v_mfma_f32_16x16x32_bf16 v[92:95], v[96:99], v[220:223], v[192:195]
	s_waitcnt lgkmcnt(1)
	v_mfma_f32_16x16x32_bf16 v[96:99], v[224:227], v[204:207], v[116:119]
	v_mfma_f32_16x16x32_bf16 v[100:103], v[224:227], v[212:215], v[100:103]
	v_mfma_f32_16x16x32_bf16 v[104:107], v[224:227], v[216:219], v[196:199]
	v_mfma_f32_16x16x32_bf16 v[108:111], v[224:227], v[220:223], v[208:211]
	s_waitcnt lgkmcnt(0)
	v_mfma_f32_16x16x32_bf16 v[112:115], v[228:231], v[204:207], v[112:115]
	v_mfma_f32_16x16x32_bf16 v[116:119], v[228:231], v[212:215], v[184:187]
	v_mfma_f32_16x16x32_bf16 v[120:123], v[228:231], v[216:219], v[188:191]
	v_mfma_f32_16x16x32_bf16 v[124:127], v[228:231], v[220:223], v[200:203]
	s_setprio 0
	s_cmp_gt_u32 s10, 13
	s_cselect_b64 s[0:1], -1, 0
	s_cmp_lt_u32 s10, 14
	s_cselect_b64 s[8:9], -1, 0
	s_or_b64 s[8:9], s[6:7], s[8:9]
	s_andn2_b64 vcc, exec, s[8:9]
	s_barrier
	s_cbranch_vccnz .LBB0_1839
	s_waitcnt vmcnt(15)
	ds_write_b128 v157, v[4:7]
	s_waitcnt vmcnt(14)
	ds_write_b128 v157, v[12:15] offset:20480
	s_waitcnt vmcnt(13)
	ds_write_b128 v158, v[20:23]
	s_waitcnt vmcnt(12)
	ds_write_b128 v158, v[32:35] offset:20480
	s_waitcnt vmcnt(11)
	ds_write_b128 v159, v[40:43]
	s_waitcnt vmcnt(10)
	ds_write_b128 v159, v[48:51] offset:20480
	s_waitcnt vmcnt(9)
	ds_write_b128 v160, v[52:55]
	s_waitcnt vmcnt(8)
	ds_write_b128 v160, v[60:63] offset:20480
.LBB0_1839:
	s_cmp_gt_u32 s10, 11
	s_mov_b64 s[8:9], -1
	s_cbranch_scc0 .LBB0_1845
	s_and_b64 vcc, exec, s[4:5]
	s_cbranch_vccz .LBB0_1842
	v_mov_b32_e32 v130, v165
	s_mov_b64 s[8:9], 0
	s_waitcnt vmcnt(8)
	v_lshl_add_u64 v[4:5], v[130:131], 1, s[76:77]
	v_mov_b32_e32 v130, v166
	global_load_dwordx4 v[4:7], v[4:5], off
	s_nop 0
	v_lshl_add_u64 v[12:13], v[130:131], 1, s[92:93]
	v_mov_b32_e32 v130, v167
	global_load_dwordx4 v[12:15], v[12:13], off
	s_nop 0
	v_lshl_add_u64 v[20:21], v[130:131], 1, s[76:77]
	v_mov_b32_e32 v130, v168
	global_load_dwordx4 v[20:23], v[20:21], off
	s_nop 0
	v_lshl_add_u64 v[32:33], v[130:131], 1, s[92:93]
	v_mov_b32_e32 v130, v169
	global_load_dwordx4 v[32:35], v[32:33], off
	s_nop 0
	v_lshl_add_u64 v[40:41], v[130:131], 1, s[76:77]
	v_mov_b32_e32 v130, v170
	global_load_dwordx4 v[40:43], v[40:41], off
	s_nop 0
	v_lshl_add_u64 v[48:49], v[130:131], 1, s[92:93]
	v_mov_b32_e32 v130, v171
	global_load_dwordx4 v[48:51], v[48:49], off
	s_nop 0
	v_lshl_add_u64 v[52:53], v[130:131], 1, s[76:77]
	global_load_dwordx4 v[52:55], v[52:53], off
	v_mov_b32_e32 v130, v172
.LBB0_1842:
	s_andn2_b64 vcc, exec, s[8:9]
	s_cbranch_vccnz .LBB0_1844
	v_add3_u32 v130, v133, v178, s97
	s_waitcnt vmcnt(8)
	v_add_u32_e32 v60, v133, v179
	s_nop 0
	v_lshl_add_u64 v[4:5], v[130:131], 1, s[76:77]
	v_add_u32_e32 v130, 0xfffffd00, v60
	global_load_dwordx4 v[4:7], v[4:5], off
	s_nop 0
	v_lshl_add_u64 v[12:13], v[130:131], 1, s[92:93]
	v_add3_u32 v130, v133, v180, s97
	global_load_dwordx4 v[12:15], v[12:13], off
	s_nop 0
	v_lshl_add_u64 v[20:21], v[130:131], 1, s[76:77]
	v_add_u32_e32 v130, 0x7d00, v60
	global_load_dwordx4 v[20:23], v[20:21], off
	s_nop 0
	v_lshl_add_u64 v[32:33], v[130:131], 1, s[92:93]
	v_add3_u32 v130, v133, v181, s97
	global_load_dwordx4 v[32:35], v[32:33], off
	s_nop 0
	v_lshl_add_u64 v[40:41], v[130:131], 1, s[76:77]
	v_add_u32_e32 v130, 0xfd00, v60
	global_load_dwordx4 v[40:43], v[40:41], off
	s_nop 0
	v_lshl_add_u64 v[48:49], v[130:131], 1, s[92:93]
	v_add3_u32 v130, v133, v182, s97
	global_load_dwordx4 v[48:51], v[48:49], off
	s_nop 0
	v_lshl_add_u64 v[52:53], v[130:131], 1, s[76:77]
	global_load_dwordx4 v[52:55], v[52:53], off
	v_add_u32_e32 v130, 0x17d00, v60

.LBB0_1846:
	v_add3_u32 v130, v133, v173, s16
	s_waitcnt vmcnt(8)
	v_lshl_add_u64 v[4:5], v[130:131], 1, s[76:77]
	v_add_u32_e32 v130, 0x100, v183
	global_load_dwordx4 v[4:7], v[4:5], off
	s_nop 0
	v_lshl_add_u64 v[12:13], v[130:131], 1, s[92:93]
	v_add3_u32 v130, v133, v175, s16
	global_load_dwordx4 v[12:15], v[12:13], off
	s_nop 0
	v_lshl_add_u64 v[20:21], v[130:131], 1, s[76:77]
	v_add_u32_e32 v130, 0x8100, v183
	global_load_dwordx4 v[20:23], v[20:21], off
	s_nop 0
	v_lshl_add_u64 v[32:33], v[130:131], 1, s[92:93]
	v_add3_u32 v130, v133, v176, s16
	global_load_dwordx4 v[32:35], v[32:33], off
	s_nop 0
	v_lshl_add_u64 v[40:41], v[130:131], 1, s[76:77]
	v_add_u32_e32 v130, 0x10100, v183
	global_load_dwordx4 v[40:43], v[40:41], off
	s_nop 0
	v_lshl_add_u64 v[48:49], v[130:131], 1, s[92:93]
	v_add3_u32 v130, v133, v177, s16
	global_load_dwordx4 v[48:51], v[48:49], off
	s_nop 0
	v_lshl_add_u64 v[52:53], v[130:131], 1, s[76:77]
	global_load_dwordx4 v[52:55], v[52:53], off
	v_add_u32_e32 v130, 0x18100, v183
	s_branch .LBB0_1828

.LBB0_1968:
	s_waitcnt vmcnt(15)
	v_lshl_add_u64 v[60:61], v[132:133], 1, s[16:17]
	global_load_dwordx4 v[60:63], v[60:61], off
	ds_read_b128 v[176:179], v134 offset:40960
	ds_read_b128 v[180:183], v134 offset:43520
	ds_read_b128 v[184:187], v135 offset:61440
	ds_read_b128 v[188:191], v135 offset:64000
	ds_read_b128 v[192:195], v134 offset:46080
	ds_read_b128 v[196:199], v134 offset:48640
	ds_read_b128 v[200:203], v160 offset:5120
	ds_read_b128 v[204:207], v160 offset:7680
	s_setprio 1
	s_waitcnt lgkmcnt(5)
	v_mfma_f32_16x16x32_bf16 v[64:67], v[184:187], v[176:179], v[64:67]
	v_mfma_f32_16x16x32_bf16 v[68:71], v[184:187], v[180:183], v[68:71]
	s_waitcnt lgkmcnt(3)
	v_mfma_f32_16x16x32_bf16 v[72:75], v[184:187], v[192:195], v[72:75]
	s_waitcnt lgkmcnt(2)
	v_mfma_f32_16x16x32_bf16 v[76:79], v[184:187], v[196:199], v[76:79]
	v_mfma_f32_16x16x32_bf16 v[80:83], v[188:191], v[176:179], v[80:83]
	v_mfma_f32_16x16x32_bf16 v[84:87], v[188:191], v[180:183], v[84:87]
	v_mfma_f32_16x16x32_bf16 v[88:91], v[188:191], v[192:195], v[88:91]
	s_waitcnt lgkmcnt(1)
	v_mfma_f32_16x16x32_bf16 v[96:99], v[200:203], v[176:179], v[96:99]
	v_mfma_f32_16x16x32_bf16 v[100:103], v[200:203], v[180:183], v[100:103]
	s_waitcnt lgkmcnt(0)
	v_mfma_f32_16x16x32_bf16 v[112:115], v[204:207], v[176:179], v[112:115]
	v_mfma_f32_16x16x32_bf16 v[184:187], v[188:191], v[196:199], v[92:95]
	v_mfma_f32_16x16x32_bf16 v[188:191], v[200:203], v[192:195], v[104:107]
	v_mfma_f32_16x16x32_bf16 v[200:203], v[200:203], v[196:199], v[108:111]
	v_mfma_f32_16x16x32_bf16 v[176:179], v[204:207], v[180:183], v[116:119]
	v_mfma_f32_16x16x32_bf16 v[180:183], v[204:207], v[192:195], v[120:123]
	v_mfma_f32_16x16x32_bf16 v[192:195], v[204:207], v[196:199], v[124:127]
	s_setprio 0
	ds_read_b128 v[196:199], v134 offset:41024
	ds_read_b128 v[204:207], v134 offset:43584
	ds_read_b128 v[104:107], v135 offset:61504
	ds_read_b128 v[116:119], v135 offset:64064
	ds_read_b128 v[208:211], v134 offset:46144
	ds_read_b128 v[212:215], v134 offset:48704
	ds_read_b128 v[216:219], v161 offset:5120
	ds_read_b128 v[220:223], v161 offset:7680
	s_setprio 1
	s_waitcnt lgkmcnt(5)
	v_mfma_f32_16x16x32_bf16 v[124:127], v[104:107], v[196:199], v[64:67]
	v_mfma_f32_16x16x32_bf16 v[108:111], v[104:107], v[204:207], v[68:71]
	s_waitcnt lgkmcnt(3)
	v_mfma_f32_16x16x32_bf16 v[92:95], v[104:107], v[208:211], v[72:75]
	s_waitcnt lgkmcnt(2)
	v_mfma_f32_16x16x32_bf16 v[76:79], v[104:107], v[212:215], v[76:79]
	v_mfma_f32_16x16x32_bf16 v[120:123], v[116:119], v[196:199], v[80:83]
	v_mfma_f32_16x16x32_bf16 v[104:107], v[116:119], v[204:207], v[84:87]
	v_mfma_f32_16x16x32_bf16 v[88:91], v[116:119], v[208:211], v[88:91]
	v_mfma_f32_16x16x32_bf16 v[72:75], v[116:119], v[212:215], v[184:187]
	s_waitcnt lgkmcnt(1)
	v_mfma_f32_16x16x32_bf16 v[116:119], v[216:219], v[196:199], v[96:99]
	v_mfma_f32_16x16x32_bf16 v[100:103], v[216:219], v[204:207], v[100:103]
	v_mfma_f32_16x16x32_bf16 v[84:87], v[216:219], v[208:211], v[188:191]
	v_mfma_f32_16x16x32_bf16 v[68:71], v[216:219], v[212:215], v[200:203]
	s_waitcnt lgkmcnt(0)
	v_mfma_f32_16x16x32_bf16 v[112:115], v[220:223], v[196:199], v[112:115]
	v_mfma_f32_16x16x32_bf16 v[96:99], v[220:223], v[204:207], v[176:179]
	v_mfma_f32_16x16x32_bf16 v[80:83], v[220:223], v[208:211], v[180:183]
	v_mfma_f32_16x16x32_bf16 v[64:67], v[220:223], v[212:215], v[192:195]
	s_setprio 0
	s_add_i32 s12, s12, 2
	s_addk_i32 s13, 0x80
	s_and_b64 vcc, exec, s[0:1]
	s_cbranch_vccnz .LBB0_1987
.LBB0_1969:
	s_cmp_gt_u32 s12, 4
	s_mov_b64 s[0:1], -1
	s_barrier
	s_waitcnt vmcnt(15)
	ds_write_b128 v155, v[0:3] offset:40960
	s_waitcnt vmcnt(14)
	ds_write_b128 v155, v[8:11] offset:61440
	s_waitcnt vmcnt(13)
	ds_write_b128 v156, v[16:19] offset:40960
	s_waitcnt vmcnt(12)
	ds_write_b128 v156, v[24:27] offset:61440
	s_waitcnt vmcnt(11)
	ds_write_b128 v157, v[28:31] offset:40960
	s_waitcnt vmcnt(10)
	ds_write_b128 v157, v[36:39] offset:61440
	s_waitcnt vmcnt(9)
	ds_write_b128 v158, v[44:47] offset:40960
	s_waitcnt vmcnt(8)
	ds_write_b128 v158, v[56:59] offset:61440
	s_cbranch_scc0 .LBB0_1975
	s_and_b64 vcc, exec, s[4:5]
	s_cbranch_vccz .LBB0_1972
	v_mov_b32_e32 v132, v163
	s_mov_b64 s[0:1], 0
	v_lshl_add_u64 v[0:1], v[132:133], 1, s[88:89]
	v_mov_b32_e32 v132, v164
	global_load_dwordx4 v[0:3], v[0:1], off
	s_nop 0
	v_lshl_add_u64 v[8:9], v[132:133], 1, s[16:17]
	v_mov_b32_e32 v132, v165
	global_load_dwordx4 v[8:11], v[8:9], off
	s_nop 0
	v_lshl_add_u64 v[16:17], v[132:133], 1, s[88:89]
	v_mov_b32_e32 v132, v167
	global_load_dwordx4 v[16:19], v[16:17], off
	s_nop 0
	v_lshl_add_u64 v[24:25], v[132:133], 1, s[16:17]
	v_mov_b32_e32 v132, v168
	global_load_dwordx4 v[24:27], v[24:25], off
	s_nop 0
	v_lshl_add_u64 v[28:29], v[132:133], 1, s[88:89]
	v_mov_b32_e32 v132, v169
	global_load_dwordx4 v[28:31], v[28:29], off
	s_nop 0
	v_lshl_add_u64 v[36:37], v[132:133], 1, s[16:17]
	v_mov_b32_e32 v132, v170
	global_load_dwordx4 v[36:39], v[36:37], off
	s_nop 0
	v_lshl_add_u64 v[44:45], v[132:133], 1, s[88:89]
	global_load_dwordx4 v[44:47], v[44:45], off
	v_mov_b32_e32 v132, v171
.LBB0_1972:
	s_andn2_b64 vcc, exec, s[0:1]
	s_cbranch_vccnz .LBB0_1974
	s_add_i32 s0, s13, 0xffffff40
	s_waitcnt vmcnt(8)
	v_add_u32_e32 v44, s13, v175
	s_and_b32 s0, s0, 0xc0
	v_add_u32_e32 v132, 0xffffff40, v44
	v_or_b32_e32 v56, s0, v136
	v_lshl_add_u64 v[0:1], v[132:133], 1, s[88:89]
	v_add_u32_e32 v132, v56, v153
	global_load_dwordx4 v[0:3], v[0:1], off
	s_nop 0
	v_lshl_add_u64 v[8:9], v[132:133], 1, s[16:17]
	v_add_u32_e32 v132, 0x3f40, v44
	global_load_dwordx4 v[8:11], v[8:9], off
	s_nop 0
	v_lshl_add_u64 v[16:17], v[132:133], 1, s[88:89]
	v_add_u32_e32 v132, v56, v172
	global_load_dwordx4 v[16:19], v[16:17], off
	s_nop 0
	v_lshl_add_u64 v[24:25], v[132:133], 1, s[16:17]
	v_add_u32_e32 v132, 0x7f40, v44
	global_load_dwordx4 v[24:27], v[24:25], off
	s_nop 0
	v_lshl_add_u64 v[28:29], v[132:133], 1, s[88:89]
	v_add_u32_e32 v132, v56, v173
	global_load_dwordx4 v[28:31], v[28:29], off
	s_nop 0
	v_lshl_add_u64 v[36:37], v[132:133], 1, s[16:17]
	v_add_u32_e32 v132, 0xbf40, v44
	global_load_dwordx4 v[36:39], v[36:37], off
	s_nop 0
	v_lshl_add_u64 v[44:45], v[132:133], 1, s[88:89]
	global_load_dwordx4 v[44:47], v[44:45], off
	v_add_u32_e32 v132, v56, v174

.LBB0_1975:
	s_andn2_b64 vcc, exec, s[0:1]
	v_add_u32_e32 v176, s13, v162
	s_cbranch_vccnz .LBB0_1977
	s_add_i32 s0, s13, 0x140
	s_and_b32 s0, s0, 0xc0
	v_add_u32_e32 v132, 0x140, v176
	s_nop 0
	v_or_b32_e32 v8, s0, v136
	v_add_u32_e32 v56, v8, v143
	v_lshl_add_u64 v[0:1], v[132:133], 1, s[88:89]
	v_add_u32_e32 v132, v56, v144
	global_load_dwordx4 v[0:3], v[0:1], off
	s_nop 0
	v_lshl_add_u64 v[8:9], v[132:133], 1, s[16:17]
	v_add_u32_e32 v132, 0x4140, v176
	global_load_dwordx4 v[8:11], v[8:9], off
	s_nop 0
	v_lshl_add_u64 v[16:17], v[132:133], 1, s[88:89]
	v_add_u32_e32 v132, v56, v137
	global_load_dwordx4 v[16:19], v[16:17], off
	s_nop 0
	v_lshl_add_u64 v[24:25], v[132:133], 1, s[16:17]
	v_add_u32_e32 v132, 0x8140, v176
	global_load_dwordx4 v[24:27], v[24:25], off
	s_nop 0
	v_lshl_add_u64 v[28:29], v[132:133], 1, s[88:89]
	v_add_u32_e32 v132, v56, v148
	global_load_dwordx4 v[28:31], v[28:29], off
	s_nop 0
	v_lshl_add_u64 v[36:37], v[132:133], 1, s[16:17]
	v_add_u32_e32 v132, 0xc140, v176
	global_load_dwordx4 v[36:39], v[36:37], off
	s_nop 0
	v_lshl_add_u64 v[44:45], v[132:133], 1, s[88:89]
	global_load_dwordx4 v[44:47], v[44:45], off
	v_add_u32_e32 v132, v56, v149
.LBB0_1977:
	s_nop 0
	v_lshl_add_u64 v[56:57], v[132:133], 1, s[16:17]
	global_load_dwordx4 v[56:59], v[56:57], off
	ds_read_b128 v[178:181], v134
	ds_read_b128 v[182:185], v134 offset:2560
	ds_read_b128 v[186:189], v135 offset:20480
	ds_read_b128 v[190:193], v135 offset:23040
	ds_read_b128 v[194:197], v134 offset:5120
	ds_read_b128 v[198:201], v134 offset:7680
	ds_read_b128 v[202:205], v135 offset:25600
	ds_read_b128 v[206:209], v135 offset:28160
	s_setprio 1
	s_waitcnt lgkmcnt(5)
	v_mfma_f32_16x16x32_bf16 v[124:127], v[186:189], v[178:181], v[124:127]
	v_mfma_f32_16x16x32_bf16 v[108:111], v[186:189], v[182:185], v[108:111]
	s_waitcnt lgkmcnt(3)
	v_mfma_f32_16x16x32_bf16 v[92:95], v[186:189], v[194:197], v[92:95]
	s_waitcnt lgkmcnt(2)
	v_mfma_f32_16x16x32_bf16 v[76:79], v[186:189], v[198:201], v[76:79]
	v_mfma_f32_16x16x32_bf16 v[120:123], v[190:193], v[178:181], v[120:123]
	v_mfma_f32_16x16x32_bf16 v[104:107], v[190:193], v[182:185], v[104:107]
	v_mfma_f32_16x16x32_bf16 v[88:91], v[190:193], v[194:197], v[88:91]
	s_waitcnt lgkmcnt(1)
	v_mfma_f32_16x16x32_bf16 v[116:119], v[202:205], v[178:181], v[116:119]
	v_mfma_f32_16x16x32_bf16 v[100:103], v[202:205], v[182:185], v[100:103]
	s_waitcnt lgkmcnt(0)
	v_mfma_f32_16x16x32_bf16 v[112:115], v[206:209], v[178:181], v[112:115]
	v_mfma_f32_16x16x32_bf16 v[186:189], v[190:193], v[198:201], v[72:75]
	v_mfma_f32_16x16x32_bf16 v[190:193], v[202:205], v[194:197], v[84:87]
	v_mfma_f32_16x16x32_bf16 v[202:205], v[202:205], v[198:201], v[68:71]
	v_mfma_f32_16x16x32_bf16 v[178:181], v[206:209], v[182:185], v[96:99]
	v_mfma_f32_16x16x32_bf16 v[182:185], v[206:209], v[194:197], v[80:83]
	v_mfma_f32_16x16x32_bf16 v[194:197], v[206:209], v[198:201], v[64:67]
	s_setprio 0
	ds_read_b128 v[198:201], v134 offset:64
	ds_read_b128 v[206:209], v134 offset:2624
	ds_read_b128 v[80:83], v135 offset:20544
	ds_read_b128 v[96:99], v135 offset:23104
	ds_read_b128 v[210:213], v134 offset:5184
	ds_read_b128 v[214:217], v134 offset:7744
	ds_read_b128 v[218:221], v135 offset:25664
	ds_read_b128 v[222:225], v135 offset:28224
	s_setprio 1
	s_waitcnt lgkmcnt(5)
	v_mfma_f32_16x16x32_bf16 v[64:67], v[80:83], v[198:201], v[124:127]
	v_mfma_f32_16x16x32_bf16 v[68:71], v[80:83], v[206:209], v[108:111]
	s_waitcnt lgkmcnt(3)
	v_mfma_f32_16x16x32_bf16 v[72:75], v[80:83], v[210:213], v[92:95]
	s_waitcnt lgkmcnt(2)
	v_mfma_f32_16x16x32_bf16 v[76:79], v[80:83], v[214:217], v[76:79]
	v_mfma_f32_16x16x32_bf16 v[80:83], v[96:99], v[198:201], v[120:123]
	v_mfma_f32_16x16x32_bf16 v[84:87], v[96:99], v[206:209], v[104:107]
	v_mfma_f32_16x16x32_bf16 v[88:91], v[96:99], v[210:213], v[88:91]
	v_mfma_f32_16x16x32_bf16 v[92:95], v[96:99], v[214:217], v[186:189]
	s_waitcnt lgkmcnt(1)
	v_mfma_f32_16x16x32_bf16 v[96:99], v[218:221], v[198:201], v[116:119]
	v_mfma_f32_16x16x32_bf16 v[100:103], v[218:221], v[206:209], v[100:103]
	v_mfma_f32_16x16x32_bf16 v[104:107], v[218:221], v[210:213], v[190:193]
	v_mfma_f32_16x16x32_bf16 v[108:111], v[218:221], v[214:217], v[202:205]
	s_waitcnt lgkmcnt(0)
	v_mfma_f32_16x16x32_bf16 v[112:115], v[222:225], v[198:201], v[112:115]
	v_mfma_f32_16x16x32_bf16 v[116:119], v[222:225], v[206:209], v[178:181]
	v_mfma_f32_16x16x32_bf16 v[120:123], v[222:225], v[210:213], v[182:185]
	v_mfma_f32_16x16x32_bf16 v[124:127], v[222:225], v[214:217], v[194:197]
	s_setprio 0
	s_cmp_gt_u32 s12, 5
	s_cselect_b64 s[0:1], -1, 0
	s_cmp_lt_u32 s12, 6
	s_cselect_b64 s[10:11], -1, 0
	s_or_b64 s[10:11], s[6:7], s[10:11]
	s_andn2_b64 vcc, exec, s[10:11]
	s_barrier
	s_cbranch_vccnz .LBB0_1979
	s_waitcnt vmcnt(15)
	ds_write_b128 v155, v[4:7]
	s_waitcnt vmcnt(14)
	ds_write_b128 v155, v[12:15] offset:20480
	s_waitcnt vmcnt(13)
	ds_write_b128 v156, v[20:23]
	s_waitcnt vmcnt(12)
	ds_write_b128 v156, v[32:35] offset:20480
	s_waitcnt vmcnt(11)
	ds_write_b128 v157, v[40:43]
	s_waitcnt vmcnt(10)
	ds_write_b128 v157, v[48:51] offset:20480
	s_waitcnt vmcnt(9)
	ds_write_b128 v158, v[52:55]
	s_waitcnt vmcnt(8)
	ds_write_b128 v158, v[60:63] offset:20480
.LBB0_1979:
	s_cmp_gt_u32 s12, 3
	s_mov_b64 s[10:11], -1
	s_cbranch_scc0 .LBB0_1985
	s_and_b64 vcc, exec, s[4:5]
	s_cbranch_vccz .LBB0_1982
	v_mov_b32_e32 v132, v163
	s_mov_b64 s[10:11], 0
	s_waitcnt vmcnt(8)
	v_lshl_add_u64 v[4:5], v[132:133], 1, s[88:89]
	v_mov_b32_e32 v132, v164
	global_load_dwordx4 v[4:7], v[4:5], off
	s_nop 0
	v_lshl_add_u64 v[12:13], v[132:133], 1, s[16:17]
	v_mov_b32_e32 v132, v165
	global_load_dwordx4 v[12:15], v[12:13], off
	s_nop 0
	v_lshl_add_u64 v[20:21], v[132:133], 1, s[88:89]
	v_mov_b32_e32 v132, v167
	global_load_dwordx4 v[20:23], v[20:21], off
	s_nop 0
	v_lshl_add_u64 v[32:33], v[132:133], 1, s[16:17]
	v_mov_b32_e32 v132, v168
	global_load_dwordx4 v[32:35], v[32:33], off
	s_nop 0
	v_lshl_add_u64 v[40:41], v[132:133], 1, s[88:89]
	v_mov_b32_e32 v132, v169
	global_load_dwordx4 v[40:43], v[40:41], off
	s_nop 0
	v_lshl_add_u64 v[48:49], v[132:133], 1, s[16:17]
	v_mov_b32_e32 v132, v170
	global_load_dwordx4 v[48:51], v[48:49], off
	s_nop 0
	v_lshl_add_u64 v[52:53], v[132:133], 1, s[88:89]
	global_load_dwordx4 v[52:55], v[52:53], off
	v_mov_b32_e32 v132, v171
.LBB0_1982:
	s_andn2_b64 vcc, exec, s[10:11]
	s_cbranch_vccnz .LBB0_1984
	s_add_i32 s10, s13, 0x80
	s_waitcnt vmcnt(8)
	v_add_u32_e32 v52, s13, v175
	s_and_b32 s10, s10, 0x80
	v_add_u32_e32 v132, 0xffffff80, v52
	v_or_b32_e32 v60, s10, v136
	v_lshl_add_u64 v[4:5], v[132:133], 1, s[88:89]
	v_add_u32_e32 v132, v60, v153
	global_load_dwordx4 v[4:7], v[4:5], off
	s_nop 0
	v_lshl_add_u64 v[12:13], v[132:133], 1, s[16:17]
	v_add_u32_e32 v132, 0x3f80, v52
	global_load_dwordx4 v[12:15], v[12:13], off
	s_nop 0
	v_lshl_add_u64 v[20:21], v[132:133], 1, s[88:89]
	v_add_u32_e32 v132, v60, v172
	global_load_dwordx4 v[20:23], v[20:21], off
	s_nop 0
	v_lshl_add_u64 v[32:33], v[132:133], 1, s[16:17]
	v_add_u32_e32 v132, 0x7f80, v52
	global_load_dwordx4 v[32:35], v[32:33], off
	s_nop 0
	v_lshl_add_u64 v[40:41], v[132:133], 1, s[88:89]
	v_add_u32_e32 v132, v60, v173
	global_load_dwordx4 v[40:43], v[40:41], off
	s_nop 0
	v_lshl_add_u64 v[48:49], v[132:133], 1, s[16:17]
	v_add_u32_e32 v132, 0xbf80, v52
	global_load_dwordx4 v[48:51], v[48:49], off
	s_nop 0
	v_lshl_add_u64 v[52:53], v[132:133], 1, s[88:89]
	global_load_dwordx4 v[52:55], v[52:53], off
	v_add_u32_e32 v132, v60, v174

.LBB0_1986:
	v_add_u32_e32 v132, 0x180, v176
	s_waitcnt vmcnt(8)
	v_add_u32_e32 v60, s13, v166
	v_lshl_add_u64 v[4:5], v[132:133], 1, s[88:89]
	v_add_u32_e32 v132, 0x80, v60
	global_load_dwordx4 v[4:7], v[4:5], off
	s_nop 0
	v_lshl_add_u64 v[12:13], v[132:133], 1, s[16:17]
	v_add_u32_e32 v132, 0x4180, v176
	global_load_dwordx4 v[12:15], v[12:13], off
	s_nop 0
	v_lshl_add_u64 v[20:21], v[132:133], 1, s[88:89]
	v_add_u32_e32 v132, 0x2080, v60
	global_load_dwordx4 v[20:23], v[20:21], off
	s_nop 0
	v_lshl_add_u64 v[32:33], v[132:133], 1, s[16:17]
	v_add_u32_e32 v132, 0x8180, v176
	global_load_dwordx4 v[32:35], v[32:33], off
	s_nop 0
	v_lshl_add_u64 v[40:41], v[132:133], 1, s[88:89]
	v_add_u32_e32 v132, 0x4080, v60
	global_load_dwordx4 v[40:43], v[40:41], off
	s_nop 0
	v_lshl_add_u64 v[48:49], v[132:133], 1, s[16:17]
	v_add_u32_e32 v132, 0xc180, v176
	global_load_dwordx4 v[48:51], v[48:49], off
	s_nop 0
	v_lshl_add_u64 v[52:53], v[132:133], 1, s[88:89]
	global_load_dwordx4 v[52:55], v[52:53], off
	v_add_u32_e32 v132, 0x6080, v60
	s_branch .LBB0_1968
